# out_gemm residual epilogue: 8 loads in flight instead of 8 serial load-wait-store steps per pass; sgu row-stat loads hoisted with counted waits
# speedup vs baseline: 1.1660x; 1.0137x over previous
; __device__ __forceinline__ u16 f2bf(float f) { return (u16)(pack2(f, 0.f) & 0xffffu); }
; __device__ __forceinline__ int tid_() { int t = threadIdx.x; asm volatile("" : "+v"(t)); return t; }
; __device__ __forceinline__ void convT_tile(const float* __restrict__ src, int lds, int k0, int c0, u16* __restrict__ dst, int Kd,
;                                            int rbase, int mode, int which, unsigned char* smem, const float* __restrict__ kscale = nullptr) {
;   float* tile = (float*)smem;
;   const int t = tid_();
;   float4 v4[4];
; #pragma unroll
;   for (int i = 0; i < 4; ++i) {
;     const f32x4 w_ = __builtin_nontemporal_load((const f32x4*)(src + (size_t)(k0 + i * 16 + (t >> 4)) * lds + c0 + (t & 15) * 4));
;     v4[i] = make_float4(w_[0], w_[1], w_[2], w_[3]);
;   }
; #pragma unroll
;   for (int i = 0; i < 4; ++i) {
;     const int kk = i * 16 + (t >> 4), cc = (t & 15) * 4;
;     const float sc = kscale ? kscale[k0 + kk] : 1.f;
;     tile[kk * 65 + cc + 0] = v4[i].x * sc; tile[kk * 65 + cc + 1] = v4[i].y * sc;
;     tile[kk * 65 + cc + 2] = v4[i].z * sc; tile[kk * 65 + cc + 3] = v4[i].w * sc;
;   }
;   __syncthreads();
; #pragma unroll
;   for (int i = 0; i < 16; ++i) {
;     const int cc = i * 4 + (t >> 6), kk = t & 63;
;     int row;
;     if (mode == 0) row = rbase + cc;
;     else { const int f = c0 + cc; row = (((f >> 4) * 2 + which) << 4) + (f & 15); }
;     dst[(size_t)row * Kd + k0 + kk] = f2bf(tile[kk * 65 + cc]);
;   }
;   __syncthreads();
; }
; __device__ __forceinline__ void conv_item(const Params& p, int it, unsigned char* smem) {
;   const int l = it / 6720;
;   int r = it % 6720;
;   if (r < 240) {
;     const int ct = r >> 4, kt = r & 15;
;     const int c0 = (ct < 8 ? ct : ct + 4) * 64;
;     const int n0 = c0 + (c0 >= 768 ? 256 : 0);
;     convT_tile(p.w_in + (size_t)l * 1024 * 1216, 1216, kt * 64, c0, p.WinT + (size_t)l * 1536 * 1024, 1024, n0, 0, 0, smem);
.LBB0_60:
	s_andn2_b64 vcc, exec, s[0:1]
	s_cbranch_vccnz .LBB0_25
	v_mov_b64_e32 v[2:3], s[10:11]
	s_load_dwordx2 s[100:101], s[10:11], 0x30
	s_waitcnt lgkmcnt(0)
	v_mov_b32_e32 v4, s100
	v_mov_b32_e32 v5, s101
	s_load_dwordx2 s[100:101], s[10:11], 0xc0
	s_waitcnt lgkmcnt(0)
	v_mov_b32_e32 v20, s100
	v_mov_b32_e32 v21, s101
	s_ashr_i32 s0, s35, 4
	s_lshl_b32 s1, s0, 6
	s_add_i32 s4, s1, 0x100
	v_mov_b32_e32 v6, v187
	s_cmp_lt_i32 s0, 8
	s_cselect_b32 s0, s1, s4
	v_lshlrev_b32_e32 v3, 4, v6
	v_ashrrev_i32_e32 v2, 4, v6
	v_ashrrev_i32_e32 v24, 6, v6
	v_and_b32_e32 v18, 0xf0, v3
	s_cmpk_gt_i32 s0, 0x2ff
	v_and_b32_e32 v26, 63, v6
	v_lshlrev_b32_e32 v3, 2, v24
	v_mad_u64_u32 v[22:23], s[12:13], v2, s28, v[18:19]
	s_cselect_b32 s4, 0x100, 0
	s_and_b32 s7, s15, 0x3c0
	v_mad_u32_u24 v23, v26, s28, v3
	s_ashr_i32 s1, s0, 31
	v_add_u32_e32 v6, s7, v2
	v_add_u32_e32 v7, 16, v6
	v_add_u32_e32 v8, 32, v6
	v_add_u32_e32 v32, 48, v6
	v_add_u32_e32 v29, 0x1040, v22
	v_add_u32_e32 v62, 0x1048, v22
	v_add_u32_e32 v63, 0x2080, v22
	v_add_u32_e32 v64, 0x2088, v22
	v_add_u32_e32 v65, 0x30c0, v22
	v_add_u32_e32 v66, 0x30c8, v22
	s_waitcnt lgkmcnt(0)
	v_mad_i64_i32 v[2:3], s[12:13], s6, v27, v[4:5]
	v_lshl_add_u64 v[2:3], s[0:1], 2, v[2:3]
	v_lshl_add_u64 v[14:15], v[2:3], 0, v[18:19]
	v_mad_i64_i32 v[2:3], s[12:13], v6, s34, v[14:15]
	v_mad_i64_i32 v[16:17], s[12:13], v7, s34, v[14:15]
	global_load_dwordx4 v[2:5], v[2:3], off nt
	v_mad_i64_i32 v[30:31], s[12:13], v8, s34, v[14:15]
	global_load_dwordx4 v[6:9], v[16:17], off nt
	global_load_dwordx4 v[10:13], v[30:31], off nt
	v_mad_i64_i32 v[14:15], s[12:13], v32, s34, v[14:15]
	global_load_dwordx4 v[14:17], v[14:15], off nt
	s_add_i32 s0, s4, s0
	s_lshl_b32 s4, s7, 1
	v_add_u32_e32 v30, s0, v24
	v_mad_i64_i32 v[20:21], s[0:1], s6, v28, v[20:21]
	v_ashrrev_i32_e32 v31, 31, v30
	v_add_u32_e32 v32, 4, v30
	v_add_u32_e32 v34, 8, v30
	v_add_u32_e32 v36, 12, v30
	v_add_u32_e32 v38, 16, v30
	v_add_u32_e32 v40, 20, v30
	v_add_u32_e32 v42, 24, v30
	v_add_u32_e32 v44, 28, v30
	v_add_u32_e32 v46, 32, v30
	v_add_u32_e32 v48, 36, v30
	v_add_u32_e32 v50, 40, v30
	v_add_u32_e32 v52, 44, v30
	v_add_u32_e32 v54, 48, v30
	v_add_u32_e32 v56, 52, v30
	v_add_u32_e32 v58, 56, v30
	v_add_u32_e32 v60, 60, v30
	v_lshl_add_u64 v[20:21], v[20:21], 0, s[4:5]
	v_lshlrev_b32_e32 v18, 1, v26
	v_lshlrev_b64 v[30:31], 11, v[30:31]
	v_ashrrev_i32_e32 v33, 31, v32
	v_ashrrev_i32_e32 v35, 31, v34
	v_ashrrev_i32_e32 v37, 31, v36
	v_ashrrev_i32_e32 v39, 31, v38
	v_ashrrev_i32_e32 v41, 31, v40
	v_ashrrev_i32_e32 v43, 31, v42
	v_ashrrev_i32_e32 v45, 31, v44
	v_ashrrev_i32_e32 v47, 31, v46
	v_ashrrev_i32_e32 v49, 31, v48
	v_ashrrev_i32_e32 v51, 31, v50
	v_ashrrev_i32_e32 v53, 31, v52
	v_ashrrev_i32_e32 v55, 31, v54
	v_ashrrev_i32_e32 v57, 31, v56
	v_ashrrev_i32_e32 v59, 31, v58
	v_ashrrev_i32_e32 v61, 31, v60
	v_lshl_add_u64 v[20:21], v[20:21], 0, v[18:19]
	v_lshlrev_b64 v[32:33], 11, v[32:33]
	v_lshlrev_b64 v[34:35], 11, v[34:35]
	v_lshlrev_b64 v[36:37], 11, v[36:37]
	v_lshlrev_b64 v[38:39], 11, v[38:39]
	v_lshlrev_b64 v[40:41], 11, v[40:41]
	v_lshlrev_b64 v[42:43], 11, v[42:43]
	v_lshlrev_b64 v[44:45], 11, v[44:45]
	v_lshlrev_b64 v[46:47], 11, v[46:47]
	v_lshlrev_b64 v[48:49], 11, v[48:49]
	v_lshlrev_b64 v[50:51], 11, v[50:51]
	v_lshlrev_b64 v[52:53], 11, v[52:53]
	v_lshlrev_b64 v[54:55], 11, v[54:55]
	v_lshlrev_b64 v[56:57], 11, v[56:57]
	v_lshlrev_b64 v[58:59], 11, v[58:59]
	v_lshlrev_b64 v[60:61], 11, v[60:61]
	v_lshl_add_u64 v[30:31], v[20:21], 0, v[30:31]
	v_lshl_add_u64 v[32:33], v[20:21], 0, v[32:33]
	v_lshl_add_u64 v[34:35], v[20:21], 0, v[34:35]
	v_lshl_add_u64 v[36:37], v[20:21], 0, v[36:37]
	v_lshl_add_u64 v[38:39], v[20:21], 0, v[38:39]
	v_lshl_add_u64 v[40:41], v[20:21], 0, v[40:41]
	v_lshl_add_u64 v[42:43], v[20:21], 0, v[42:43]
	v_lshl_add_u64 v[44:45], v[20:21], 0, v[44:45]
	v_lshl_add_u64 v[46:47], v[20:21], 0, v[46:47]
	v_lshl_add_u64 v[48:49], v[20:21], 0, v[48:49]
	v_lshl_add_u64 v[50:51], v[20:21], 0, v[50:51]
	v_lshl_add_u64 v[52:53], v[20:21], 0, v[52:53]
	v_lshl_add_u64 v[54:55], v[20:21], 0, v[54:55]
	v_lshl_add_u64 v[56:57], v[20:21], 0, v[56:57]
	s_waitcnt vmcnt(0) lgkmcnt(0)
	ds_write2_b32 v22, v2, v3 offset1:1
	ds_write2_b32 v22, v4, v5 offset0:2 offset1:3
	ds_write2_b32 v29, v6, v7 offset1:1
	ds_write2_b32 v62, v8, v9 offset1:1
	ds_write2_b32 v63, v10, v11 offset1:1
	ds_write2_b32 v64, v12, v13 offset1:1
	ds_write2_b32 v65, v14, v15 offset1:1
	ds_write2_b32 v66, v16, v17 offset1:1
	s_waitcnt lgkmcnt(0)
	s_barrier
	ds_read2_b32 v[2:3], v23 offset1:4
	ds_read2_b32 v[4:5], v23 offset0:8 offset1:12
	ds_read2_b32 v[6:7], v23 offset0:16 offset1:20
	ds_read2_b32 v[8:9], v23 offset0:24 offset1:28
	ds_read2_b32 v[10:11], v23 offset0:32 offset1:36
	ds_read2_b32 v[12:13], v23 offset0:40 offset1:44
	ds_read2_b32 v[14:15], v23 offset0:48 offset1:52
	ds_read2_b32 v[16:17], v23 offset0:56 offset1:60
	s_waitcnt lgkmcnt(7)
	v_cvt_pk_bf16_f32 v2, v2, s0
	v_lshl_add_u64 v[58:59], v[20:21], 0, v[58:59]
	v_lshl_add_u64 v[20:21], v[20:21], 0, v[60:61]
	v_cvt_pk_bf16_f32 v3, v3, s0
	s_waitcnt lgkmcnt(6)
	v_cvt_pk_bf16_f32 v4, v4, s0
	v_cvt_pk_bf16_f32 v5, v5, s0
	s_waitcnt lgkmcnt(5)
	v_cvt_pk_bf16_f32 v6, v6, s0
	v_cvt_pk_bf16_f32 v7, v7, s0
	s_waitcnt lgkmcnt(4)
	v_cvt_pk_bf16_f32 v8, v8, s0
	v_cvt_pk_bf16_f32 v9, v9, s0
	s_waitcnt lgkmcnt(3)
	v_cvt_pk_bf16_f32 v10, v10, s0
	v_cvt_pk_bf16_f32 v11, v11, s0
	s_waitcnt lgkmcnt(2)
	v_cvt_pk_bf16_f32 v12, v12, s0
	v_cvt_pk_bf16_f32 v13, v13, s0
	s_waitcnt lgkmcnt(1)
	v_cvt_pk_bf16_f32 v14, v14, s0
	v_cvt_pk_bf16_f32 v15, v15, s0
	s_waitcnt lgkmcnt(0)
	v_cvt_pk_bf16_f32 v16, v16, s0
	v_cvt_pk_bf16_f32 v17, v17, s0
	global_store_short v[30:31], v2, off
	global_store_short v[32:33], v3, off
	global_store_short v[34:35], v4, off
	global_store_short v[36:37], v5, off
	global_store_short v[38:39], v6, off
	global_store_short v[40:41], v7, off
	global_store_short v[42:43], v8, off
	global_store_short v[44:45], v9, off
	global_store_short v[46:47], v10, off
	global_store_short v[48:49], v11, off
	global_store_short v[50:51], v12, off
	global_store_short v[52:53], v13, off
	global_store_short v[54:55], v14, off
	global_store_short v[56:57], v15, off
	global_store_short v[58:59], v16, off
	global_store_short v[20:21], v17, off
	s_waitcnt lgkmcnt(0)
	s_barrier
	s_branch .LBB0_25

; __device__ __forceinline__ void elem_item(const Params& p, int it) {
;     ...
;   if (it < 2048) {
; #pragma unroll
;     for (int i = 0; i < 4; ++i) {
;       const int idx = it * 1024 + i * 256 + t;
;       const int n1 = idx >> 14, m = (idx >> 7) & 127, kk = idx & 127;
;       const int rip = m >> 6, k2 = m & 63, ri = kk >> 6, n2 = kk & 63;
;       const int n = n1 + 128 * n2;
;       const int ph = (k2 * n) & 8191;
;       const float xx = (float)ph / 4096.f;
;       const float cs = cospif(xx), sn = sinpif(xx);
.LBB0_104:
	s_andn2_b64 vcc, exec, s[4:5]
	s_cbranch_vccnz .LBB0_106
	v_mov_b64_e32 v[2:3], s[10:11]
	s_load_dwordx2 s[100:101], s[10:11], 0xf8
	v_add_u32_e32 v14, s12, v8
	v_add_u32_e32 v4, 0x208000, v14
	v_add_u32_e32 v15, 0x208100, v14
	v_lshlrev_b32_e32 v9, 7, v8
	v_lshrrev_b32_e32 v5, 14, v4
	v_lshrrev_b32_e32 v10, 14, v15
	v_lshrrev_b32_e32 v11, 7, v4
	v_lshrrev_b32_e32 v12, 7, v15
	v_and_b32_e32 v11, 63, v11
	v_and_b32_e32 v12, 63, v12
	v_add_u32_e32 v10, v10, v9
	v_add_u32_e32 v5, v5, v9
	v_mul_lo_u32 v5, v11, v5
	v_mul_lo_u32 v10, v12, v10
	v_and_b32_e32 v5, 0x1fff, v5
	v_and_b32_e32 v10, 0x1fff, v10
	v_cvt_f32_u32_e32 v11, v5
	v_cvt_f32_u32_e32 v10, v10
	v_and_b32_e32 v16, 64, v8
	v_and_b32_e32 v17, 0x2000, v4
	v_cmp_eq_u32_e64 s[4:5], 0, v17
	v_pk_mul_f32 v[10:11], v[10:11], s[0:1] op_sel_hi:[1,0]
	v_ashrrev_i32_e32 v5, 31, v4
	v_pk_mul_f32 v[12:13], v[10:11], 0.5 op_sel_hi:[1,0]
	s_waitcnt lgkmcnt(0)
; __device__ __forceinline__ u16 f2bf(float f) { return (u16)(pack2(f, 0.f) & 0xffffu); }
; __device__ __forceinline__ void elem_item(const Params& p, int it) {
;     ...
;       const int n1 = idx >> 14, m = (idx >> 7) & 127, kk = idx & 127;
;       const int rip = m >> 6, k2 = m & 63, ri = kk >> 6, n2 = kk & 63;
;       const int n = n1 + 128 * n2;
;       const int ph = (k2 * n) & 8191;
;       const float xx = (float)ph / 4096.f;
;       const float cs = cospif(xx), sn = sinpif(xx);
;       const float v = rip == 0 ? (ri == 0 ? cs : sn) : (ri == 0 ? -sn : cs);
;       p.M1[idx] = f2bf(v);
;     }
	v_mov_b32_e32 v2, s100
	v_mov_b32_e32 v3, s101
	v_lshl_add_u64 v[4:5], v[4:5], 1, v[2:3]
	v_fract_f32_e32 v18, v13
	v_fract_f32_e32 v19, v12
	v_add_f32_e32 v18, v18, v18
	v_cmp_neq_f32_e32 vcc, s14, v13
	v_add_f32_e32 v19, v19, v19
	s_nop 0
	v_cndmask_b32_e32 v13, 0, v18, vcc
	v_cmp_neq_f32_e32 vcc, s14, v12
	s_nop 1
	v_cndmask_b32_e32 v12, 0, v19, vcc
	v_cmp_lt_f32_e32 vcc, 1.0, v11
	s_nop 1
	v_cndmask_b32_e32 v13, v11, v13, vcc
	v_add_f32_e32 v18, v13, v13
	v_rndne_f32_e32 v18, v18
	v_fmac_f32_e32 v13, -0.5, v18
	v_cvt_i32_f32_e32 v18, v18
	v_mul_f32_e32 v20, v13, v13
	v_fmamk_f32 v22, v20, 0x3e75aa41, v1
	v_fmamk_f32 v24, v20, 0x3d4be544, v6
	v_fmaak_f32 v22, v20, v22, 0x40234736
	v_fmaak_f32 v24, v20, v24, 0xbfaad1da
	v_cmp_lt_f32_e32 vcc, 1.0, v10
	v_mul_f32_e32 v23, v13, v20
	v_fmaak_f32 v22, v20, v22, 0xc0a55e0e
	v_fmaak_f32 v24, v20, v24, 0x4081e0d3
	v_cndmask_b32_e32 v12, v10, v12, vcc
	v_and_b32_e32 v28, 1, v18
	v_mul_f32_e32 v22, v23, v22
	v_fmaak_f32 v23, v20, v24, 0xc09de9e6
	v_add_f32_e32 v19, v12, v12
	v_and_b32_e32 v27, 2, v18
	v_fmac_f32_e32 v22, 0x40490fdb, v13
	v_fma_f32 v13, v20, v23, 1.0
	v_cmp_eq_u32_e32 vcc, 0, v28
	v_rndne_f32_e32 v19, v19
	v_lshlrev_b32_e32 v18, 30, v18
	v_cndmask_b32_e64 v20, -v22, v13, vcc
	v_cndmask_b32_e32 v13, v13, v22, vcc
	v_cmp_eq_u32_e32 vcc, 0, v27
	v_fmac_f32_e32 v12, -0.5, v19
	v_bitop3_b32 v13, v18, v13, s15 bitop3:0x6c
	v_cndmask_b32_e64 v20, -v20, v20, vcc
	v_cmp_lg_f32_e32 vcc, s14, v11
	v_mul_f32_e32 v21, v12, v12
	v_fmamk_f32 v25, v21, 0x3e75aa41, v1
	v_cndmask_b32_e32 v11, v7, v20, vcc
	v_cndmask_b32_e32 v13, v7, v13, vcc
	v_cmp_eq_u32_e32 vcc, 0, v16
	v_fmaak_f32 v25, v21, v25, 0x40234736
	v_mul_f32_e32 v26, v12, v21
	v_cndmask_b32_e32 v16, v13, v11, vcc
	v_cndmask_b32_e64 v11, v11, -v13, vcc
	v_cndmask_b32_e64 v11, v11, v16, s[4:5]
	v_fmaak_f32 v25, v21, v25, 0xc0a55e0e
	v_cvt_pk_bf16_f32 v11, v11, s0
	v_cvt_i32_f32_e32 v19, v19
	global_store_short v[4:5], v11, off
	v_mul_f32_e32 v11, v26, v25
	v_fmac_f32_e32 v11, 0x40490fdb, v12
	v_fmamk_f32 v12, v21, 0x3d4be544, v6
	v_fmaak_f32 v12, v21, v12, 0xbfaad1da
	v_fmaak_f32 v12, v21, v12, 0x4081e0d3
	v_fmaak_f32 v12, v21, v12, 0xc09de9e6
	v_and_b32_e32 v13, 1, v19
	v_and_b32_e32 v29, 2, v19
	v_fma_f32 v12, v21, v12, 1.0
	v_cmp_eq_u32_e64 s[4:5], 0, v13
	v_cmp_eq_u32_e64 s[6:7], 0, v29
	v_and_b32_e32 v16, 0x2000, v15
	v_cndmask_b32_e64 v13, -v11, v12, s[4:5]
	v_cndmask_b32_e64 v13, -v13, v13, s[6:7]
	v_cmp_lg_f32_e64 s[6:7], s14, v10
	v_cndmask_b32_e64 v10, v12, v11, s[4:5]
	v_lshlrev_b32_e32 v11, 30, v19
	v_bitop3_b32 v10, v11, v10, s15 bitop3:0x6c
	v_cndmask_b32_e64 v11, v7, v10, s[6:7]
	v_add_u32_e32 v10, 0x208300, v14
	v_add_u32_e32 v12, 0x208200, v14
	v_lshrrev_b32_e32 v14, 14, v12
	v_lshrrev_b32_e32 v15, 14, v10
	v_lshrrev_b32_e32 v18, 7, v12
	v_lshrrev_b32_e32 v19, 7, v10
	v_and_b32_e32 v18, 63, v18
	v_and_b32_e32 v19, 63, v19
	v_add_u32_e32 v15, v15, v9
	v_add_u32_e32 v9, v14, v9
	v_mul_lo_u32 v9, v18, v9
	v_mul_lo_u32 v14, v19, v15
	v_and_b32_e32 v9, 0x1fff, v9
	v_and_b32_e32 v14, 0x1fff, v14
	v_cvt_f32_u32_e32 v15, v9
	v_cvt_f32_u32_e32 v14, v14
	v_cndmask_b32_e64 v13, v7, v13, s[6:7]
	v_cndmask_b32_e32 v17, v11, v13, vcc
	v_cndmask_b32_e64 v9, v13, -v11, vcc
	v_cmp_eq_u32_e64 s[4:5], 0, v16
	v_pk_mul_f32 v[14:15], v[14:15], s[0:1] op_sel_hi:[1,0]
	s_nop 0
	v_cndmask_b32_e64 v9, v9, v17, s[4:5]
	v_pk_mul_f32 v[16:17], v[14:15], 0.5 op_sel_hi:[1,0]
	v_cvt_pk_bf16_f32 v9, v9, s0
	v_fract_f32_e32 v11, v17
	v_add_f32_e32 v11, v11, v11
	v_cmp_neq_f32_e64 s[4:5], s14, v17
	global_store_short v[4:5], v9, off offset:512
	s_nop 0
	v_cndmask_b32_e64 v11, 0, v11, s[4:5]
	v_cmp_lt_f32_e64 s[4:5], 1.0, v15
	s_nop 1
	v_cndmask_b32_e64 v11, v15, v11, s[4:5]
	v_add_f32_e32 v13, v11, v11
	v_rndne_f32_e32 v13, v13
	v_fmac_f32_e32 v11, -0.5, v13
	v_mul_f32_e32 v5, v11, v11
	v_fmamk_f32 v9, v5, 0x3e75aa41, v1
	v_fmaak_f32 v9, v5, v9, 0x40234736
	v_cvt_i32_f32_e32 v17, v13
	v_fmaak_f32 v9, v5, v9, 0xc0a55e0e
	v_mul_f32_e32 v13, v11, v5
	v_mul_f32_e32 v9, v13, v9
	v_fmac_f32_e32 v9, 0x40490fdb, v11
	v_fmamk_f32 v11, v5, 0x3d4be544, v6
	v_fmaak_f32 v11, v5, v11, 0xbfaad1da
	v_fmaak_f32 v11, v5, v11, 0x4081e0d3
	v_fmaak_f32 v11, v5, v11, 0xc09de9e6
	v_fma_f32 v5, v5, v11, 1.0
	v_and_b32_e32 v11, 1, v17
	v_and_b32_e32 v4, 2, v17
	v_cmp_eq_u32_e64 s[4:5], 0, v11
	v_cmp_eq_u32_e64 s[6:7], 0, v4
	v_ashrrev_i32_e32 v13, 31, v12
	v_cndmask_b32_e64 v11, -v9, v5, s[4:5]
	v_cndmask_b32_e64 v5, v5, v9, s[4:5]
	v_lshlrev_b32_e32 v9, 30, v17
	v_cndmask_b32_e64 v4, -v11, v11, s[6:7]
	v_cmp_lg_f32_e64 s[6:7], s14, v15
	v_bitop3_b32 v5, v9, v5, s15 bitop3:0x6c
	v_and_b32_e32 v9, 0x2000, v12
	v_cndmask_b32_e64 v4, v7, v4, s[6:7]
	v_cndmask_b32_e64 v5, v7, v5, s[6:7]
	v_cndmask_b32_e32 v11, v5, v4, vcc
	v_cndmask_b32_e64 v4, v4, -v5, vcc
	v_cmp_eq_u32_e64 s[4:5], 0, v9
	s_nop 1
	v_cndmask_b32_e64 v4, v4, v11, s[4:5]
	v_cvt_pk_bf16_f32 v9, v4, s0
	v_fract_f32_e32 v4, v16
	v_add_f32_e32 v4, v4, v4
	v_cmp_neq_f32_e64 s[4:5], s14, v16
	s_nop 1
	v_cndmask_b32_e64 v4, 0, v4, s[4:5]
	v_cmp_lt_f32_e64 s[4:5], 1.0, v14
	s_nop 1
	v_cndmask_b32_e64 v11, v14, v4, s[4:5]
	v_add_f32_e32 v4, v11, v11
	v_rndne_f32_e32 v15, v4
	v_lshl_add_u64 v[4:5], v[12:13], 1, v[2:3]
	v_fmac_f32_e32 v11, -0.5, v15
	global_store_short v[4:5], v9, off
	v_mul_f32_e32 v5, v11, v11
	v_fmamk_f32 v9, v5, 0x3e75aa41, v1
	v_fmaak_f32 v9, v5, v9, 0x40234736
	v_fmaak_f32 v9, v5, v9, 0xc0a55e0e
	v_mul_f32_e32 v12, v11, v5
	v_mul_f32_e32 v9, v12, v9
	v_cvt_i32_f32_e32 v16, v15
	v_fmac_f32_e32 v9, 0x40490fdb, v11
	v_fmamk_f32 v11, v5, 0x3d4be544, v6
	v_fmaak_f32 v11, v5, v11, 0xbfaad1da
	v_fmaak_f32 v11, v5, v11, 0x4081e0d3
	v_fmaak_f32 v11, v5, v11, 0xc09de9e6
	v_fma_f32 v5, v5, v11, 1.0
	v_and_b32_e32 v11, 1, v16
	v_and_b32_e32 v4, 2, v16
	v_cmp_eq_u32_e64 s[4:5], 0, v11
	v_cmp_eq_u32_e64 s[6:7], 0, v4
	s_nop 0
	v_cndmask_b32_e64 v11, -v9, v5, s[4:5]
	v_cndmask_b32_e64 v5, v5, v9, s[4:5]
	v_lshlrev_b32_e32 v9, 30, v16
	v_cndmask_b32_e64 v4, -v11, v11, s[6:7]
	v_cmp_lg_f32_e64 s[6:7], s14, v14
	v_bitop3_b32 v5, v9, v5, s15 bitop3:0x6c
	v_and_b32_e32 v9, 0x2000, v10
	v_cndmask_b32_e64 v4, v7, v4, s[6:7]
	v_cndmask_b32_e64 v5, v7, v5, s[6:7]
	v_cndmask_b32_e32 v11, v5, v4, vcc
	v_cndmask_b32_e64 v4, v4, -v5, vcc
	v_cmp_eq_u32_e32 vcc, 0, v9
	s_nop 1
	v_cndmask_b32_e32 v4, v4, v11, vcc
	v_ashrrev_i32_e32 v11, 31, v10
	v_cvt_pk_bf16_f32 v4, v4, s0
	v_lshl_add_u64 v[2:3], v[10:11], 1, v[2:3]
	global_store_short v[2:3], v4, off

; __device__ __forceinline__ u16 f2bf(float f) { return (u16)(pack2(f, 0.f) & 0xffffu); }
; __device__ __forceinline__ void elem_item(const Params& p, int it) {
;     ...
;   if (it < 128) {
; #pragma unroll
;     for (int i = 0; i < 4; ++i) { const int idx = it * 1024 + i * 256 + t; p.Wsgu[idx] = f2bf(p.w_sgu[idx]); }
;     return;
.LBB0_107:
	s_andn2_b64 vcc, exec, s[4:5]
	s_cbranch_vccnz .LBB0_64
	v_mov_b64_e32 v[2:3], s[10:11]
	s_load_dwordx2 s[100:101], s[10:11], 0x40
	s_waitcnt lgkmcnt(0)
	v_mov_b32_e32 v4, s100
	v_mov_b32_e32 v5, s101
	v_add_u32_e32 v8, s12, v8
	v_add_u32_e32 v8, 0x228000, v8
	v_ashrrev_i32_e32 v9, 31, v8
	s_load_dwordx2 s[100:101], s[10:11], 0xf0
	s_waitcnt lgkmcnt(0)
	v_mov_b32_e32 v2, s100
	v_mov_b32_e32 v3, s101
	s_waitcnt lgkmcnt(0)
	v_lshl_add_u64 v[4:5], v[8:9], 2, v[4:5]
	global_load_dword v10, v[4:5], off
	global_load_dword v11, v[4:5], off offset:1024
	global_load_dword v12, v[4:5], off offset:2048
	global_load_dword v13, v[4:5], off offset:3072
	v_lshl_add_u64 v[2:3], v[8:9], 1, v[2:3]
	s_waitcnt vmcnt(0) lgkmcnt(0)
	v_cvt_pk_bf16_f32 v4, v10, s0
	v_cvt_pk_bf16_f32 v5, v11, s0
	v_cvt_pk_bf16_f32 v8, v12, s0
	v_cvt_pk_bf16_f32 v9, v13, s0
	global_store_short v[2:3], v4, off
	global_store_short v[2:3], v5, off offset:512
	global_store_short v[2:3], v8, off offset:1024
	global_store_short v[2:3], v9, off offset:1536
	s_branch .LBB0_64

; template <bool COMBINE, bool MOD>
; __device__ __forceinline__ void phase_combine_modulate(const Params& p, int lprev, int lnext, const float* xlat, const float* xctx,
;                                                        float* olat, float* octx, int nrows) {
;     ...
;     const bool lat = row0 < T_LAT;
;     const float* xr = lat ? xlat + (size_t)row0 * DM : xctx + (size_t)(row0 - T_LAT) * DM;
;     const int cond = row_cond(row0);
;     float4 v[R][4];
; #pragma unroll
;     for (int r = 0; r < R; ++r)
; #pragma unroll
;       for (int i = 0; i < 4; ++i) v[r][i] = *(const float4*)(xr + (size_t)r * DM + i * 256 + lane * 4);
;     if (COMBINE) {
;       const int b = row_batch(row0);
;       const int myinv = p.INV[(size_t)row0 * 16 + (lane & 31)];
;       const float* g2 = p.mada + (size_t)(lprev * 3 + cond) * 6144 + 5 * 1024;
;       float* orow = lat ? olat + (size_t)row0 * DM : octx + (size_t)(row0 - T_LAT) * DM;
; #pragma unroll
;       for (int r = 0; r < R; ++r) {
;         float4 s[4];
; #pragma unroll
;         for (int i = 0; i < 4; ++i) s[i] = make_float4(0.f, 0.f, 0.f, 0.f);
;         unsigned mask = (unsigned)((__ballot(myinv >= 0) >> (16 * r)) & 0xFFFFull);
;         while (mask) {
;           const int e0 = __builtin_ctz(mask);
;           mask &= mask - 1;
;           const bool two = mask != 0u;
;           const int e1 = two ? __builtin_ctz(mask) : e0;
;           mask &= mask - 1;
;           const int s0 = __shfl(myinv, 16 * r + e0), s1 = __shfl(myinv, 16 * r + e1);
;           const size_t y0 = lat ? (size_t)(b * 16 + e0) * 1024 + s0 : (size_t)32768 + (size_t)(b * 16 + e0) * 128 + s0;
;           const size_t y1 = lat ? (size_t)(b * 16 + e1) * 1024 + s1 : (size_t)32768 + (size_t)(b * 16 + e1) * 128 + s1;
;           u32x2 a0[4], a1[4];
; #pragma unroll
;           for (int i = 0; i < 4; ++i) { a0[i] = *(const u32x2*)(p.YB + y0 * 1024 + lane * 4 + i * 256); a1[i] = *(const u32x2*)(p.YB + y1 * 1024 + lane * 4 + i * 256); }
.LBB0_164:
	s_or_b64 exec, exec, s[0:1]
	v_mov_b64_e32 v[4:5], s[42:43]
	global_load_dwordx2 v[6:7], v[4:5], off offset:416
	v_lshlrev_b32_e32 v48, 2, v36
	v_mov_b32_e32 v49, v1
	v_lshlrev_b64 v[8:9], 6, v[34:35]
	v_mov_b32_e32 v39, v1
	v_lshl_add_u64 v[2:3], v[2:3], 0, v[48:49]
	global_load_dwordx2 v[54:55], v[4:5], off offset:184
	global_load_dwordx4 v[30:33], v[2:3], off
	global_load_dwordx4 v[26:29], v[2:3], off offset:1024
	global_load_dwordx4 v[22:25], v[2:3], off offset:2048
	global_load_dwordx4 v[18:21], v[2:3], off offset:3072
	v_add_co_u32_e32 v2, vcc, 0x1000, v2
	v_lshrrev_b32_e32 v0, 4, v0
	s_nop 0
	v_addc_co_u32_e32 v3, vcc, 0, v3, vcc
	v_ashrrev_i32_e32 v41, 9, v34
	v_and_b32_e32 v92, 0xffffff0, v0
	v_and_b32_e32 v93, -16, v41
	v_lshlrev_b32_e32 v46, 1, v36
	s_waitcnt vmcnt(0) lgkmcnt(0)
	v_lshl_add_u64 v[4:5], v[6:7], 0, v[8:9]
	v_lshl_add_u64 v[4:5], v[4:5], 0, v[38:39]
	global_load_dword v39, v[4:5], off
	global_load_dwordx4 v[14:17], v[2:3], off
	global_load_dwordx4 v[10:13], v[2:3], off offset:1024
	global_load_dwordx4 v[6:9], v[2:3], off offset:2048
	s_nop 0
	global_load_dwordx4 v[2:5], v[2:3], off offset:3072
	s_waitcnt vmcnt(0) lgkmcnt(0)
	v_cmp_lt_i32_e32 vcc, -1, v39
	s_and_b32 s8, vcc_lo, 0xffff
	s_cmp_eq_u32 s8, 0
	s_cbranch_scc1 .LBB0_175
	v_mov_b64_e32 v[56:57], s[42:43]
	s_load_dwordx2 s[100:101], s[42:43], 0x1a8
	v_mov_b32_e32 v47, v1
	v_mov_b32_e32 v68, 0
	v_mov_b32_e32 v69, v68
	v_mov_b32_e32 v70, v68
	v_mov_b32_e32 v71, v68
	v_mov_b32_e32 v66, v68
	v_mov_b32_e32 v67, v68
	v_mov_b32_e32 v62, v68
	v_mov_b32_e32 v63, v68
	v_mov_b32_e32 v64, v68
	v_mov_b32_e32 v65, v68
	v_mov_b32_e32 v58, v68
	v_mov_b32_e32 v59, v68
	v_mov_b32_e32 v60, v68
	v_mov_b32_e32 v61, v68
	s_waitcnt lgkmcnt(0)
	v_mov_b32_e32 v56, s100
	v_mov_b32_e32 v57, s101
	v_lshl_add_u64 v[72:73], v[56:57], 0, v[46:47]
	v_mov_b32_e32 v56, v68
	v_mov_b32_e32 v57, v68
	s_branch .LBB0_167

; template <bool COMBINE, bool MOD>
; __device__ __forceinline__ void phase_combine_modulate(const Params& p, int lprev, int lnext, const float* xlat, const float* xctx,
;                                                        float* olat, float* octx, int nrows) {
;     ...
;         unsigned mask = (unsigned)((__ballot(myinv >= 0) >> (16 * r)) & 0xFFFFull);
;         while (mask) {
;           const int e0 = __builtin_ctz(mask);
;           mask &= mask - 1;
;           const bool two = mask != 0u;
;           const int e1 = two ? __builtin_ctz(mask) : e0;
;           mask &= mask - 1;
;           const int s0 = __shfl(myinv, 16 * r + e0), s1 = __shfl(myinv, 16 * r + e1);
;           const size_t y0 = lat ? (size_t)(b * 16 + e0) * 1024 + s0 : (size_t)32768 + (size_t)(b * 16 + e0) * 128 + s0;
;           const size_t y1 = lat ? (size_t)(b * 16 + e1) * 1024 + s1 : (size_t)32768 + (size_t)(b * 16 + e1) * 128 + s1;
;     ...
; #pragma unroll
;         for (int i = 0; i < 4; ++i) {
;           const int col = i * 256 + lane * 4;
;           const float4 g4 = *(const float4*)(g2 + col);
;           v[r][i].x += g4.x * s[i].x; v[r][i].y += g4.y * s[i].y; v[r][i].z += g4.z * s[i].z; v[r][i].w += g4.w * s[i].w;
;           *(float4*)(orow + (size_t)r * DM + col) = v[r][i];
;         }
.LBB0_176:
	v_min_i32_e32 v0, 0x4000, v34
	v_ashrrev_i32_e32 v94, 13, v0
	v_mul_hi_i32_i24_e32 v73, 0x6000, v94
	v_mul_i32_i24_e32 v72, 0x6000, v94
	v_lshl_add_u64 v[54:55], v[54:55], 0, v[72:73]
	s_mov_b64 s[0:1], 0x5000
	v_lshl_add_u64 v[76:77], v[54:55], 0, s[0:1]
	v_lshl_add_u64 v[52:53], s[46:47], 0, v[52:53]
	v_lshl_add_u64 v[50:51], s[48:49], 0, v[50:51]
	v_mov_b32_e32 v49, v1
	v_cndmask_b32_e64 v51, v51, v53, s[40:41]
	v_cndmask_b32_e64 v50, v50, v52, s[40:41]
	v_lshl_add_u64 v[52:53], v[76:77], 0, v[48:49]
	global_load_dwordx4 v[72:75], v[52:53], off
	v_mov_b32_e32 v41, v1
	v_lshl_add_u64 v[54:55], v[76:77], 0, v[40:41]
	v_mov_b32_e32 v43, v1
	v_mov_b32_e32 v45, v1
	v_cndmask_b32_e64 v0, 0, 1, vcc
	v_cmp_ne_u32_e32 vcc, 0, v0
	s_cmpk_gt_u32 vcc_lo, 0xffff
	s_waitcnt vmcnt(0) lgkmcnt(0)
	v_pk_fma_f32 v[30:31], v[70:71], v[72:73], v[30:31]
	v_pk_fma_f32 v[32:33], v[68:69], v[74:75], v[32:33]
	v_lshl_add_u64 v[72:73], v[50:51], 0, v[48:49]
	global_store_dwordx4 v[72:73], v[30:33], off
	global_load_dwordx4 v[68:71], v[54:55], off
	s_waitcnt vmcnt(0) lgkmcnt(0)
	v_pk_fma_f32 v[26:27], v[66:67], v[68:69], v[26:27]
	v_pk_fma_f32 v[28:29], v[56:57], v[70:71], v[28:29]
	global_store_dwordx4 v[72:73], v[26:29], off offset:1024
	v_lshl_add_u64 v[56:57], v[76:77], 0, v[42:43]
	global_load_dwordx4 v[66:69], v[56:57], off
	s_waitcnt vmcnt(0) lgkmcnt(0)
	v_pk_fma_f32 v[22:23], v[64:65], v[66:67], v[22:23]
	v_pk_fma_f32 v[24:25], v[62:63], v[68:69], v[24:25]
	global_store_dwordx4 v[72:73], v[22:25], off offset:2048
	v_lshl_add_u64 v[62:63], v[76:77], 0, v[44:45]
	global_load_dwordx4 v[64:67], v[62:63], off
	s_waitcnt vmcnt(0) lgkmcnt(0)
	v_pk_fma_f32 v[18:19], v[60:61], v[64:65], v[18:19]
	v_pk_fma_f32 v[20:21], v[58:59], v[66:67], v[20:21]
	v_mov_b32_e32 v59, 0
	global_store_dwordx4 v[72:73], v[18:21], off offset:3072
	v_mov_b32_e32 v58, v59
	v_mov_b32_e32 v61, v59
	v_mov_b32_e32 v60, v59
	v_mov_b32_e32 v65, v59
	v_mov_b32_e32 v64, v59
	v_mov_b32_e32 v67, v59
	v_mov_b32_e32 v66, v59
	v_mov_b32_e32 v69, v59
	v_mov_b32_e32 v68, v59
	v_mov_b32_e32 v71, v59
	v_mov_b32_e32 v70, v59
	v_mov_b32_e32 v75, v59
	v_mov_b32_e32 v74, v59
	v_mov_b32_e32 v73, v59
	v_mov_b32_e32 v72, v59
	s_cbranch_scc0 .LBB0_159
	v_mov_b64_e32 v[58:59], s[42:43]
	s_load_dwordx2 s[100:101], s[42:43], 0x1a8
	v_mov_b32_e32 v47, v1
	v_mov_b32_e32 v72, 0
	s_lshr_b32 s8, vcc_lo, 16
	v_mov_b32_e32 v73, v72
	v_mov_b32_e32 v74, v72
	v_mov_b32_e32 v75, v72
	v_mov_b32_e32 v70, v72
	v_mov_b32_e32 v71, v72
	v_mov_b32_e32 v68, v72
	v_mov_b32_e32 v69, v72
	v_mov_b32_e32 v66, v72
	v_mov_b32_e32 v67, v72
	v_mov_b32_e32 v64, v72
	v_mov_b32_e32 v65, v72
	v_mov_b32_e32 v60, v72
	v_mov_b32_e32 v61, v72
	s_waitcnt lgkmcnt(0)
	v_mov_b32_e32 v58, s100
	v_mov_b32_e32 v59, s101
	v_lshl_add_u64 v[76:77], v[58:59], 0, v[46:47]
	v_mov_b32_e32 v58, v72
	v_mov_b32_e32 v59, v72
	s_branch .LBB0_179

; #define XCD_FOR(u, T)                                                                                         \
;   for (int _x = bid_() & 7, _gb = gridDim.x >> 3, _hi = (int)(((long)(_x + 1) * (T)) >> 3),                    \
;            u = (int)(((long)_x * (T)) >> 3) + (bid_() >> 3);                                                  \
;        u < _hi; u += _gb)
; template <int NT, bool BKN, bool MASK = false, bool ROWSS = false, class Epi> ...
;     ...
;   float ss_[4] = {0.f, 0.f, 0.f, 0.f};
;   int stk_ = 0;
;   f32x4 acc[4][NT];
; #pragma unroll
;   for (int i = 0; i < 4; ++i)
; #pragma unroll
;     for (int j = 0; j < NT; ++j) acc[i][j] = (f32x4){0.f, 0.f, 0.f, 0.f};
;   const int nk = K >> 6;
;   const int nkm1 = nk - 1;
;   __syncthreads();
;   GEMM_LOAD(ra0, rb0, 0);
;   GEMM_LOAD(ra1, rb1, 1);
;   GEMM_STORE(ra0, rb0, 0);
;   GEMM_LOAD(ra0, rb0, (2 < nkm1 ? 2 : nkm1));
;   __syncthreads();
; __device__ __forceinline__ void phase_in_gemm(const Params& p, int l, unsigned char* smem) {
;     ...
;   XCD_FOR(t, 132 * 11) {
;     const int mt = t / 11, nt = t % 11;
;     const int row_base = mt * 128;
;     auto epi = [&](f32x4(&acc)[4][4], int r0, int c0) {
;       const bool act = nt < 4;
;       auto vf = [&](int, int, float v) { return act ? gelu_tanh(v) : v; };
;       auto rp = [&](int r) -> u16* {
;         const int row = row_base + r;
;         if (nt < 4) return p.PX + (size_t)row * 1024 + nt * 128;
;         if (nt >= 8) return p.PX + (size_t)row * 1024 + 512 + (nt - 8) * 128;
;         const int ri = (nt - 4) >> 1, jx = ((nt - 4) & 1) * 128;
;         if (row < T_LAT) return p.GD + ((size_t)((row >> 13) * 2 + ri) * SEQ + (row & (SEQ - 1))) * 256 + jx;
;         const int rc = row - T_LAT;
;         return p.GDc + ((size_t)((rc >> 8) * 2 + ri) * CTX + (rc & 255)) * 256 + jx;
;       };
;       epi_staged_bf16<4>(acc, r0, c0, smem, vf, rp);
;     };
;     gemm_tile<4, false>(p.H + (size_t)row_base * 1024, 1024, nullptr, 128, W + (size_t)nt * 128 * 1024, 1024, 1024, smem, epi);
.LBB0_243:
	v_mov_b64_e32 v[2:3], s[4:5]
	s_load_dwordx2 s[100:101], s[4:5], 0x118
	s_mul_hi_i32 s0, s9, 0x2e8ba2e9
	s_lshr_b32 s1, s0, 31
	s_ashr_i32 s0, s0, 1
	s_add_i32 s0, s0, s1
	v_mov_b32_e32 v70, v187
	s_mul_i32 s1, s0, 11
	s_lshl_b32 s42, s0, 7
	s_sub_i32 s40, s9, s1
	v_ashrrev_i32_e32 v6, 3, v70
	s_ashr_i32 s43, s42, 31
	v_ashrrev_i32_e32 v7, 31, v6
	s_lshl_b64 s[0:1], s[42:43], 11
	s_ashr_i32 s41, s40, 31
	v_lshlrev_b32_e32 v72, 4, v70
	v_lshlrev_b64 v[68:69], 11, v[6:7]
	s_mov_b64 s[18:19], 0x20000
	s_lshl_b64 s[38:39], s[40:41], 18
	v_and_b32_e32 v0, 0x70, v72
	v_lshl_add_u64 v[8:9], v[68:69], 0, s[18:19]
	s_mov_b64 s[18:19], 0x30000
	v_lshl_add_u64 v[4:5], v[132:133], 0, s[38:39]
	v_lshl_add_u64 v[6:7], v[68:69], 0, s[12:13]
	v_lshl_add_u64 v[10:11], v[68:69], 0, s[18:19]
	s_waitcnt lgkmcnt(0)
	s_barrier
	v_lshrrev_b32_e32 v71, 4, v70
	v_and_b32_e32 v72, 0xffffff80, v72
	v_and_b32_e32 v157, 15, v70
	v_bfe_u32 v159, v70, 4, 2
	v_bfe_u32 v156, v70, 6, 1
	v_ashrrev_i32_e32 v158, 7, v70
	v_mov_b32_e32 v78, 0
	v_mov_b32_e32 v79, v78
	v_mov_b32_e32 v80, v78
	v_mov_b32_e32 v81, v78
	v_mov_b32_e32 v74, v78
	v_mov_b32_e32 v75, v78
	v_mov_b32_e32 v76, v78
	v_mov_b32_e32 v77, v78
	v_mov_b32_e32 v82, v78
	v_mov_b32_e32 v83, v78
	v_mov_b32_e32 v84, v78
	v_mov_b32_e32 v85, v78
	v_mov_b32_e32 v86, v78
	v_mov_b32_e32 v87, v78
	v_mov_b32_e32 v88, v78
	v_mov_b32_e32 v89, v78
	v_mov_b32_e32 v126, v78
	v_mov_b32_e32 v127, v78
	v_mov_b32_e32 v128, v78
	v_mov_b32_e32 v129, v78
	v_mov_b32_e32 v122, v78
	v_mov_b32_e32 v123, v78
	v_mov_b32_e32 v124, v78
	v_mov_b32_e32 v125, v78
	v_mov_b32_e32 v102, v78
	v_mov_b32_e32 v103, v78
	v_mov_b32_e32 v104, v78
	v_mov_b32_e32 v105, v78
	v_mov_b32_e32 v110, v78
	v_mov_b32_e32 v111, v78
	v_mov_b32_e32 v112, v78
	v_mov_b32_e32 v113, v78
	v_mov_b32_e32 v114, v78
	v_mov_b32_e32 v115, v78
	v_mov_b32_e32 v116, v78
	v_mov_b32_e32 v117, v78
	v_mov_b32_e32 v94, v78
	v_mov_b32_e32 v95, v78
	v_mov_b32_e32 v96, v78
	v_mov_b32_e32 v97, v78
	v_mov_b32_e32 v90, v78
	v_mov_b32_e32 v91, v78
	v_mov_b32_e32 v92, v78
	v_mov_b32_e32 v93, v78
	v_mov_b32_e32 v98, v78
	v_mov_b32_e32 v99, v78
	s_waitcnt lgkmcnt(0)
	v_mov_b32_e32 v66, s100
	v_mov_b32_e32 v67, s101
	v_lshl_add_u64 v[2:3], v[66:67], 0, s[0:1]
	v_lshl_add_u64 v[2:3], v[2:3], 0, v[0:1]
	v_lshl_add_u64 v[136:137], v[2:3], 0, v[68:69]
	v_lshl_add_u64 v[138:139], v[2:3], 0, v[6:7]
	v_lshl_add_u64 v[140:141], v[2:3], 0, v[8:9]
	v_lshl_add_u64 v[142:143], v[2:3], 0, v[10:11]
	v_lshl_add_u64 v[2:3], v[4:5], 0, v[0:1]
	v_lshl_add_u64 v[144:145], v[2:3], 0, v[68:69]
	v_lshl_add_u64 v[146:147], v[2:3], 0, v[6:7]
	v_lshl_add_u64 v[148:149], v[2:3], 0, v[8:9]
	v_lshl_add_u64 v[150:151], v[2:3], 0, v[10:11]
	global_load_dwordx4 v[34:37], v[136:137], off
	global_load_dwordx4 v[38:41], v[138:139], off
	global_load_dwordx4 v[42:45], v[140:141], off
	global_load_dwordx4 v[46:49], v[142:143], off
	global_load_dwordx4 v[50:53], v[144:145], off
	global_load_dwordx4 v[54:57], v[146:147], off
	global_load_dwordx4 v[58:61], v[148:149], off
	global_load_dwordx4 v[62:65], v[150:151], off
	global_load_dwordx4 v[2:5], v[136:137], off offset:128
	global_load_dwordx4 v[26:29], v[138:139], off offset:128
	global_load_dwordx4 v[22:25], v[140:141], off offset:128
	global_load_dwordx4 v[18:21], v[142:143], off offset:128
	global_load_dwordx4 v[6:9], v[144:145], off offset:128
	global_load_dwordx4 v[14:17], v[146:147], off offset:128
	global_load_dwordx4 v[10:13], v[148:149], off offset:128
	global_load_dwordx4 v[30:33], v[150:151], off offset:128
	v_xor_b32_e32 v0, v71, v70
	v_lshlrev_b32_e32 v0, 4, v0
	v_and_or_b32 v163, v0, s14, v72
	v_bfe_u32 v0, v70, 1, 3
	v_bitop3_b32 v71, v71, v0, 3 bitop3:0x6c
	v_lshlrev_b32_e32 v72, 7, v157
	v_bitop3_b32 v0, v159, v0, 4 bitop3:0x36
	v_lshlrev_b32_e32 v71, 4, v71
	v_lshl_or_b32 v73, v158, 13, v72
	v_lshl_or_b32 v72, v156, 13, v72
	v_lshlrev_b32_e32 v0, 4, v0
	v_or_b32_e32 v162, v71, v73
	v_or_b32_e32 v164, v71, v72
	v_or_b32_e32 v160, v0, v73
	v_or_b32_e32 v161, v0, v72
	v_and_b32_e32 v0, 7, v70
	v_lshl_add_u64 v[70:71], s[38:39], 0, v[68:69]
	v_lshl_add_u64 v[68:69], v[68:69], 0, s[0:1]
	v_lshlrev_b32_e32 v0, 4, v0
	v_lshl_add_u64 v[152:153], v[134:135], 0, v[70:71]
	v_lshl_add_u64 v[154:155], v[66:67], 0, v[68:69]
	s_mov_b32 s0, -2
	v_mov_b32_e32 v66, v78
	v_mov_b32_e32 v67, v78
	v_mov_b32_e32 v68, v78
	v_mov_b32_e32 v69, v78
	v_mov_b32_e32 v70, v78
	v_mov_b32_e32 v71, v78
	v_mov_b32_e32 v72, v78
	v_mov_b32_e32 v73, v78
	v_mov_b32_e32 v100, v78
	v_mov_b32_e32 v101, v78
	v_mov_b32_e32 v106, v78
	v_mov_b32_e32 v107, v78
	v_mov_b32_e32 v108, v78
	v_mov_b32_e32 v109, v78
	v_mov_b32_e32 v118, v78
	v_mov_b32_e32 v119, v78
	v_mov_b32_e32 v120, v78
	v_mov_b32_e32 v121, v78
	s_waitcnt vmcnt(0) lgkmcnt(0)
	ds_write_b128 v163, v[34:37]
	ds_write_b128 v163, v[38:41] offset:4096
	ds_write_b128 v163, v[42:45] offset:8192
	ds_write_b128 v163, v[46:49] offset:12288
	ds_write_b128 v163, v[50:53] offset:16384
	ds_write_b128 v163, v[54:57] offset:20480
	ds_write_b128 v163, v[58:61] offset:24576
	ds_write_b128 v163, v[62:65] offset:28672
	global_load_dwordx4 v[34:37], v[136:137], off offset:256
	global_load_dwordx4 v[38:41], v[138:139], off offset:256
	global_load_dwordx4 v[46:49], v[140:141], off offset:256
	global_load_dwordx4 v[42:45], v[142:143], off offset:256
	global_load_dwordx4 v[50:53], v[144:145], off offset:256
	global_load_dwordx4 v[58:61], v[146:147], off offset:256
	global_load_dwordx4 v[54:57], v[148:149], off offset:256
	global_load_dwordx4 v[62:65], v[150:151], off offset:256
	s_waitcnt lgkmcnt(0)
	s_barrier

; #define XCD_FOR(u, T)                                                                                         \
;   for (int _x = bid_() & 7, _gb = gridDim.x >> 3, _hi = (int)(((long)(_x + 1) * (T)) >> 3),                    \
;            u = (int)(((long)_x * (T)) >> 3) + (bid_() >> 3);                                                  \
;        u < _hi; u += _gb)
; template <int NT, bool BKN, bool MASK = false, bool ROWSS = false, class Epi> ...
;     ...
;   const int nk = K >> 6;
;   const int nkm1 = nk - 1;
;   __syncthreads();
;   GEMM_LOAD(ra0, rb0, 0);
;   GEMM_LOAD(ra1, rb1, 1);
;   GEMM_STORE(ra0, rb0, 0);
;   GEMM_LOAD(ra0, rb0, (2 < nkm1 ? 2 : nkm1));
;   __syncthreads();
; __device__ __forceinline__ void phase_mix_a(const Params& p, int l, bool last, unsigned char* smem) {
;     ...
;     XCD_FOR(t, 132 * 6) {
;       const int mt = t / 6, nt = t % 6, row_base = mt * 128;
;       auto epi = [&](f32x4(&acc)[4][4], int r0, int c0) {
;         const float* rs = (const float*)(smem + 65536);
;         auto vf = [&](int r, int, float v) { return v * rs[r]; };
;         auto rp = [&](int r) -> u16* { return p.QR + (size_t)(row_base + r) * 768 + nt * 128; };
;         epi_staged_bf16<4>(acc, r0, c0, smem, vf, rp);
;       };
;       gemm_tile<4, false, false, true>(p.PX + (size_t)row_base * 1024 + 512, 1024, nullptr, 128, W + (size_t)nt * 128 * 256, 256, 256, smem, epi);
.LBB0_545:
	v_mov_b64_e32 v[2:3], s[40:41]
	s_load_dwordx2 s[100:101], s[40:41], 0x120
	s_mul_hi_i32 s19, s9, 0x2aaaaaab
	s_lshr_b32 s0, s19, 31
	s_add_i32 s19, s19, s0
	s_lshl_b32 s4, s19, 7
	s_ashr_i32 s5, s4, 31
	v_mov_b32_e32 v146, v187
	s_lshl_b64 s[34:35], s[4:5], 11
	s_mul_i32 s0, s19, -6
	v_ashrrev_i32_e32 v142, 3, v146
	v_lshlrev_b32_e32 v54, 4, v146
	v_and_b32_e32 v0, 0x70, v54
	v_ashrrev_i32_e32 v143, 31, v142
	v_add_u32_e32 v140, 32, v142
	s_add_i32 s0, s9, s0
	v_lshlrev_b64 v[6:7], 11, v[142:143]
	v_ashrrev_i32_e32 v141, 31, v140
	v_add_u32_e32 v138, 64, v142
	s_ashr_i32 s1, s0, 31
	v_ashrrev_i32_e32 v139, 31, v138
	v_add_u32_e32 v136, 0x60, v142
	s_lshl_b64 s[0:1], s[0:1], 16
	v_ashrrev_i32_e32 v137, 31, v136
	v_lshl_add_u64 v[4:5], v[134:135], 0, s[0:1]
	s_waitcnt lgkmcnt(0)
	s_barrier
	v_lshrrev_b32_e32 v80, 4, v146
	v_and_b32_e32 v145, 15, v146
	v_bfe_u32 v132, v146, 1, 3
	v_bfe_u32 v144, v146, 6, 1
	v_and_b32_e32 v54, 0xffffff80, v54
	v_lshlrev_b32_e32 v112, 7, v145
	v_cmp_lt_i32_e32 vcc, v212, v227
	s_waitcnt lgkmcnt(0)
	v_mov_b32_e32 v2, s100
	v_mov_b32_e32 v3, s101
	v_lshl_add_u64 v[2:3], v[2:3], 0, s[34:35]
	v_lshl_add_u64 v[2:3], v[2:3], 0, v[0:1]
	v_lshl_add_u64 v[78:79], v[2:3], 0, v[6:7]
	v_lshlrev_b64 v[6:7], 11, v[140:141]
	v_lshl_add_u64 v[82:83], v[2:3], 0, v[6:7]
	v_lshlrev_b64 v[6:7], 11, v[138:139]
	v_lshl_add_u64 v[84:85], v[2:3], 0, v[6:7]
	v_lshlrev_b64 v[6:7], 11, v[136:137]
	v_lshl_add_u64 v[86:87], v[2:3], 0, v[6:7]
	v_lshl_add_u64 v[2:3], v[4:5], 0, v[0:1]
	v_lshlrev_b64 v[4:5], 9, v[142:143]
	v_lshl_add_u64 v[88:89], v[2:3], 0, v[4:5]
	v_lshlrev_b64 v[4:5], 9, v[140:141]
	v_lshl_add_u64 v[90:91], v[2:3], 0, v[4:5]
	v_lshlrev_b64 v[4:5], 9, v[138:139]
	v_lshl_add_u64 v[92:93], v[2:3], 0, v[4:5]
	v_lshlrev_b64 v[4:5], 9, v[136:137]
	v_lshl_add_u64 v[94:95], v[2:3], 0, v[4:5]
	global_load_dwordx4 v[14:17], v[78:79], off offset:1024
	global_load_dwordx4 v[18:21], v[82:83], off offset:1024
	global_load_dwordx4 v[6:9], v[84:85], off offset:1024
	global_load_dwordx4 v[2:5], v[86:87], off offset:1024
	global_load_dwordx4 v[26:29], v[88:89], off
	global_load_dwordx4 v[34:37], v[90:91], off
	global_load_dwordx4 v[46:49], v[92:93], off
	global_load_dwordx4 v[50:53], v[94:95], off
	global_load_dwordx4 v[74:77], v[78:79], off offset:1152
	global_load_dwordx4 v[30:33], v[82:83], off offset:1152
	global_load_dwordx4 v[22:25], v[84:85], off offset:1152
	global_load_dwordx4 v[10:13], v[86:87], off offset:1152
	global_load_dwordx4 v[70:73], v[88:89], off offset:128
	global_load_dwordx4 v[42:45], v[90:91], off offset:128
	global_load_dwordx4 v[62:65], v[92:93], off offset:128
	global_load_dwordx4 v[38:41], v[94:95], off offset:128
	v_ashrrev_i32_e32 v0, 7, v146
	v_lshl_or_b32 v133, v0, 13, v112
	v_lshl_or_b32 v141, v144, 13, v112
	v_bfe_u32 v137, v146, 4, 2
	s_waitcnt vmcnt(0) lgkmcnt(0)
	v_and_b32_e32 v56, 0xffff0000, v14
	v_lshlrev_b32_e32 v55, 16, v14
	v_and_b32_e32 v58, 0xffff0000, v15
	v_mul_f32_e32 v56, v56, v56
	v_lshlrev_b32_e32 v57, 16, v15
	v_fmac_f32_e32 v56, v55, v55
	v_mul_f32_e32 v55, v58, v58
	v_and_b32_e32 v60, 0xffff0000, v16
	v_fmac_f32_e32 v55, v57, v57
	v_lshlrev_b32_e32 v59, 16, v16
	v_add_f32_e32 v55, v56, v55
	v_mul_f32_e32 v56, v60, v60
	v_and_b32_e32 v66, 0xffff0000, v17
	v_fmac_f32_e32 v56, v59, v59
	v_lshlrev_b32_e32 v61, 16, v17
	v_add_f32_e32 v55, v56, v55
	v_mul_f32_e32 v56, v66, v66
	v_fmac_f32_e32 v56, v61, v61
	v_add_f32_e32 v81, v56, v55
	v_xor_b32_e32 v55, v80, v146
	v_lshlrev_b32_e32 v55, 4, v55
	v_bitop3_b32 v80, v80, v132, 3 bitop3:0x6c
	v_and_or_b32 v139, v55, s14, v54
	v_lshlrev_b32_e32 v80, 4, v80
	ds_write_b128 v139, v[14:17]
	ds_write_b128 v139, v[18:21] offset:4096
	ds_write_b128 v139, v[6:9] offset:8192
	ds_write_b128 v139, v[2:5] offset:12288
	ds_write_b128 v139, v[26:29] offset:16384
	ds_write_b128 v139, v[34:37] offset:20480
	ds_write_b128 v139, v[46:49] offset:24576
	ds_write_b128 v139, v[50:53] offset:28672
	v_or_b32_e32 v147, v80, v133
	v_or_b32_e32 v148, v80, v141
	global_load_dwordx4 v[46:49], v[78:79], off offset:1280
	global_load_dwordx4 v[34:37], v[82:83], off offset:1280
	global_load_dwordx4 v[26:29], v[84:85], off offset:1280
	global_load_dwordx4 v[14:17], v[86:87], off offset:1280
	global_load_dwordx4 v[50:53], v[88:89], off offset:256
	global_load_dwordx4 v[54:57], v[90:91], off offset:256
	global_load_dwordx4 v[58:61], v[92:93], off offset:256
	global_load_dwordx4 v[66:69], v[94:95], off offset:256
	s_waitcnt lgkmcnt(0)
	s_barrier
; template <int NT, bool BKN, bool MASK = false, bool ROWSS = false, class Epi> ...
;     ...
;   for (int kt = 0; kt < nk - 2; kt += 2) {
;     GEMM_COMPUTE(0);
;     GEMM_STORE(ra1, rb1, 1);
;     GEMM_LOAD(ra1, rb1, kt + 3);
	ds_read_b128 v[96:99], v147
	ds_read_b128 v[100:103], v147 offset:2048
	ds_read_b128 v[104:107], v147 offset:4096
	ds_read_b128 v[108:111], v147 offset:6144
	ds_read_b128 v[112:115], v148 offset:16384
	ds_read_b128 v[116:119], v148 offset:18432
	ds_read_b128 v[120:123], v148 offset:20480
	ds_read_b128 v[124:127], v148 offset:22528
	v_bitop3_b32 v80, v137, v132, 4 bitop3:0x36
	v_lshlrev_b32_e32 v80, 4, v80
	v_or_b32_e32 v143, v80, v133
	v_or_b32_e32 v141, v80, v141
	s_waitcnt lgkmcnt(0)
	v_mfma_f32_16x16x32_bf16 v[128:131], v[96:99], v[112:115], 0
	v_and_b32_e32 v132, 0xffff0000, v74
	v_lshlrev_b32_e32 v80, 16, v74
	v_and_b32_e32 v149, 0xffff0000, v75
	v_mfma_f32_16x16x32_bf16 v[150:153], v[96:99], v[116:119], 0
	v_mul_f32_e32 v132, v132, v132
	v_lshlrev_b32_e32 v133, 16, v75
	v_fmac_f32_e32 v132, v80, v80
	v_mfma_f32_16x16x32_bf16 v[154:157], v[96:99], v[120:123], 0
	v_mul_f32_e32 v80, v149, v149
	v_fmac_f32_e32 v80, v133, v133
	v_add_f32_e32 v80, v132, v80
	v_mfma_f32_16x16x32_bf16 v[96:99], v[96:99], v[124:127], 0
	s_waitcnt vmcnt(0)
	v_and_b32_e32 v149, 0xffff0000, v47
	v_mfma_f32_16x16x32_bf16 v[158:161], v[100:103], v[112:115], 0
	v_lshlrev_b32_e32 v133, 16, v47
	v_mfma_f32_16x16x32_bf16 v[162:165], v[100:103], v[116:119], 0
	v_mfma_f32_16x16x32_bf16 v[166:169], v[100:103], v[120:123], 0
	v_mfma_f32_16x16x32_bf16 v[100:103], v[100:103], v[124:127], 0
	v_mfma_f32_16x16x32_bf16 v[170:173], v[104:107], v[112:115], 0
	v_mfma_f32_16x16x32_bf16 v[174:177], v[104:107], v[116:119], 0
	v_mfma_f32_16x16x32_bf16 v[178:181], v[104:107], v[120:123], 0
	v_mfma_f32_16x16x32_bf16 v[104:107], v[104:107], v[124:127], 0
	v_mfma_f32_16x16x32_bf16 v[112:115], v[108:111], v[112:115], 0
	v_mfma_f32_16x16x32_bf16 v[116:119], v[108:111], v[116:119], 0
	v_mfma_f32_16x16x32_bf16 v[120:123], v[108:111], v[120:123], 0
	v_mfma_f32_16x16x32_bf16 v[108:111], v[108:111], v[124:127], 0
	ds_read_b128 v[124:127], v143
	ds_read_b128 v[182:185], v143 offset:2048
	ds_read_b128 v[188:191], v143 offset:4096
	ds_read_b128 v[192:195], v143 offset:6144
	ds_read_b128 v[196:199], v141 offset:16384
	ds_read_b128 v[200:203], v141 offset:18432
	ds_read_b128 v[204:207], v141 offset:20480
	ds_read_b128 v[208:211], v141 offset:22528
	ds_write_b128 v139, v[74:77] offset:32768
	ds_write_b128 v139, v[30:33] offset:36864
	ds_write_b128 v139, v[22:25] offset:40960
	ds_write_b128 v139, v[10:13] offset:45056
	ds_write_b128 v139, v[70:73] offset:49152
	ds_write_b128 v139, v[42:45] offset:53248
	ds_write_b128 v139, v[62:65] offset:57344
	ds_write_b128 v139, v[38:41] offset:61440
	s_waitcnt lgkmcnt(11)
	v_mfma_f32_16x16x32_bf16 v[128:131], v[124:127], v[196:199], v[128:131]
	s_waitcnt lgkmcnt(10)
	v_mfma_f32_16x16x32_bf16 v[150:153], v[124:127], v[200:203], v[150:153]
	s_waitcnt lgkmcnt(9)
	v_mfma_f32_16x16x32_bf16 v[154:157], v[124:127], v[204:207], v[154:157]
	s_waitcnt lgkmcnt(8)
	v_mfma_f32_16x16x32_bf16 v[96:99], v[124:127], v[208:211], v[96:99]
	v_mfma_f32_16x16x32_bf16 v[124:127], v[182:185], v[196:199], v[158:161]
	v_mfma_f32_16x16x32_bf16 v[158:161], v[182:185], v[200:203], v[162:165]
	v_mfma_f32_16x16x32_bf16 v[162:165], v[182:185], v[204:207], v[166:169]
	v_mfma_f32_16x16x32_bf16 v[166:169], v[188:191], v[196:199], v[170:173]
	v_mfma_f32_16x16x32_bf16 v[170:173], v[188:191], v[200:203], v[174:177]
	v_mfma_f32_16x16x32_bf16 v[174:177], v[188:191], v[204:207], v[178:181]
	s_nop 2
	v_and_b32_e32 v179, 0xffff0000, v76
	v_lshlrev_b32_e32 v178, 16, v76
	v_mul_f32_e32 v132, v179, v179
	v_and_b32_e32 v181, 0xffff0000, v77
	v_fmac_f32_e32 v132, v178, v178
	v_lshlrev_b32_e32 v180, 16, v77
	v_add_f32_e32 v80, v132, v80
	v_mul_f32_e32 v132, v181, v181
	v_fmac_f32_e32 v132, v180, v180
	v_add_f32_e32 v80, v132, v80
	v_add_f32_e32 v132, v81, v80
	global_load_dwordx4 v[78:81], v[78:79], off offset:1408
	s_nop 0
	global_load_dwordx4 v[62:65], v[82:83], off offset:1408
	global_load_dwordx4 v[42:45], v[84:85], off offset:1408
	global_load_dwordx4 v[38:41], v[86:87], off offset:1408
	s_nop 0
	global_load_dwordx4 v[82:85], v[88:89], off offset:384
	s_nop 0
	global_load_dwordx4 v[86:89], v[90:91], off offset:384
	global_load_dwordx4 v[70:73], v[92:93], off offset:384
	global_load_dwordx4 v[74:77], v[94:95], off offset:384
	v_mfma_f32_16x16x32_bf16 v[100:103], v[182:185], v[208:211], v[100:103]
	s_waitcnt lgkmcnt(0)
	s_barrier
	v_mfma_f32_16x16x32_bf16 v[104:107], v[188:191], v[208:211], v[104:107]
	v_mfma_f32_16x16x32_bf16 v[112:115], v[192:195], v[196:199], v[112:115]
	v_mfma_f32_16x16x32_bf16 v[116:119], v[192:195], v[200:203], v[116:119]
	v_mfma_f32_16x16x32_bf16 v[120:123], v[192:195], v[204:207], v[120:123]
	v_mfma_f32_16x16x32_bf16 v[108:111], v[192:195], v[208:211], v[108:111]
	ds_read_b128 v[90:93], v147 offset:32768
	ds_read_b128 v[178:181], v147 offset:34816
	ds_read_b128 v[182:185], v147 offset:36864
	ds_read_b128 v[188:191], v147 offset:38912
	ds_read_b128 v[192:195], v148 offset:49152
	ds_read_b128 v[196:199], v148 offset:51200
	ds_read_b128 v[200:203], v148 offset:53248
	ds_read_b128 v[204:207], v148 offset:55296
	s_waitcnt lgkmcnt(0)
	v_mfma_f32_16x16x32_bf16 v[128:131], v[90:93], v[192:195], v[128:131]
	v_mfma_f32_16x16x32_bf16 v[150:153], v[90:93], v[196:199], v[150:153]
	v_mfma_f32_16x16x32_bf16 v[154:157], v[90:93], v[200:203], v[154:157]
	v_mfma_f32_16x16x32_bf16 v[90:93], v[90:93], v[204:207], v[96:99]
	v_mfma_f32_16x16x32_bf16 v[94:97], v[178:181], v[192:195], v[124:127]
	v_mfma_f32_16x16x32_bf16 v[124:127], v[178:181], v[196:199], v[158:161]
	v_mfma_f32_16x16x32_bf16 v[158:161], v[178:181], v[200:203], v[162:165]
	v_mfma_f32_16x16x32_bf16 v[98:101], v[178:181], v[204:207], v[100:103]
	v_mfma_f32_16x16x32_bf16 v[162:165], v[182:185], v[192:195], v[166:169]
	v_mfma_f32_16x16x32_bf16 v[166:169], v[182:185], v[196:199], v[170:173]
	v_mfma_f32_16x16x32_bf16 v[170:173], v[182:185], v[200:203], v[174:177]
	v_mfma_f32_16x16x32_bf16 v[102:105], v[182:185], v[204:207], v[104:107]
	v_mfma_f32_16x16x32_bf16 v[112:115], v[188:191], v[192:195], v[112:115]
	v_mfma_f32_16x16x32_bf16 v[116:119], v[188:191], v[196:199], v[116:119]
	v_mfma_f32_16x16x32_bf16 v[120:123], v[188:191], v[200:203], v[120:123]
	v_mfma_f32_16x16x32_bf16 v[106:109], v[188:191], v[204:207], v[108:111]
	ds_read_b128 v[174:177], v143 offset:32768
	ds_read_b128 v[178:181], v143 offset:34816
	ds_read_b128 v[182:185], v143 offset:36864
	ds_read_b128 v[188:191], v143 offset:38912
	ds_read_b128 v[192:195], v141 offset:49152
	ds_read_b128 v[196:199], v141 offset:51200
	ds_read_b128 v[200:203], v141 offset:53248
	ds_read_b128 v[204:207], v141 offset:55296
	ds_write_b128 v139, v[46:49]
	ds_write_b128 v139, v[34:37] offset:4096
	ds_write_b128 v139, v[26:29] offset:8192
	ds_write_b128 v139, v[14:17] offset:12288
	ds_write_b128 v139, v[50:53] offset:16384
	ds_write_b128 v139, v[54:57] offset:20480
	ds_write_b128 v139, v[58:61] offset:24576
	ds_write_b128 v139, v[66:69] offset:28672
	s_waitcnt lgkmcnt(0)
	v_mfma_f32_16x16x32_bf16 v[110:113], v[188:191], v[192:195], v[112:115]
	s_barrier
	v_mfma_f32_16x16x32_bf16 v[114:117], v[188:191], v[196:199], v[116:119]
	v_mfma_f32_16x16x32_bf16 v[118:121], v[188:191], v[200:203], v[120:123]
	s_nop 2
	v_and_b32_e32 v123, 0xffff0000, v46
	v_lshlrev_b32_e32 v122, 16, v46
	v_mul_f32_e32 v123, v123, v123
	v_fmac_f32_e32 v123, v122, v122
	v_mul_f32_e32 v122, v149, v149
	v_mfma_f32_16x16x32_bf16 v[128:131], v[174:177], v[192:195], v[128:131]
	v_fmac_f32_e32 v122, v133, v133
	v_add_f32_e32 v122, v123, v122
	v_mfma_f32_16x16x32_bf16 v[150:153], v[174:177], v[196:199], v[150:153]
	v_mfma_f32_16x16x32_bf16 v[154:157], v[174:177], v[200:203], v[154:157]
	v_mfma_f32_16x16x32_bf16 v[90:93], v[174:177], v[204:207], v[90:93]
	v_and_b32_e32 v175, 0xffff0000, v48
	v_lshlrev_b32_e32 v174, 16, v48
	v_mul_f32_e32 v123, v175, v175
	v_and_b32_e32 v177, 0xffff0000, v49
	v_fmac_f32_e32 v123, v174, v174
	v_lshlrev_b32_e32 v176, 16, v49
	v_add_f32_e32 v122, v123, v122
	v_mul_f32_e32 v123, v177, v177
	v_mfma_f32_16x16x32_bf16 v[94:97], v[178:181], v[192:195], v[94:97]
	v_fmac_f32_e32 v123, v176, v176
	v_add_f32_e32 v122, v123, v122
	v_add_f32_e32 v149, v132, v122
	v_mfma_f32_16x16x32_bf16 v[124:127], v[178:181], v[196:199], v[124:127]
	v_mfma_f32_16x16x32_bf16 v[158:161], v[178:181], v[200:203], v[158:161]
	v_mfma_f32_16x16x32_bf16 v[98:101], v[178:181], v[204:207], v[98:101]
	v_mfma_f32_16x16x32_bf16 v[162:165], v[182:185], v[192:195], v[162:165]
	v_mfma_f32_16x16x32_bf16 v[166:169], v[182:185], v[196:199], v[166:169]
	v_mfma_f32_16x16x32_bf16 v[170:173], v[182:185], v[200:203], v[170:173]
	v_mfma_f32_16x16x32_bf16 v[102:105], v[182:185], v[204:207], v[102:105]
	ds_read_b128 v[46:49], v147
	ds_read_b128 v[50:53], v147 offset:2048
	ds_read_b128 v[54:57], v147 offset:4096
	ds_read_b128 v[58:61], v147 offset:6144
	ds_read_b128 v[66:69], v148 offset:16384
	ds_read_b128 v[174:177], v148 offset:18432
	ds_read_b128 v[178:181], v148 offset:20480
	ds_read_b128 v[182:185], v148 offset:22528
	v_mfma_f32_16x16x32_bf16 v[106:109], v[188:191], v[204:207], v[106:109]
	s_waitcnt lgkmcnt(0)
	v_mfma_f32_16x16x32_bf16 v[128:131], v[46:49], v[66:69], v[128:131]
	v_mfma_f32_16x16x32_bf16 v[150:153], v[46:49], v[174:177], v[150:153]
	v_mfma_f32_16x16x32_bf16 v[154:157], v[46:49], v[178:181], v[154:157]
	v_mfma_f32_16x16x32_bf16 v[46:49], v[46:49], v[182:185], v[90:93]
	v_mfma_f32_16x16x32_bf16 v[90:93], v[50:53], v[66:69], v[94:97]
	v_mfma_f32_16x16x32_bf16 v[94:97], v[50:53], v[174:177], v[124:127]
	v_mfma_f32_16x16x32_bf16 v[158:161], v[50:53], v[178:181], v[158:161]
	v_mfma_f32_16x16x32_bf16 v[50:53], v[50:53], v[182:185], v[98:101]
	v_mfma_f32_16x16x32_bf16 v[98:101], v[54:57], v[66:69], v[162:165]
	v_mfma_f32_16x16x32_bf16 v[162:165], v[54:57], v[174:177], v[166:169]
	v_mfma_f32_16x16x32_bf16 v[166:169], v[54:57], v[178:181], v[170:173]
	v_mfma_f32_16x16x32_bf16 v[54:57], v[54:57], v[182:185], v[102:105]
	v_mfma_f32_16x16x32_bf16 v[170:173], v[58:61], v[66:69], v[110:113]
	v_mfma_f32_16x16x32_bf16 v[174:177], v[58:61], v[174:177], v[114:117]
	v_mfma_f32_16x16x32_bf16 v[178:181], v[58:61], v[178:181], v[118:121]
	v_mfma_f32_16x16x32_bf16 v[182:185], v[58:61], v[182:185], v[106:109]
	ds_read_b128 v[58:61], v143
	ds_read_b128 v[66:69], v143 offset:2048
	ds_read_b128 v[188:191], v143 offset:4096
	ds_read_b128 v[192:195], v143 offset:6144
	ds_read_b128 v[196:199], v141 offset:16384
	ds_read_b128 v[200:203], v141 offset:18432
	ds_read_b128 v[204:207], v141 offset:20480
	ds_read_b128 v[208:211], v141 offset:22528
	s_waitcnt vmcnt(0)
	ds_write_b128 v139, v[78:81] offset:32768
	ds_write_b128 v139, v[62:65] offset:36864
	ds_write_b128 v139, v[42:45] offset:40960
	ds_write_b128 v139, v[38:41] offset:45056
	ds_write_b128 v139, v[82:85] offset:49152
	ds_write_b128 v139, v[86:89] offset:53248
	ds_write_b128 v139, v[70:73] offset:57344
	ds_write_b128 v139, v[74:77] offset:61440
	s_waitcnt lgkmcnt(0)
	v_mfma_f32_16x16x32_bf16 v[130:133], v[58:61], v[196:199], v[128:131]
	s_barrier
; template <int NT, bool BKN, bool MASK = false, bool ROWSS = false, class Epi> ...
;     ...
;   if (ROWSS) {
;     float* rs = (float*)(smem + 65536);
; #pragma unroll
;     for (int i = 0; i < 4; ++i) {
;       float s = ss_[i];
;       s += __shfl_xor(s, 1); s += __shfl_xor(s, 2); s += __shfl_xor(s, 4);
;       if ((t & 7) == 0) rs[(t >> 3) + 32 * i] = rsqrtf(s / (float)K + 1e-6f);
;     }
;     __syncthreads();
;   }
	v_mfma_f32_16x16x32_bf16 v[126:129], v[58:61], v[200:203], v[150:153]
	s_nop 2
	v_and_b32_e32 v151, 0xffff0000, v78
	v_lshlrev_b32_e32 v150, 16, v78
	v_and_b32_e32 v153, 0xffff0000, v79
	v_mul_f32_e32 v151, v151, v151
	v_lshlrev_b32_e32 v152, 16, v79
	v_fmac_f32_e32 v151, v150, v150
	v_mul_f32_e32 v150, v153, v153
	v_mfma_f32_16x16x32_bf16 v[122:125], v[58:61], v[204:207], v[154:157]
	v_fmac_f32_e32 v150, v152, v152
	v_add_f32_e32 v150, v151, v150
	s_nop 0
	v_and_b32_e32 v155, 0xffff0000, v80
	v_lshlrev_b32_e32 v154, 16, v80
	v_mul_f32_e32 v151, v155, v155
	v_and_b32_e32 v157, 0xffff0000, v81
	v_fmac_f32_e32 v151, v154, v154
	v_lshlrev_b32_e32 v156, 16, v81
	v_add_f32_e32 v150, v151, v150
	v_mul_f32_e32 v151, v157, v157
	v_fmac_f32_e32 v151, v156, v156
	v_mfma_f32_16x16x32_bf16 v[114:117], v[66:69], v[196:199], v[90:93]
	v_add_f32_e32 v150, v151, v150
	v_add_f32_e32 v149, v149, v150
	v_mfma_f32_16x16x32_bf16 v[90:93], v[66:69], v[204:207], v[158:161]
	ds_read_b128 v[70:73], v147 offset:32768
	ds_read_b128 v[74:77], v147 offset:34816
	ds_read_b128 v[78:81], v147 offset:36864
	ds_read_b128 v[82:85], v147 offset:38912
	ds_read_b128 v[86:89], v148 offset:49152
	ds_read_b128 v[150:153], v148 offset:51200
	ds_read_b128 v[154:157], v148 offset:53248
	ds_read_b128 v[158:161], v148 offset:55296
	v_mfma_f32_16x16x32_bf16 v[118:121], v[58:61], v[208:211], v[46:49]
	v_mfma_f32_16x16x32_bf16 v[110:113], v[66:69], v[200:203], v[94:97]
	v_mfma_f32_16x16x32_bf16 v[94:97], v[66:69], v[208:211], v[50:53]
	v_mfma_f32_16x16x32_bf16 v[98:101], v[188:191], v[196:199], v[98:101]
	v_mfma_f32_16x16x32_bf16 v[102:105], v[188:191], v[200:203], v[162:165]
	v_mfma_f32_16x16x32_bf16 v[106:109], v[188:191], v[204:207], v[166:169]
	v_mfma_f32_16x16x32_bf16 v[66:69], v[188:191], v[208:211], v[54:57]
	v_mfma_f32_16x16x32_bf16 v[46:49], v[192:195], v[200:203], v[174:177]
	v_mfma_f32_16x16x32_bf16 v[50:53], v[192:195], v[204:207], v[178:181]
	v_mfma_f32_16x16x32_bf16 v[54:57], v[192:195], v[208:211], v[182:185]
	v_mfma_f32_16x16x32_bf16 v[58:61], v[192:195], v[196:199], v[170:173]
	s_waitcnt lgkmcnt(3)
	v_mfma_f32_16x16x32_bf16 v[114:117], v[74:77], v[86:89], v[114:117]
	v_mfma_f32_16x16x32_bf16 v[130:133], v[70:73], v[86:89], v[130:133]
	s_waitcnt lgkmcnt(2)
	v_mfma_f32_16x16x32_bf16 v[126:129], v[70:73], v[150:153], v[126:129]
	s_waitcnt lgkmcnt(1)
	v_mfma_f32_16x16x32_bf16 v[122:125], v[70:73], v[154:157], v[122:125]
	s_waitcnt lgkmcnt(0)
	v_mfma_f32_16x16x32_bf16 v[70:73], v[70:73], v[158:161], v[118:121]
	v_mfma_f32_16x16x32_bf16 v[118:121], v[74:77], v[150:153], v[110:113]
	v_mfma_f32_16x16x32_bf16 v[90:93], v[74:77], v[154:157], v[90:93]
	v_mfma_f32_16x16x32_bf16 v[74:77], v[74:77], v[158:161], v[94:97]
	v_mfma_f32_16x16x32_bf16 v[162:165], v[78:81], v[86:89], v[98:101]
	v_mfma_f32_16x16x32_bf16 v[166:169], v[78:81], v[150:153], v[102:105]
	v_mfma_f32_16x16x32_bf16 v[170:173], v[78:81], v[154:157], v[106:109]
	v_mfma_f32_16x16x32_bf16 v[66:69], v[78:81], v[158:161], v[66:69]
	v_mfma_f32_16x16x32_bf16 v[46:49], v[82:85], v[150:153], v[46:49]
	v_mfma_f32_16x16x32_bf16 v[50:53], v[82:85], v[154:157], v[50:53]
	v_mfma_f32_16x16x32_bf16 v[150:153], v[82:85], v[158:161], v[54:57]
	s_nop 2
	ds_read_b128 v[54:57], v143 offset:32768
	ds_read_b128 v[78:81], v143 offset:34816
	ds_read_b128 v[154:157], v143 offset:36864
	ds_read_b128 v[158:161], v143 offset:38912
	ds_read_b128 v[174:177], v141 offset:49152
	ds_read_b128 v[178:181], v141 offset:51200
	ds_read_b128 v[182:185], v141 offset:53248
	ds_read_b128 v[188:191], v141 offset:55296
	v_mfma_f32_16x16x32_bf16 v[58:61], v[82:85], v[86:89], v[58:61]
	s_waitcnt lgkmcnt(3)
	v_mfma_f32_16x16x32_bf16 v[82:85], v[78:81], v[174:177], v[114:117]
	s_nop 2
	v_cndmask_b32_e32 v114, v186, v212, vcc
	v_cmp_lt_i32_e32 vcc, v253, v227
	v_lshlrev_b32_e32 v114, 2, v114
	v_and_b32_e32 v117, 7, v146
	v_cndmask_b32_e32 v115, v186, v253, vcc
	v_cmp_lt_i32_e32 vcc, v252, v227
	v_lshlrev_b32_e32 v115, 2, v115
	s_waitcnt lgkmcnt(2)
	v_mfma_f32_16x16x32_bf16 v[86:89], v[78:81], v[178:181], v[118:121]
	v_cndmask_b32_e32 v116, v186, v252, vcc
	v_cmp_eq_u32_e32 vcc, 0, v117
	ds_bpermute_b32 v117, v114, v149
	v_lshlrev_b32_e32 v116, 2, v116
	v_mfma_f32_16x16x32_bf16 v[98:101], v[54:57], v[174:177], v[130:133]
	s_waitcnt lgkmcnt(0)
	v_add_f32_e32 v117, v149, v117
	ds_bpermute_b32 v118, v115, v117
	v_mfma_f32_16x16x32_bf16 v[102:105], v[54:57], v[178:181], v[126:129]
	s_waitcnt lgkmcnt(0)
	v_add_f32_e32 v117, v117, v118
	ds_bpermute_b32 v118, v116, v117
	v_mfma_f32_16x16x32_bf16 v[106:109], v[54:57], v[182:185], v[122:125]
	v_mfma_f32_16x16x32_bf16 v[110:113], v[54:57], v[188:191], v[70:73]
	v_mfma_f32_16x16x32_bf16 v[90:93], v[78:81], v[182:185], v[90:93]
	v_mfma_f32_16x16x32_bf16 v[94:97], v[78:81], v[188:191], v[74:77]
	v_mfma_f32_16x16x32_bf16 v[70:73], v[154:157], v[174:177], v[162:165]
	v_mfma_f32_16x16x32_bf16 v[74:77], v[154:157], v[178:181], v[166:169]
	v_mfma_f32_16x16x32_bf16 v[78:81], v[154:157], v[182:185], v[170:173]
	v_mfma_f32_16x16x32_bf16 v[66:69], v[154:157], v[188:191], v[66:69]
	v_mfma_f32_16x16x32_bf16 v[58:61], v[158:161], v[174:177], v[58:61]
	v_mfma_f32_16x16x32_bf16 v[54:57], v[158:161], v[178:181], v[46:49]
	v_mfma_f32_16x16x32_bf16 v[50:53], v[158:161], v[182:185], v[50:53]
	v_mfma_f32_16x16x32_bf16 v[46:49], v[158:161], v[188:191], v[150:153]
	s_and_saveexec_b64 s[0:1], vcc
	s_cbranch_execz .LBB0_547
	s_waitcnt lgkmcnt(0)
	v_add_f32_e32 v117, v117, v118
	v_fmamk_f32 v117, v117, 0x3b800000, v224
	v_mul_f32_e32 v118, 0x4b800000, v117
	v_cmp_gt_f32_e64 s[38:39], s85, v117
	s_nop 1
	v_cndmask_b32_e64 v117, v117, v118, s[38:39]
	v_rsq_f32_e32 v117, v117
	s_nop 0
	v_mul_f32_e32 v118, 0x45800000, v117
	v_cndmask_b32_e64 v117, v117, v118, s[38:39]
	v_lshl_add_u32 v118, v142, 2, v213
	ds_write_b32 v118, v117

; template <int NT, bool BKN, bool MASK = false, bool ROWSS = false, class Epi> ...
;     ...
;   __syncthreads();
;   GEMM_LOAD(ra0, rb0, 0);
;   GEMM_LOAD(ra1, rb1, 1);
;   GEMM_STORE(ra0, rb0, 0);
;   GEMM_LOAD(ra0, rb0, (2 < nkm1 ? 2 : nkm1));
;   __syncthreads();
;   for (int kt = 0; kt < nk - 2; kt += 2) {
;     GEMM_COMPUTE(0);
.LBB0_573:
	v_mov_b64_e32 v[2:3], s[40:41]
	s_load_dwordx2 s[100:101], s[40:41], 0x120
	s_and_b32 s4, s18, 0xffffff80
	v_mov_b32_e32 v102, v187
	s_ashr_i32 s5, s4, 31
	s_and_b32 s19, s9, 7
	v_ashrrev_i32_e32 v98, 3, v102
	s_lshl_b64 s[0:1], s[4:5], 11
	v_lshlrev_b32_e32 v43, 4, v102
	v_add_u32_e32 v96, 32, v98
	v_add_u32_e32 v94, 64, v98
	v_add_u32_e32 v92, 0x60, v98
	s_lshl_b32 s94, s19, 15
	v_and_b32_e32 v0, 0x70, v43
	v_ashrrev_i32_e32 v99, 31, v98
	v_ashrrev_i32_e32 v97, 31, v96
	v_ashrrev_i32_e32 v95, 31, v94
	v_ashrrev_i32_e32 v93, 31, v92
	v_lshl_add_u64 v[10:11], v[90:91], 0, s[94:95]
	v_lshlrev_b64 v[4:5], 11, v[96:97]
	v_lshlrev_b64 v[6:7], 11, v[94:95]
	v_lshlrev_b64 v[12:13], 11, v[92:93]
	v_lshl_add_u64 v[14:15], v[10:11], 0, v[0:1]
	v_lshlrev_b64 v[10:11], 8, v[98:99]
	v_lshlrev_b64 v[16:17], 8, v[94:95]
	v_lshl_add_u64 v[10:11], v[14:15], 0, v[10:11]
	v_lshl_add_u64 v[38:39], v[14:15], 0, v[16:17]
	v_lshlrev_b64 v[16:17], 8, v[92:93]
	v_lshl_add_u64 v[40:41], v[14:15], 0, v[16:17]
	s_waitcnt lgkmcnt(0)
	s_barrier
	v_lshrrev_b32_e32 v42, 4, v102
	v_and_b32_e32 v101, 15, v102
	v_bfe_u32 v68, v102, 1, 3
	v_bfe_u32 v100, v102, 6, 1
	v_bfe_u32 v93, v102, 4, 2
	v_cmp_lt_i32_e32 vcc, v212, v227
	s_waitcnt lgkmcnt(0)
	v_mov_b32_e32 v2, s100
	v_mov_b32_e32 v3, s101
	v_lshl_add_u64 v[2:3], v[2:3], 0, s[0:1]
	v_lshl_add_u64 v[8:9], v[2:3], 0, v[0:1]
	v_lshlrev_b64 v[2:3], 11, v[98:99]
	v_lshl_add_u64 v[2:3], v[8:9], 0, v[2:3]
	v_lshl_add_u64 v[4:5], v[8:9], 0, v[4:5]
	v_lshl_add_u64 v[6:7], v[8:9], 0, v[6:7]
	v_lshl_add_u64 v[8:9], v[8:9], 0, v[12:13]
	v_lshlrev_b64 v[12:13], 8, v[96:97]
	v_lshl_add_u64 v[12:13], v[14:15], 0, v[12:13]
	global_load_dwordx4 v[44:47], v[2:3], off offset:1536
	global_load_dwordx4 v[30:33], v[4:5], off offset:1536
	global_load_dwordx4 v[22:25], v[6:7], off offset:1536
	global_load_dwordx4 v[18:21], v[8:9], off offset:1536
	global_load_dwordx4 v[56:59], v[10:11], off
	global_load_dwordx4 v[60:63], v[12:13], off
	global_load_dwordx4 v[64:67], v[38:39], off
	global_load_dwordx4 v[74:77], v[40:41], off
	global_load_dwordx4 v[34:37], v[2:3], off offset:1664
	global_load_dwordx4 v[70:73], v[4:5], off offset:1664
	global_load_dwordx4 v[50:53], v[6:7], off offset:1664
	global_load_dwordx4 v[26:29], v[8:9], off offset:1664
	global_load_dwordx4 v[14:17], v[10:11], off offset:128
	s_nop 0
	global_load_dwordx4 v[2:5], v[12:13], off offset:128
	global_load_dwordx4 v[6:9], v[38:39], off offset:128
	s_nop 0
	global_load_dwordx4 v[10:13], v[40:41], off offset:128
	v_ashrrev_i32_e32 v0, 7, v102
	s_waitcnt vmcnt(0) lgkmcnt(0)
	v_and_b32_e32 v39, 0xffff0000, v44
	v_lshlrev_b32_e32 v38, 16, v44
	v_and_b32_e32 v41, 0xffff0000, v45
	v_mul_f32_e32 v39, v39, v39
	v_lshlrev_b32_e32 v40, 16, v45
	v_fmac_f32_e32 v39, v38, v38
	v_mul_f32_e32 v38, v41, v41
	v_and_b32_e32 v49, 0xffff0000, v46
	v_fmac_f32_e32 v38, v40, v40
	v_lshlrev_b32_e32 v48, 16, v46
	v_add_f32_e32 v38, v39, v38
	v_mul_f32_e32 v39, v49, v49
	v_and_b32_e32 v55, 0xffff0000, v47
	v_fmac_f32_e32 v39, v48, v48
	v_lshlrev_b32_e32 v54, 16, v47
	v_add_f32_e32 v38, v39, v38
	v_mul_f32_e32 v39, v55, v55
	v_fmac_f32_e32 v39, v54, v54
	v_add_f32_e32 v55, v39, v38
	v_xor_b32_e32 v38, v42, v102
	v_lshlrev_b32_e32 v38, 4, v38
	v_and_b32_e32 v39, 0xffffff80, v43
	v_and_or_b32 v54, v38, s14, v39
	ds_write_b128 v54, v[44:47]
	ds_write_b128 v54, v[30:33] offset:4096
	ds_write_b128 v54, v[22:25] offset:8192
	ds_write_b128 v54, v[18:21] offset:12288
	ds_write_b128 v54, v[56:59] offset:16384
	ds_write_b128 v54, v[60:63] offset:20480
	ds_write_b128 v54, v[64:67] offset:24576
	ds_write_b128 v54, v[74:77] offset:28672
	v_bitop3_b32 v38, v42, v68, 3 bitop3:0x6c
	v_lshlrev_b32_e32 v61, 7, v101
	v_lshlrev_b32_e32 v60, 4, v38
	v_lshl_or_b32 v69, v0, 13, v61
	v_lshl_or_b32 v95, v100, 13, v61
	v_or_b32_e32 v97, v60, v69
	v_or_b32_e32 v99, v60, v95
	s_waitcnt lgkmcnt(0)
	s_barrier
	ds_read_b128 v[38:41], v97
	ds_read_b128 v[42:45], v97 offset:2048
	ds_read_b128 v[46:49], v97 offset:4096
	ds_read_b128 v[56:59], v97 offset:6144
	ds_read_b128 v[60:63], v99 offset:16384
	ds_read_b128 v[64:67], v99 offset:18432
	ds_read_b128 v[74:77], v99 offset:20480
	ds_read_b128 v[78:81], v99 offset:22528
	v_bitop3_b32 v68, v93, v68, 4 bitop3:0x36
	v_lshlrev_b32_e32 v68, 4, v68
	v_or_b32_e32 v69, v68, v69
	v_or_b32_e32 v68, v68, v95
	s_waitcnt lgkmcnt(3)
	v_mfma_f32_16x16x32_bf16 v[82:85], v[38:41], v[60:63], 0
	v_and_b32_e32 v102, 7, v102
	s_waitcnt lgkmcnt(2)
	v_mfma_f32_16x16x32_bf16 v[86:89], v[38:41], v[64:67], 0
	s_waitcnt lgkmcnt(1)
	v_mfma_f32_16x16x32_bf16 v[104:107], v[38:41], v[74:77], 0
	s_waitcnt lgkmcnt(0)
	v_mfma_f32_16x16x32_bf16 v[38:41], v[38:41], v[78:81], 0
	v_mfma_f32_16x16x32_bf16 v[108:111], v[42:45], v[60:63], 0
	v_mfma_f32_16x16x32_bf16 v[112:115], v[42:45], v[64:67], 0
	v_mfma_f32_16x16x32_bf16 v[116:119], v[42:45], v[74:77], 0
	v_mfma_f32_16x16x32_bf16 v[42:45], v[42:45], v[78:81], 0
	v_mfma_f32_16x16x32_bf16 v[120:123], v[46:49], v[60:63], 0
	v_mfma_f32_16x16x32_bf16 v[124:127], v[46:49], v[64:67], 0
	v_mfma_f32_16x16x32_bf16 v[128:131], v[46:49], v[74:77], 0
	v_mfma_f32_16x16x32_bf16 v[46:49], v[46:49], v[78:81], 0
	v_mfma_f32_16x16x32_bf16 v[60:63], v[56:59], v[60:63], 0
	v_mfma_f32_16x16x32_bf16 v[64:67], v[56:59], v[64:67], 0
	v_mfma_f32_16x16x32_bf16 v[74:77], v[56:59], v[74:77], 0
	v_mfma_f32_16x16x32_bf16 v[56:59], v[56:59], v[78:81], 0
	ds_read_b128 v[78:81], v69
	ds_read_b128 v[132:135], v69 offset:2048
	ds_read_b128 v[136:139], v69 offset:4096
	ds_read_b128 v[140:143], v69 offset:6144
	ds_read_b128 v[144:147], v68 offset:16384
	ds_read_b128 v[148:151], v68 offset:18432
	ds_read_b128 v[152:155], v68 offset:20480
	ds_read_b128 v[156:159], v68 offset:22528
	ds_write_b128 v54, v[34:37] offset:32768
	ds_write_b128 v54, v[70:73] offset:36864
	ds_write_b128 v54, v[50:53] offset:40960
	ds_write_b128 v54, v[26:29] offset:45056
	ds_write_b128 v54, v[14:17] offset:49152
	ds_write_b128 v54, v[2:5] offset:53248
	ds_write_b128 v54, v[6:9] offset:57344
	ds_write_b128 v54, v[10:13] offset:61440
	s_waitcnt lgkmcnt(11)
	v_mfma_f32_16x16x32_bf16 v[120:123], v[136:139], v[144:147], v[120:123]
	s_waitcnt lgkmcnt(0)
	s_barrier
; template <int NT, bool BKN, bool MASK = false, bool ROWSS = false, class Epi> ...
;     ...
;   if (ROWSS) {
;     float* rs = (float*)(smem + 65536);
; #pragma unroll
;     for (int i = 0; i < 4; ++i) {
;       float s = ss_[i];
;       s += __shfl_xor(s, 1); s += __shfl_xor(s, 2); s += __shfl_xor(s, 4);
;       if ((t & 7) == 0) rs[(t >> 3) + 32 * i] = rsqrtf(s / (float)K + 1e-6f);
;     }
;     __syncthreads();
;   }
	v_mfma_f32_16x16x32_bf16 v[124:127], v[136:139], v[148:151], v[124:127]
	v_mfma_f32_16x16x32_bf16 v[128:131], v[136:139], v[152:155], v[128:131]
	v_mfma_f32_16x16x32_bf16 v[136:139], v[136:139], v[156:159], v[46:49]
	v_mfma_f32_16x16x32_bf16 v[46:49], v[140:143], v[156:159], v[56:59]
	s_nop 2
	v_and_b32_e32 v57, 0xffff0000, v34
	v_lshlrev_b32_e32 v56, 16, v34
	v_and_b32_e32 v59, 0xffff0000, v35
	v_mul_f32_e32 v57, v57, v57
	v_lshlrev_b32_e32 v58, 16, v35
	v_fmac_f32_e32 v57, v56, v56
	v_mul_f32_e32 v56, v59, v59
	v_mfma_f32_16x16x32_bf16 v[82:85], v[78:81], v[144:147], v[82:85]
	v_fmac_f32_e32 v56, v58, v58
	v_add_f32_e32 v56, v57, v56
	v_mfma_f32_16x16x32_bf16 v[86:89], v[78:81], v[148:151], v[86:89]
	v_mfma_f32_16x16x32_bf16 v[104:107], v[78:81], v[152:155], v[104:107]
	v_mfma_f32_16x16x32_bf16 v[78:81], v[78:81], v[156:159], v[38:41]
	v_mfma_f32_16x16x32_bf16 v[38:41], v[140:143], v[148:151], v[64:67]
	s_nop 2
	v_and_b32_e32 v65, 0xffff0000, v36
	v_lshlrev_b32_e32 v64, 16, v36
	v_mul_f32_e32 v57, v65, v65
	v_and_b32_e32 v67, 0xffff0000, v37
	v_fmac_f32_e32 v57, v64, v64
	v_lshlrev_b32_e32 v66, 16, v37
	v_add_f32_e32 v56, v57, v56
	v_mul_f32_e32 v57, v67, v67
	v_fmac_f32_e32 v57, v66, v66
	v_add_f32_e32 v56, v57, v56
	v_mfma_f32_16x16x32_bf16 v[108:111], v[132:135], v[144:147], v[108:111]
	v_add_f32_e32 v95, v55, v56
	v_mfma_f32_16x16x32_bf16 v[112:115], v[132:135], v[148:151], v[112:115]
	v_mfma_f32_16x16x32_bf16 v[116:119], v[132:135], v[152:155], v[116:119]
	v_mfma_f32_16x16x32_bf16 v[132:135], v[132:135], v[156:159], v[42:45]
	v_mfma_f32_16x16x32_bf16 v[42:45], v[140:143], v[152:155], v[74:77]
	ds_read_b128 v[2:5], v97 offset:32768
	ds_read_b128 v[6:9], v97 offset:34816
	ds_read_b128 v[10:13], v97 offset:36864
	ds_read_b128 v[14:17], v97 offset:38912
	ds_read_b128 v[34:37], v99 offset:49152
	ds_read_b128 v[54:57], v99 offset:51200
	ds_read_b128 v[64:67], v99 offset:53248
	ds_read_b128 v[74:77], v99 offset:55296
	v_cndmask_b32_e32 v97, v186, v212, vcc
	v_cmp_lt_i32_e32 vcc, v253, v227
	v_lshlrev_b32_e32 v97, 2, v97
	v_mfma_f32_16x16x32_bf16 v[60:63], v[140:143], v[144:147], v[60:63]
	v_cndmask_b32_e32 v99, v186, v253, vcc
	v_cmp_lt_i32_e32 vcc, v252, v227
	v_lshlrev_b32_e32 v99, 2, v99
	s_waitcnt lgkmcnt(3)
	v_mfma_f32_16x16x32_bf16 v[82:85], v[2:5], v[34:37], v[82:85]
	v_cndmask_b32_e32 v103, v186, v252, vcc
	v_cmp_eq_u32_e32 vcc, 0, v102
	ds_bpermute_b32 v102, v97, v95
	v_mfma_f32_16x16x32_bf16 v[108:111], v[6:9], v[34:37], v[108:111]
	v_lshlrev_b32_e32 v103, 2, v103
	s_waitcnt lgkmcnt(0)
	v_add_f32_e32 v95, v95, v102
	ds_bpermute_b32 v102, v99, v95
	v_mfma_f32_16x16x32_bf16 v[112:115], v[6:9], v[54:57], v[112:115]
	s_waitcnt lgkmcnt(0)
	v_add_f32_e32 v95, v95, v102
	v_mfma_f32_16x16x32_bf16 v[116:119], v[6:9], v[64:67], v[116:119]
	ds_bpermute_b32 v102, v103, v95
	v_mfma_f32_16x16x32_bf16 v[6:9], v[6:9], v[74:77], v[132:135]
	v_mfma_f32_16x16x32_bf16 v[120:123], v[10:13], v[34:37], v[120:123]
	v_mfma_f32_16x16x32_bf16 v[124:127], v[10:13], v[54:57], v[124:127]
	v_mfma_f32_16x16x32_bf16 v[128:131], v[10:13], v[64:67], v[128:131]
	v_mfma_f32_16x16x32_bf16 v[10:13], v[10:13], v[74:77], v[136:139]
	v_mfma_f32_16x16x32_bf16 v[132:135], v[14:17], v[34:37], v[60:63]
	v_mfma_f32_16x16x32_bf16 v[136:139], v[14:17], v[54:57], v[38:41]
	v_mfma_f32_16x16x32_bf16 v[140:143], v[14:17], v[64:67], v[42:45]
	v_mfma_f32_16x16x32_bf16 v[144:147], v[14:17], v[74:77], v[46:49]
	ds_read_b128 v[14:17], v69 offset:32768
	ds_read_b128 v[34:37], v69 offset:34816
	ds_read_b128 v[148:151], v69 offset:36864
	ds_read_b128 v[152:155], v69 offset:38912
	ds_read_b128 v[156:159], v68 offset:49152
	ds_read_b128 v[160:163], v68 offset:51200
	ds_read_b128 v[164:167], v68 offset:53248
	ds_read_b128 v[168:171], v68 offset:55296
	v_mfma_f32_16x16x32_bf16 v[86:89], v[2:5], v[54:57], v[86:89]
	v_mfma_f32_16x16x32_bf16 v[104:107], v[2:5], v[64:67], v[104:107]
	v_mfma_f32_16x16x32_bf16 v[2:5], v[2:5], v[74:77], v[78:81]
	s_waitcnt lgkmcnt(3)
	v_mfma_f32_16x16x32_bf16 v[74:77], v[14:17], v[156:159], v[82:85]
	s_waitcnt lgkmcnt(2)
	v_mfma_f32_16x16x32_bf16 v[78:81], v[14:17], v[160:163], v[86:89]
	s_waitcnt lgkmcnt(1)
	v_mfma_f32_16x16x32_bf16 v[82:85], v[14:17], v[164:167], v[104:107]
	s_waitcnt lgkmcnt(0)
	v_mfma_f32_16x16x32_bf16 v[86:89], v[14:17], v[168:171], v[2:5]
	v_mfma_f32_16x16x32_bf16 v[54:57], v[34:37], v[156:159], v[108:111]
	v_mfma_f32_16x16x32_bf16 v[58:61], v[34:37], v[160:163], v[112:115]
	v_mfma_f32_16x16x32_bf16 v[62:65], v[34:37], v[164:167], v[116:119]
	v_mfma_f32_16x16x32_bf16 v[66:69], v[34:37], v[168:171], v[6:9]
	v_mfma_f32_16x16x32_bf16 v[38:41], v[148:151], v[156:159], v[120:123]
	v_mfma_f32_16x16x32_bf16 v[42:45], v[148:151], v[160:163], v[124:127]
	v_mfma_f32_16x16x32_bf16 v[46:49], v[148:151], v[164:167], v[128:131]
	v_mfma_f32_16x16x32_bf16 v[34:37], v[148:151], v[168:171], v[10:13]
	v_mfma_f32_16x16x32_bf16 v[14:17], v[152:155], v[156:159], v[132:135]
	v_mfma_f32_16x16x32_bf16 v[10:13], v[152:155], v[160:163], v[136:139]
	v_mfma_f32_16x16x32_bf16 v[6:9], v[152:155], v[164:167], v[140:143]
	v_mfma_f32_16x16x32_bf16 v[2:5], v[152:155], v[168:171], v[144:147]
	s_and_saveexec_b64 s[0:1], vcc
	s_cbranch_execz .LBB0_575
	v_add_f32_e32 v95, v95, v102
	v_fmamk_f32 v95, v95, 0x3c000000, v224
	v_mul_f32_e32 v102, 0x4b800000, v95
	v_cmp_gt_f32_e64 s[38:39], s85, v95
	v_lshl_add_u32 v98, v98, 2, v213
	s_nop 0
	v_cndmask_b32_e64 v95, v95, v102, s[38:39]
	v_rsq_f32_e32 v95, v95
	s_nop 0
	v_mul_f32_e32 v102, 0x45800000, v95
	v_cndmask_b32_e64 v95, v95, v102, s[38:39]
	ds_write_b32 v98, v95

; __device__ __forceinline__ int tid_() { int t = threadIdx.x; asm volatile("" : "+v"(t)); return t; }
; template <class RP>
; __device__ __forceinline__ void epi_staged_bf16_T(f32x4 (&acc)[4][4], int r0, int c0, unsigned char* smem, RP colptr) {
;   constexpr int PITCH = 136;
;   u16* Ts = (u16*)smem;
;   const int t = tid_();
;   __syncthreads();
; #pragma unroll
;   for (int mi = 0; mi < 4; ++mi)
; #pragma unroll
;     for (int ni = 0; ni < 4; ++ni) {
;       u32x2 pk;
;       pk.x = pack2(acc[mi][ni][0], acc[mi][ni][1]);
;       pk.y = pack2(acc[mi][ni][2], acc[mi][ni][3]);
;       *(u32x2*)(Ts + (c0 + ni * 16) * PITCH + r0 + mi * 16) = pk;
;     }
;   __syncthreads();
; __device__ __forceinline__ void phase_mix_a(const Params& p, int l, bool last, unsigned char* smem) {
;     ...
; #pragma unroll
;           for (int mi = 0; mi < 4; ++mi)
; #pragma unroll
;             for (int j = 0; j < 4; ++j) {
;               const float sc = rs[r0 + mi * 16 + j];
; #pragma unroll
;               for (int ni = 0; ni < 4; ++ni) acc[mi][ni][j] *= sc;
;             }
;           auto cp = [&](int c) -> u16* { return p.Vt + ((size_t)(b * 4 + h) * 128 + c) * NPOS + pos_base; };
;           epi_staged_bf16_T(acc, r0, c0, smem, cp);
.LBB0_581:
	s_or_b64 exec, exec, s[0:1]
	s_lshr_b32 s5, s19, 1
	v_lshlrev_b32_e32 v0, 6, v0
	s_bitcmp1_b32 s9, 0
	v_lshl_or_b32 v18, v93, 2, v0
	s_cselect_b64 s[34:35], -1, 0
	s_waitcnt lgkmcnt(0)
	v_lshl_or_b32 v19, v100, 6, v101
	s_mov_b64 s[0:1], -1
	s_and_b64 vcc, exec, s[34:35]
	v_lshl_add_u32 v20, v18, 2, v213
	s_barrier
	s_cbranch_vccz .LBB0_583
	ds_read_b128 v[22:25], v20
	ds_read_b128 v[26:29], v20 offset:64
	v_mul_u32_u24_e32 v0, 0x88, v19
	v_lshlrev_b32_e32 v0, 1, v0
	v_mov_b32_e32 v21, v187
	s_waitcnt lgkmcnt(1)
	v_pk_mul_f32 v[30:31], v[86:87], v[22:23]
	v_pk_mul_f32 v[32:33], v[74:75], v[22:23]
	v_pk_mul_f32 v[50:51], v[78:79], v[22:23]
	v_pk_mul_f32 v[52:53], v[82:83], v[22:23]
	v_pk_mul_f32 v[70:71], v[88:89], v[24:25]
	v_pk_mul_f32 v[72:73], v[76:77], v[24:25]
	v_pk_mul_f32 v[92:93], v[80:81], v[24:25]
	v_pk_mul_f32 v[94:95], v[84:85], v[24:25]
	s_waitcnt lgkmcnt(0)
	v_pk_mul_f32 v[96:97], v[66:67], v[26:27]
	v_pk_mul_f32 v[98:99], v[54:55], v[26:27]
	v_pk_mul_f32 v[100:101], v[58:59], v[26:27]
	v_pk_mul_f32 v[102:103], v[62:63], v[26:27]
	v_pk_mul_f32 v[104:105], v[68:69], v[28:29]
	ds_read_b128 v[22:25], v20 offset:128
	v_pk_mul_f32 v[106:107], v[56:57], v[28:29]
	v_pk_mul_f32 v[108:109], v[60:61], v[28:29]
	v_pk_mul_f32 v[110:111], v[64:65], v[28:29]
	ds_read_b128 v[26:29], v20 offset:192
	v_cvt_pk_bf16_f32 v32, v32, v33
	v_cvt_pk_bf16_f32 v33, v72, v73
	v_lshl_add_u32 v0, v18, 1, v0
	v_cvt_pk_bf16_f32 v30, v30, v31
	v_cvt_pk_bf16_f32 v31, v70, v71
	v_cvt_pk_bf16_f32 v70, v98, v99
	v_cvt_pk_bf16_f32 v71, v106, v107
	s_waitcnt lgkmcnt(0)
	s_barrier
	v_cvt_pk_bf16_f32 v50, v50, v51
	v_cvt_pk_bf16_f32 v51, v92, v93
	ds_write2_b64 v0, v[32:33], v[70:71] offset1:4
	v_cvt_pk_bf16_f32 v32, v100, v101
	v_cvt_pk_bf16_f32 v33, v108, v109
	v_add_u32_e32 v70, 0x1000, v0
	v_cvt_pk_bf16_f32 v52, v52, v53
	v_cvt_pk_bf16_f32 v53, v94, v95
	ds_write2_b64 v70, v[50:51], v[32:33] offset0:32 offset1:36
	v_cvt_pk_bf16_f32 v32, v102, v103
	v_cvt_pk_bf16_f32 v33, v110, v111
	v_add_u32_e32 v71, 0x2000, v0
	v_pk_mul_f32 v[112:113], v[34:35], v[22:23]
	v_pk_mul_f32 v[114:115], v[38:39], v[22:23]
	v_pk_mul_f32 v[116:117], v[42:43], v[22:23]
	v_pk_mul_f32 v[22:23], v[46:47], v[22:23]
	v_pk_mul_f32 v[118:119], v[36:37], v[24:25]
	v_pk_mul_f32 v[120:121], v[40:41], v[24:25]
	v_pk_mul_f32 v[122:123], v[44:45], v[24:25]
	v_pk_mul_f32 v[24:25], v[48:49], v[24:25]
	v_pk_mul_f32 v[124:125], v[2:3], v[26:27]
	v_pk_mul_f32 v[126:127], v[14:15], v[26:27]
	v_pk_mul_f32 v[128:129], v[10:11], v[26:27]
	v_pk_mul_f32 v[26:27], v[6:7], v[26:27]
	v_pk_mul_f32 v[130:131], v[4:5], v[28:29]
	v_pk_mul_f32 v[132:133], v[16:17], v[28:29]
	v_pk_mul_f32 v[134:135], v[12:13], v[28:29]
	v_pk_mul_f32 v[28:29], v[8:9], v[28:29]
	ds_write2_b64 v71, v[52:53], v[32:33] offset0:64 offset1:68
	v_cvt_pk_bf16_f32 v32, v96, v97
	v_cvt_pk_bf16_f32 v33, v104, v105
	v_add_u32_e32 v52, 0x3000, v0
	ds_write2_b64 v52, v[30:31], v[32:33] offset0:96 offset1:100
	v_cvt_pk_bf16_f32 v30, v114, v115
	v_cvt_pk_bf16_f32 v31, v120, v121
	v_cvt_pk_bf16_f32 v22, v22, v23
	v_cvt_pk_bf16_f32 v23, v24, v25
	v_cvt_pk_bf16_f32 v50, v126, v127
	v_cvt_pk_bf16_f32 v51, v132, v133
	v_cvt_pk_bf16_f32 v26, v26, v27
	v_cvt_pk_bf16_f32 v27, v28, v29
	v_cvt_pk_bf16_f32 v32, v116, v117
	v_cvt_pk_bf16_f32 v33, v122, v123
	v_cvt_pk_bf16_f32 v24, v112, v113
	v_cvt_pk_bf16_f32 v25, v118, v119
	ds_write2_b64 v0, v[30:31], v[50:51] offset0:8 offset1:12
	v_cvt_pk_bf16_f32 v30, v128, v129
	v_cvt_pk_bf16_f32 v31, v134, v135
	ds_write2_b64 v71, v[22:23], v[26:27] offset0:72 offset1:76
	v_cvt_pk_bf16_f32 v22, v124, v125
	v_cvt_pk_bf16_f32 v23, v130, v131
	v_mov_b64_e32 v[26:27], s[40:41]
	ds_write2_b64 v70, v[32:33], v[30:31] offset0:40 offset1:44
	ds_write2_b64 v52, v[24:25], v[22:23] offset0:104 offset1:108
	s_waitcnt lgkmcnt(0)
	s_barrier
; template <class RP>
; __device__ __forceinline__ void epi_staged_bf16_T(f32x4 (&acc)[4][4], int r0, int c0, unsigned char* smem, RP colptr) {
;     ...
; #pragma unroll
;   for (int i = 0; i < 8; ++i) {
;     const int c = t + 256 * i, col = c >> 4, ch = c & 15;
;     *(u32x4*)(colptr(col) + ch * 8) = *(const u32x4*)(Ts + col * PITCH + ch * 8);
;   }
; __device__ __forceinline__ void phase_mix_a(const Params& p, int l, bool last, unsigned char* smem) {
;     ...
;           auto cp = [&](int c) -> u16* { return p.Vt + ((size_t)(b * 4 + h) * 128 + c) * NPOS + pos_base; };
	s_load_dwordx2 s[100:101], s[40:41], 0x158
	s_add_i32 s1, s18, 0xffffc000
	s_and_b32 s19, s18, 0x1f80
	s_ashr_i32 s0, s9, 9
	s_lshr_b32 s1, s1, 8
	s_addk_i32 s19, 0x100
	s_and_b32 s34, s18, 0x80
	v_lshlrev_b32_e32 v0, 4, v21
	s_cmpk_lt_i32 s4, 0x4000
	v_and_b32_e32 v0, 0xf0, v0
	v_ashrrev_i32_e32 v30, 4, v21
	s_cselect_b32 s35, s0, s1
	v_mad_u64_u32 v[22:23], s[0:1], v30, s23, v[0:1]
	s_cselect_b32 s19, s19, s34
	s_lshl_b32 s0, s35, 2
	s_or_b32 s0, s0, s5
	s_ashr_i32 s1, s0, 31
	s_lshl_b64 s[0:1], s[0:1], 7
	v_ashrrev_i32_e32 v31, 31, v30
	ds_read_b128 v[22:25], v22
	v_lshl_add_u64 v[30:31], s[0:1], 0, v[30:31]
	s_lshl_b32 s94, s19, 1
	s_waitcnt lgkmcnt(0)
	v_mov_b32_e32 v28, s100
	v_mov_b32_e32 v29, s101
	v_mad_u64_u32 v[28:29], s[34:35], v30, s68, v[28:29]
	v_mad_i32_i24 v29, v31, s68, v29
	v_lshl_add_u64 v[28:29], v[28:29], 0, s[94:95]
	v_lshl_add_u64 v[28:29], v[28:29], 0, v[0:1]
	global_store_dwordx4 v[28:29], v[22:25], off
	s_load_dwordx2 s[100:101], s[40:41], 0x158
	s_waitcnt lgkmcnt(0)
	v_mov_b32_e32 v28, s100
	v_mov_b32_e32 v29, s101
	s_nop 0
	v_add_u32_e32 v22, 0x100, v21
	v_ashrrev_i32_e32 v22, 4, v22
	v_mad_u64_u32 v[24:25], s[34:35], v22, s23, v[0:1]
	v_ashrrev_i32_e32 v23, 31, v22
	v_lshl_add_u64 v[30:31], s[0:1], 0, v[22:23]
	ds_read_b128 v[22:25], v24
	s_waitcnt lgkmcnt(0)
	v_mad_u64_u32 v[28:29], s[34:35], v30, s68, v[28:29]
	v_mad_i32_i24 v29, v31, s68, v29
	v_lshl_add_u64 v[28:29], v[28:29], 0, s[94:95]
	v_lshl_add_u64 v[28:29], v[28:29], 0, v[0:1]
	global_store_dwordx4 v[28:29], v[22:25], off
	s_load_dwordx2 s[100:101], s[40:41], 0x158
	s_waitcnt lgkmcnt(0)
	v_mov_b32_e32 v28, s100
	v_mov_b32_e32 v29, s101
	s_nop 0
	v_add_u32_e32 v22, 0x200, v21
	v_ashrrev_i32_e32 v22, 4, v22
	v_mad_u64_u32 v[24:25], s[34:35], v22, s23, v[0:1]
	v_ashrrev_i32_e32 v23, 31, v22
	v_lshl_add_u64 v[30:31], s[0:1], 0, v[22:23]
	ds_read_b128 v[22:25], v24
	s_waitcnt lgkmcnt(0)
	v_mad_u64_u32 v[28:29], s[34:35], v30, s68, v[28:29]
	v_mad_i32_i24 v29, v31, s68, v29
	v_lshl_add_u64 v[28:29], v[28:29], 0, s[94:95]
	v_lshl_add_u64 v[28:29], v[28:29], 0, v[0:1]
	global_store_dwordx4 v[28:29], v[22:25], off
	global_load_dwordx2 v[28:29], v[26:27], off offset:344
	s_nop 0
	v_add_u32_e32 v22, 0x300, v21
	v_ashrrev_i32_e32 v22, 4, v22
	v_mad_u64_u32 v[24:25], s[34:35], v22, s23, v[0:1]
	v_ashrrev_i32_e32 v23, 31, v22
	v_lshl_add_u64 v[30:31], s[0:1], 0, v[22:23]
	ds_read_b128 v[22:25], v24
	s_waitcnt vmcnt(0) lgkmcnt(0)
	v_mad_u64_u32 v[28:29], s[34:35], v30, s68, v[28:29]
	v_mad_i32_i24 v29, v31, s68, v29
	v_lshl_add_u64 v[28:29], v[28:29], 0, s[94:95]
	v_lshl_add_u64 v[28:29], v[28:29], 0, v[0:1]
	global_store_dwordx4 v[28:29], v[22:25], off
	global_load_dwordx2 v[28:29], v[26:27], off offset:344
	s_nop 0
	v_add_u32_e32 v22, 0x400, v21
	v_ashrrev_i32_e32 v22, 4, v22
	v_mad_u64_u32 v[24:25], s[34:35], v22, s23, v[0:1]
	v_ashrrev_i32_e32 v23, 31, v22
	v_lshl_add_u64 v[30:31], s[0:1], 0, v[22:23]
	ds_read_b128 v[22:25], v24
	s_waitcnt vmcnt(0) lgkmcnt(0)
	v_mad_u64_u32 v[28:29], s[34:35], v30, s68, v[28:29]
	v_mad_i32_i24 v29, v31, s68, v29
	v_lshl_add_u64 v[28:29], v[28:29], 0, s[94:95]
	v_lshl_add_u64 v[28:29], v[28:29], 0, v[0:1]
	global_store_dwordx4 v[28:29], v[22:25], off
	global_load_dwordx2 v[28:29], v[26:27], off offset:344
	s_nop 0
	v_add_u32_e32 v22, 0x500, v21
	v_ashrrev_i32_e32 v22, 4, v22
	v_mad_u64_u32 v[24:25], s[34:35], v22, s23, v[0:1]
	v_ashrrev_i32_e32 v23, 31, v22
	v_lshl_add_u64 v[30:31], s[0:1], 0, v[22:23]
	ds_read_b128 v[22:25], v24
	s_waitcnt vmcnt(0) lgkmcnt(0)
	v_mad_u64_u32 v[28:29], s[34:35], v30, s68, v[28:29]
	v_mad_i32_i24 v29, v31, s68, v29
	v_lshl_add_u64 v[28:29], v[28:29], 0, s[94:95]
	v_lshl_add_u64 v[28:29], v[28:29], 0, v[0:1]
	global_store_dwordx4 v[28:29], v[22:25], off
	global_load_dwordx2 v[28:29], v[26:27], off offset:344
	s_nop 0
	v_add_u32_e32 v22, 0x600, v21
	v_ashrrev_i32_e32 v22, 4, v22
	v_mad_u64_u32 v[24:25], s[34:35], v22, s23, v[0:1]
	v_ashrrev_i32_e32 v23, 31, v22
	v_lshl_add_u64 v[30:31], s[0:1], 0, v[22:23]
	ds_read_b128 v[22:25], v24
	v_add_u32_e32 v21, 0x700, v21
	s_waitcnt vmcnt(0) lgkmcnt(0)
	v_mad_u64_u32 v[28:29], s[34:35], v30, s68, v[28:29]
	v_mad_i32_i24 v29, v31, s68, v29
	v_lshl_add_u64 v[28:29], v[28:29], 0, s[94:95]
	v_lshl_add_u64 v[28:29], v[28:29], 0, v[0:1]
	global_store_dwordx4 v[28:29], v[22:25], off
	global_load_dwordx2 v[26:27], v[26:27], off offset:344
	s_nop 0
	v_ashrrev_i32_e32 v22, 4, v21
	v_mad_u64_u32 v[24:25], s[34:35], v22, s23, v[0:1]
	v_ashrrev_i32_e32 v23, 31, v22
	v_lshl_add_u64 v[28:29], s[0:1], 0, v[22:23]
	ds_read_b128 v[22:25], v24
	s_waitcnt vmcnt(0) lgkmcnt(0)
	v_mad_u64_u32 v[26:27], s[0:1], v28, s68, v[26:27]
	v_mad_i32_i24 v27, v29, s68, v27
	v_lshl_add_u64 v[26:27], v[26:27], 0, s[94:95]
	v_lshl_add_u64 v[26:27], v[26:27], 0, v[0:1]
	global_store_dwordx4 v[26:27], v[22:25], off
	s_cbranch_execnz .LBB0_572
	s_branch .LBB0_584

; __device__ __forceinline__ int tid_() { int t = threadIdx.x; asm volatile("" : "+v"(t)); return t; }
; __device__ __forceinline__ void phase_mix_a(const Params& p, int l, bool last, unsigned char* smem) {
;     ...
;       float* rsv = (float*)(smem + 65536 + 512);
;       {
;         const int t3 = tid_(), q = t3 >> 1, half = t3 & 1;
;         const u16* vp = p.PX + (size_t)(row_base + q) * 1024 + 256 + half * 128;
;         float s = 0.f;
; #pragma unroll
;         for (int i = 0; i < 16; ++i) {
;           const u32x4 w = *(const u32x4*)(vp + i * 8);
;           const float a0 = __uint_as_float(w.x << 16), a1 = __uint_as_float(w.x & 0xffff0000u), a2 = __uint_as_float(w.y << 16), a3 = __uint_as_float(w.y & 0xffff0000u);
;           const float a4 = __uint_as_float(w.z << 16), a5 = __uint_as_float(w.z & 0xffff0000u), a6 = __uint_as_float(w.w << 16), a7 = __uint_as_float(w.w & 0xffff0000u);
;           s += (a0 * a0 + a1 * a1) + (a2 * a2 + a3 * a3) + (a4 * a4 + a5 * a5) + (a6 * a6 + a7 * a7);
;         }
.LBB0_603:
	s_waitcnt vmcnt(0) lgkmcnt(0)
	v_mov_b64_e32 v[2:3], s[40:41]
	v_mov_b32_e32 v0, v187
	s_load_dwordx2 s[100:101], s[40:41], 0x48
	s_waitcnt lgkmcnt(0)
	v_mov_b32_e32 v6, s100
	v_mov_b32_e32 v7, s101
	s_load_dwordx2 s[100:101], s[40:41], 0x38
	s_waitcnt lgkmcnt(0)
	v_mov_b32_e32 v8, s100
	v_mov_b32_e32 v9, s101
	s_load_dwordx2 s[100:101], s[40:41], 0x120
	s_waitcnt lgkmcnt(0)
	v_mov_b32_e32 v2, s100
	v_mov_b32_e32 v3, s101
	s_and_b32 s38, s19, 0xffffff80
	v_ashrrev_i32_e32 v10, 1, v0
	v_add_u32_e32 v4, s38, v10
	v_ashrrev_i32_e32 v5, 31, v4
	v_and_b32_e32 v11, 1, v0
	v_lshlrev_b64 v[4:5], 11, v[4:5]
	v_lshlrev_b32_e32 v0, 8, v11
	v_cmp_lt_i32_e32 vcc, v212, v227
	s_waitcnt lgkmcnt(0)
	v_lshl_add_u64 v[2:3], v[2:3], 0, v[4:5]
	v_lshl_add_u64 v[2:3], v[2:3], 0, v[0:1]
	global_load_dwordx4 v[20:23], v[2:3], off offset:512
	global_load_dwordx4 v[24:27], v[2:3], off offset:528
	global_load_dwordx4 v[28:31], v[2:3], off offset:544
	global_load_dwordx4 v[32:35], v[2:3], off offset:560
	global_load_dwordx4 v[36:39], v[2:3], off offset:576
	global_load_dwordx4 v[40:43], v[2:3], off offset:592
	global_load_dwordx4 v[44:47], v[2:3], off offset:608
	global_load_dwordx4 v[48:51], v[2:3], off offset:624
	global_load_dwordx4 v[52:55], v[2:3], off offset:640
	global_load_dwordx4 v[56:59], v[2:3], off offset:656
	global_load_dwordx4 v[60:63], v[2:3], off offset:672
	global_load_dwordx4 v[64:67], v[2:3], off offset:688
	global_load_dwordx4 v[68:71], v[2:3], off offset:704
	global_load_dwordx4 v[72:75], v[2:3], off offset:720
	global_load_dwordx4 v[76:79], v[2:3], off offset:736
	s_waitcnt vmcnt(14) lgkmcnt(0)
	v_and_b32_e32 v4, 0xffff0000, v20
	v_lshlrev_b32_e32 v0, 16, v20
	v_and_b32_e32 v20, 0xffff0000, v21
	v_mul_f32_e32 v4, v4, v4
	v_lshlrev_b32_e32 v5, 16, v21
	v_fmac_f32_e32 v4, v0, v0
	v_mul_f32_e32 v0, v20, v20
	v_lshlrev_b32_e32 v21, 16, v22
	v_and_b32_e32 v22, 0xffff0000, v22
	v_fmac_f32_e32 v0, v5, v5
	v_add_f32_e32 v0, v4, v0
	v_mul_f32_e32 v4, v22, v22
	v_lshlrev_b32_e32 v16, 16, v23
	v_and_b32_e32 v23, 0xffff0000, v23
	v_fmac_f32_e32 v4, v21, v21
	v_add_f32_e32 v0, v4, v0
	v_mul_f32_e32 v4, v23, v23
	v_fmac_f32_e32 v4, v16, v16
	v_add_f32_e32 v0, v4, v0
	s_waitcnt vmcnt(13) lgkmcnt(0)
	v_and_b32_e32 v5, 0xffff0000, v24
	v_lshlrev_b32_e32 v4, 16, v24
	v_lshlrev_b32_e32 v24, 16, v25
	v_and_b32_e32 v25, 0xffff0000, v25
	v_mul_f32_e32 v5, v5, v5
	v_fmac_f32_e32 v5, v4, v4
	v_mul_f32_e32 v4, v25, v25
	v_lshlrev_b32_e32 v16, 16, v26
	v_and_b32_e32 v26, 0xffff0000, v26
	v_fmac_f32_e32 v4, v24, v24
	v_add_f32_e32 v4, v5, v4
	v_mul_f32_e32 v5, v26, v26
	v_lshlrev_b32_e32 v17, 16, v27
	v_and_b32_e32 v27, 0xffff0000, v27
	v_fmac_f32_e32 v5, v16, v16
	v_add_f32_e32 v4, v5, v4
	v_mul_f32_e32 v5, v27, v27
	v_fmac_f32_e32 v5, v17, v17
	v_add_f32_e32 v4, v5, v4
	v_add_f32_e32 v0, v0, v4
	s_waitcnt vmcnt(12) lgkmcnt(0)
	v_and_b32_e32 v5, 0xffff0000, v28
	v_lshlrev_b32_e32 v4, 16, v28
	v_lshlrev_b32_e32 v28, 16, v29
	v_and_b32_e32 v29, 0xffff0000, v29
	v_mul_f32_e32 v5, v5, v5
	v_fmac_f32_e32 v5, v4, v4
	v_mul_f32_e32 v4, v29, v29
	v_lshlrev_b32_e32 v16, 16, v30
	v_and_b32_e32 v30, 0xffff0000, v30
	v_fmac_f32_e32 v4, v28, v28
	v_add_f32_e32 v4, v5, v4
	v_mul_f32_e32 v5, v30, v30
	v_lshlrev_b32_e32 v17, 16, v31
	v_and_b32_e32 v31, 0xffff0000, v31
	v_fmac_f32_e32 v5, v16, v16
	v_add_f32_e32 v4, v5, v4
	v_mul_f32_e32 v5, v31, v31
	v_fmac_f32_e32 v5, v17, v17
	v_add_f32_e32 v4, v5, v4
	v_add_f32_e32 v0, v0, v4
	s_waitcnt vmcnt(11) lgkmcnt(0)
	v_and_b32_e32 v5, 0xffff0000, v32
	v_lshlrev_b32_e32 v4, 16, v32
	v_lshlrev_b32_e32 v32, 16, v33
	v_and_b32_e32 v33, 0xffff0000, v33
	v_mul_f32_e32 v5, v5, v5
	v_fmac_f32_e32 v5, v4, v4
	v_mul_f32_e32 v4, v33, v33
	v_lshlrev_b32_e32 v16, 16, v34
	v_and_b32_e32 v34, 0xffff0000, v34
	v_fmac_f32_e32 v4, v32, v32
	v_add_f32_e32 v4, v5, v4
	v_mul_f32_e32 v5, v34, v34
	v_lshlrev_b32_e32 v17, 16, v35
	v_and_b32_e32 v35, 0xffff0000, v35
	v_fmac_f32_e32 v5, v16, v16
	v_add_f32_e32 v4, v5, v4
	v_mul_f32_e32 v5, v35, v35
	v_fmac_f32_e32 v5, v17, v17
	v_add_f32_e32 v4, v5, v4
	v_add_f32_e32 v0, v0, v4
	s_waitcnt vmcnt(10) lgkmcnt(0)
	v_and_b32_e32 v5, 0xffff0000, v36
	v_lshlrev_b32_e32 v4, 16, v36
	v_lshlrev_b32_e32 v36, 16, v37
	v_and_b32_e32 v37, 0xffff0000, v37
	v_mul_f32_e32 v5, v5, v5
	v_fmac_f32_e32 v5, v4, v4
	v_mul_f32_e32 v4, v37, v37
	v_lshlrev_b32_e32 v16, 16, v38
	v_and_b32_e32 v38, 0xffff0000, v38
	v_fmac_f32_e32 v4, v36, v36
	v_add_f32_e32 v4, v5, v4
	v_mul_f32_e32 v5, v38, v38
	v_lshlrev_b32_e32 v17, 16, v39
	v_and_b32_e32 v39, 0xffff0000, v39
	v_fmac_f32_e32 v5, v16, v16
	v_add_f32_e32 v4, v5, v4
	v_mul_f32_e32 v5, v39, v39
	v_fmac_f32_e32 v5, v17, v17
	v_add_f32_e32 v4, v5, v4
	v_add_f32_e32 v0, v0, v4
	s_waitcnt vmcnt(9) lgkmcnt(0)
	v_and_b32_e32 v5, 0xffff0000, v40
	v_lshlrev_b32_e32 v4, 16, v40
	v_lshlrev_b32_e32 v40, 16, v41
	v_and_b32_e32 v41, 0xffff0000, v41
	v_mul_f32_e32 v5, v5, v5
	v_fmac_f32_e32 v5, v4, v4
	v_mul_f32_e32 v4, v41, v41
	v_lshlrev_b32_e32 v16, 16, v42
	v_and_b32_e32 v42, 0xffff0000, v42
	v_fmac_f32_e32 v4, v40, v40
	v_add_f32_e32 v4, v5, v4
	v_mul_f32_e32 v5, v42, v42
	v_lshlrev_b32_e32 v17, 16, v43
	v_and_b32_e32 v43, 0xffff0000, v43
	v_fmac_f32_e32 v5, v16, v16
	v_add_f32_e32 v4, v5, v4
	v_mul_f32_e32 v5, v43, v43
	v_fmac_f32_e32 v5, v17, v17
	v_add_f32_e32 v4, v5, v4
	v_add_f32_e32 v0, v0, v4
	s_waitcnt vmcnt(8) lgkmcnt(0)
; __device__ __forceinline__ void phase_mix_a(const Params& p, int l, bool last, unsigned char* smem) {
;     ...
; #pragma unroll
;         for (int i = 0; i < 16; ++i) {
;           const u32x4 w = *(const u32x4*)(vp + i * 8);
;           const float a0 = __uint_as_float(w.x << 16), a1 = __uint_as_float(w.x & 0xffff0000u), a2 = __uint_as_float(w.y << 16), a3 = __uint_as_float(w.y & 0xffff0000u);
;           const float a4 = __uint_as_float(w.z << 16), a5 = __uint_as_float(w.z & 0xffff0000u), a6 = __uint_as_float(w.w << 16), a7 = __uint_as_float(w.w & 0xffff0000u);
;           s += (a0 * a0 + a1 * a1) + (a2 * a2 + a3 * a3) + (a4 * a4 + a5 * a5) + (a6 * a6 + a7 * a7);
;         }
;         s += __shfl_xor(s, 1);
;         __syncthreads();
;         if (half == 0) rsv[q] = rsqrtf(s * (1.f / 256.f) + 1e-6f);
	v_and_b32_e32 v5, 0xffff0000, v44
	v_lshlrev_b32_e32 v4, 16, v44
	v_lshlrev_b32_e32 v44, 16, v45
	v_and_b32_e32 v45, 0xffff0000, v45
	v_mul_f32_e32 v5, v5, v5
	v_fmac_f32_e32 v5, v4, v4
	v_mul_f32_e32 v4, v45, v45
	v_lshlrev_b32_e32 v16, 16, v46
	v_and_b32_e32 v46, 0xffff0000, v46
	v_fmac_f32_e32 v4, v44, v44
	v_add_f32_e32 v4, v5, v4
	v_mul_f32_e32 v5, v46, v46
	v_lshlrev_b32_e32 v17, 16, v47
	v_and_b32_e32 v47, 0xffff0000, v47
	v_fmac_f32_e32 v5, v16, v16
	v_add_f32_e32 v4, v5, v4
	v_mul_f32_e32 v5, v47, v47
	v_fmac_f32_e32 v5, v17, v17
	v_add_f32_e32 v4, v5, v4
	v_add_f32_e32 v0, v0, v4
	s_waitcnt vmcnt(7) lgkmcnt(0)
	v_and_b32_e32 v5, 0xffff0000, v48
	v_lshlrev_b32_e32 v4, 16, v48
	v_lshlrev_b32_e32 v48, 16, v49
	v_and_b32_e32 v49, 0xffff0000, v49
	v_mul_f32_e32 v5, v5, v5
	v_fmac_f32_e32 v5, v4, v4
	v_mul_f32_e32 v4, v49, v49
	v_lshlrev_b32_e32 v16, 16, v50
	v_and_b32_e32 v50, 0xffff0000, v50
	v_fmac_f32_e32 v4, v48, v48
	v_add_f32_e32 v4, v5, v4
	v_mul_f32_e32 v5, v50, v50
	v_lshlrev_b32_e32 v17, 16, v51
	v_and_b32_e32 v51, 0xffff0000, v51
	v_fmac_f32_e32 v5, v16, v16
	v_add_f32_e32 v4, v5, v4
	v_mul_f32_e32 v5, v51, v51
	v_fmac_f32_e32 v5, v17, v17
	v_add_f32_e32 v4, v5, v4
	v_add_f32_e32 v0, v0, v4
	s_waitcnt vmcnt(6) lgkmcnt(0)
	v_and_b32_e32 v5, 0xffff0000, v52
	v_lshlrev_b32_e32 v4, 16, v52
	v_lshlrev_b32_e32 v52, 16, v53
	v_and_b32_e32 v53, 0xffff0000, v53
	v_mul_f32_e32 v5, v5, v5
	v_fmac_f32_e32 v5, v4, v4
	v_mul_f32_e32 v4, v53, v53
	v_lshlrev_b32_e32 v16, 16, v54
	v_and_b32_e32 v54, 0xffff0000, v54
	v_fmac_f32_e32 v4, v52, v52
	v_add_f32_e32 v4, v5, v4
	v_mul_f32_e32 v5, v54, v54
	v_lshlrev_b32_e32 v17, 16, v55
	v_and_b32_e32 v55, 0xffff0000, v55
	v_fmac_f32_e32 v5, v16, v16
	v_add_f32_e32 v4, v5, v4
	v_mul_f32_e32 v5, v55, v55
	v_fmac_f32_e32 v5, v17, v17
	v_add_f32_e32 v4, v5, v4
	v_add_f32_e32 v0, v0, v4
	s_waitcnt vmcnt(5) lgkmcnt(0)
	v_and_b32_e32 v5, 0xffff0000, v56
	v_lshlrev_b32_e32 v4, 16, v56
	v_lshlrev_b32_e32 v56, 16, v57
	v_and_b32_e32 v57, 0xffff0000, v57
	v_mul_f32_e32 v5, v5, v5
	v_fmac_f32_e32 v5, v4, v4
	v_mul_f32_e32 v4, v57, v57
	v_lshlrev_b32_e32 v16, 16, v58
	v_and_b32_e32 v58, 0xffff0000, v58
	v_fmac_f32_e32 v4, v56, v56
	v_add_f32_e32 v4, v5, v4
	v_mul_f32_e32 v5, v58, v58
	v_lshlrev_b32_e32 v17, 16, v59
	v_and_b32_e32 v59, 0xffff0000, v59
	v_fmac_f32_e32 v5, v16, v16
	v_add_f32_e32 v4, v5, v4
	v_mul_f32_e32 v5, v59, v59
	v_fmac_f32_e32 v5, v17, v17
	v_add_f32_e32 v4, v5, v4
	v_add_f32_e32 v0, v0, v4
	s_waitcnt vmcnt(4) lgkmcnt(0)
	v_and_b32_e32 v5, 0xffff0000, v60
	v_lshlrev_b32_e32 v4, 16, v60
	v_lshlrev_b32_e32 v60, 16, v61
	v_and_b32_e32 v61, 0xffff0000, v61
	v_mul_f32_e32 v5, v5, v5
	v_fmac_f32_e32 v5, v4, v4
	v_mul_f32_e32 v4, v61, v61
	v_lshlrev_b32_e32 v16, 16, v62
	v_and_b32_e32 v62, 0xffff0000, v62
	v_fmac_f32_e32 v4, v60, v60
	v_add_f32_e32 v4, v5, v4
	v_mul_f32_e32 v5, v62, v62
	v_lshlrev_b32_e32 v17, 16, v63
	v_and_b32_e32 v63, 0xffff0000, v63
	v_fmac_f32_e32 v5, v16, v16
	v_add_f32_e32 v4, v5, v4
	v_mul_f32_e32 v5, v63, v63
	v_fmac_f32_e32 v5, v17, v17
	v_add_f32_e32 v4, v5, v4
	v_add_f32_e32 v0, v0, v4
	s_waitcnt vmcnt(3) lgkmcnt(0)
	v_and_b32_e32 v5, 0xffff0000, v64
	v_lshlrev_b32_e32 v4, 16, v64
	v_lshlrev_b32_e32 v64, 16, v65
	v_and_b32_e32 v65, 0xffff0000, v65
	v_mul_f32_e32 v5, v5, v5
	v_fmac_f32_e32 v5, v4, v4
	v_mul_f32_e32 v4, v65, v65
	v_lshlrev_b32_e32 v16, 16, v66
	v_and_b32_e32 v66, 0xffff0000, v66
	v_fmac_f32_e32 v4, v64, v64
	v_add_f32_e32 v4, v5, v4
	v_mul_f32_e32 v5, v66, v66
	v_lshlrev_b32_e32 v17, 16, v67
	v_and_b32_e32 v67, 0xffff0000, v67
	v_fmac_f32_e32 v5, v16, v16
	v_add_f32_e32 v4, v5, v4
	v_mul_f32_e32 v5, v67, v67
	v_fmac_f32_e32 v5, v17, v17
	v_add_f32_e32 v4, v5, v4
	v_add_f32_e32 v0, v0, v4
	s_waitcnt vmcnt(2) lgkmcnt(0)
	v_and_b32_e32 v5, 0xffff0000, v68
	v_lshlrev_b32_e32 v4, 16, v68
	v_lshlrev_b32_e32 v68, 16, v69
	v_and_b32_e32 v69, 0xffff0000, v69
	v_mul_f32_e32 v5, v5, v5
	v_fmac_f32_e32 v5, v4, v4
	v_mul_f32_e32 v4, v69, v69
	v_lshlrev_b32_e32 v16, 16, v70
	v_and_b32_e32 v70, 0xffff0000, v70
	v_fmac_f32_e32 v4, v68, v68
	v_add_f32_e32 v4, v5, v4
	v_mul_f32_e32 v5, v70, v70
	v_lshlrev_b32_e32 v17, 16, v71
	v_and_b32_e32 v71, 0xffff0000, v71
	v_fmac_f32_e32 v5, v16, v16
	v_add_f32_e32 v4, v5, v4
	v_mul_f32_e32 v5, v71, v71
	v_fmac_f32_e32 v5, v17, v17
	v_add_f32_e32 v4, v5, v4
	v_add_f32_e32 v0, v0, v4
	s_waitcnt vmcnt(1) lgkmcnt(0)
	v_and_b32_e32 v5, 0xffff0000, v72
	v_lshlrev_b32_e32 v4, 16, v72
	v_lshlrev_b32_e32 v72, 16, v73
	v_and_b32_e32 v73, 0xffff0000, v73
	v_mul_f32_e32 v5, v5, v5
	v_fmac_f32_e32 v5, v4, v4
	v_mul_f32_e32 v4, v73, v73
	v_lshlrev_b32_e32 v16, 16, v74
	v_and_b32_e32 v74, 0xffff0000, v74
	v_fmac_f32_e32 v4, v72, v72
	v_add_f32_e32 v4, v5, v4
	v_mul_f32_e32 v5, v74, v74
	v_lshlrev_b32_e32 v17, 16, v75
	v_and_b32_e32 v75, 0xffff0000, v75
	v_fmac_f32_e32 v5, v16, v16
	v_add_f32_e32 v4, v5, v4
	v_mul_f32_e32 v5, v75, v75
	v_fmac_f32_e32 v5, v17, v17
	v_add_f32_e32 v4, v5, v4
	v_add_f32_e32 v0, v0, v4
	s_waitcnt vmcnt(0) lgkmcnt(0)
	v_and_b32_e32 v5, 0xffff0000, v76
	v_lshlrev_b32_e32 v4, 16, v76
	v_lshlrev_b32_e32 v76, 16, v77
	v_and_b32_e32 v77, 0xffff0000, v77
	v_mul_f32_e32 v5, v5, v5
	v_fmac_f32_e32 v5, v4, v4
	v_mul_f32_e32 v4, v77, v77
	v_lshlrev_b32_e32 v16, 16, v78
	v_and_b32_e32 v78, 0xffff0000, v78
	v_fmac_f32_e32 v4, v76, v76
	v_add_f32_e32 v4, v5, v4
	v_mul_f32_e32 v5, v78, v78
	v_lshlrev_b32_e32 v17, 16, v79
	v_and_b32_e32 v79, 0xffff0000, v79
	v_fmac_f32_e32 v5, v16, v16
	v_add_f32_e32 v4, v5, v4
	v_mul_f32_e32 v5, v79, v79
	v_fmac_f32_e32 v5, v17, v17
	v_add_f32_e32 v4, v5, v4
	v_add_f32_e32 v0, v0, v4
	global_load_dwordx4 v[2:5], v[2:3], off offset:752
	s_waitcnt lgkmcnt(0)
	s_barrier
	s_waitcnt vmcnt(0)
	v_lshlrev_b32_e32 v12, 16, v2
	v_and_b32_e32 v2, 0xffff0000, v2
	v_lshlrev_b32_e32 v13, 16, v3
	v_and_b32_e32 v3, 0xffff0000, v3
	v_mul_f32_e32 v2, v2, v2
	v_mul_f32_e32 v3, v3, v3
	v_lshlrev_b32_e32 v14, 16, v4
	v_and_b32_e32 v4, 0xffff0000, v4
	v_fmac_f32_e32 v2, v12, v12
	v_fmac_f32_e32 v3, v13, v13
	v_add_f32_e32 v2, v2, v3
	v_mul_f32_e32 v3, v4, v4
	v_lshlrev_b32_e32 v15, 16, v5
	v_and_b32_e32 v5, 0xffff0000, v5
	v_fmac_f32_e32 v3, v14, v14
	v_add_f32_e32 v2, v3, v2
	v_mul_f32_e32 v3, v5, v5
	v_fmac_f32_e32 v3, v15, v15
	v_add_f32_e32 v2, v3, v2
	v_add_f32_e32 v0, v0, v2
	v_cndmask_b32_e32 v2, v186, v212, vcc
	v_lshlrev_b32_e32 v2, 2, v2
	ds_bpermute_b32 v2, v2, v0
	v_cmp_eq_u32_e32 vcc, 0, v11
	s_and_saveexec_b64 s[0:1], vcc
	s_cbranch_execz .LBB0_602
	s_waitcnt lgkmcnt(0)
	v_add_f32_e32 v0, v0, v2
	v_fmamk_f32 v0, v0, 0x3b800000, v224
	v_mul_f32_e32 v2, 0x4b800000, v0
	v_cmp_gt_f32_e32 vcc, s85, v0
	s_nop 1
	v_cndmask_b32_e32 v0, v0, v2, vcc
	v_rsq_f32_e32 v0, v0
	s_nop 0
	v_mul_f32_e32 v2, 0x45800000, v0
	v_cndmask_b32_e32 v0, v0, v2, vcc
	v_mov_b32_e32 v2, 0x10200
	v_lshl_add_u32 v2, v10, 2, v2
	ds_write_b32 v2, v0
	s_branch .LBB0_602

; template <int NT, bool BKN, bool MASK = false, bool ROWSS = false, class Epi> ...
;     ...
;   for (int kt = 0; kt < nk - 2; kt += 2) {
;     GEMM_COMPUTE(0);
;     GEMM_STORE(ra1, rb1, 1);
;     GEMM_LOAD(ra1, rb1, kt + 3);
;     __syncthreads();
;     GEMM_COMPUTE(1);
;     GEMM_STORE(ra0, rb0, 0);
;     GEMM_LOAD(ra0, rb0, (kt + 4 < nkm1 ? kt + 4 : nkm1));
;     __syncthreads();
;   }
.LBB0_628:
	ds_read_b128 v[198:201], v197
	ds_read_b128 v[202:205], v197 offset:2048
	ds_read_b128 v[206:209], v197 offset:4096
	ds_read_b128 v[210:213], v197 offset:6144
	ds_read_b128 v[230:233], v196 offset:16384
	ds_read_b128 v[234:237], v196 offset:18432
	ds_read_b128 v[238:241], v196 offset:20480
	ds_read_b128 v[242:245], v196 offset:22528
	s_mov_b32 s1, 0xfffe8000
	s_waitcnt lgkmcnt(0)
	v_mfma_f32_16x16x32_bf16 v[126:129], v[198:201], v[230:233], v[126:129]
	s_add_i32 s0, s0, 2
	v_mfma_f32_16x16x32_bf16 v[122:125], v[198:201], v[234:237], v[122:125]
	v_mfma_f32_16x16x32_bf16 v[114:117], v[198:201], v[238:241], v[114:117]
	v_mfma_f32_16x16x32_bf16 v[110:113], v[198:201], v[242:245], v[110:113]
	v_mfma_f32_16x16x32_bf16 v[106:109], v[202:205], v[230:233], v[106:109]
	v_mfma_f32_16x16x32_bf16 v[102:105], v[202:205], v[234:237], v[102:105]
	v_mfma_f32_16x16x32_bf16 v[98:101], v[202:205], v[238:241], v[98:101]
	v_mfma_f32_16x16x32_bf16 v[94:97], v[202:205], v[242:245], v[94:97]
	v_mfma_f32_16x16x32_bf16 v[90:93], v[206:209], v[230:233], v[90:93]
	v_mfma_f32_16x16x32_bf16 v[198:201], v[206:209], v[234:237], v[86:89]
	v_mfma_f32_16x16x32_bf16 v[202:205], v[206:209], v[238:241], v[82:85]
	v_mfma_f32_16x16x32_bf16 v[206:209], v[206:209], v[242:245], v[78:81]
	v_mfma_f32_16x16x32_bf16 v[230:233], v[210:213], v[230:233], v[74:77]
	v_mfma_f32_16x16x32_bf16 v[234:237], v[210:213], v[234:237], v[66:69]
	v_mfma_f32_16x16x32_bf16 v[238:241], v[210:213], v[238:241], v[62:65]
	v_mfma_f32_16x16x32_bf16 v[210:213], v[210:213], v[242:245], v[50:53]
	s_nop 1
	ds_read_b128 v[62:65], v195
	ds_read_b128 v[82:85], v195 offset:2048
	ds_read_b128 v[242:245], v195 offset:4096
	ds_read_b128 v[246:249], v195 offset:6144
	ds_read_b128 v[250:253], v194 offset:16384
	ds_read_b128 v[220:223], v194 offset:18432
	ds_read_b128 v[224:227], v194 offset:20480
	ds_read_b128 v[216:219], v194 offset:22528
	s_waitcnt vmcnt(0)
	ds_write_b128 v160, v[14:17] offset:32768
	s_waitcnt vmcnt(0)
	ds_write_b128 v160, v[22:25] offset:36864
	ds_write_b128 v160, v[26:29] offset:40960
	ds_write_b128 v160, v[30:33] offset:45056
	ds_write_b16 v161, v18 offset:49152
	ds_write_b16_d16_hi v0, v18 offset:49280
	ds_write_b16 v162, v19 offset:49152
	ds_write_b16_d16_hi v163, v19 offset:49152
	ds_write_b16 v164, v20 offset:49152
	ds_write_b16_d16_hi v165, v20 offset:49152
	ds_write_b16 v166, v21 offset:49152
	ds_write_b16_d16_hi v167, v21 offset:49152
	ds_write_b16 v169, v10 offset:49152
	ds_write_b16_d16_hi v168, v10 offset:49280
	ds_write_b16 v170, v11 offset:49152
	ds_write_b16_d16_hi v171, v11 offset:49152
	ds_write_b16 v172, v12 offset:49152
	ds_write_b16_d16_hi v173, v12 offset:49152
	ds_write_b16 v174, v13 offset:49152
	ds_write_b16_d16_hi v175, v13 offset:49152
	ds_write_b16 v176, v2 offset:49152
	ds_write_b16_d16_hi v177, v2 offset:49280
	ds_write_b16 v178, v3 offset:49152
	ds_write_b16_d16_hi v179, v3 offset:49152
	ds_write_b16 v180, v4 offset:49152
	ds_write_b16_d16_hi v181, v4 offset:49152
	ds_write_b16 v182, v5 offset:49152
	ds_write_b16_d16_hi v183, v5 offset:49152
	ds_write_b16 v184, v6 offset:49152
	ds_write_b16_d16_hi v185, v6 offset:49280
	ds_write_b16 v188, v7 offset:49152
	ds_write_b16_d16_hi v189, v7 offset:49152
	ds_write_b16 v190, v8 offset:49152
	ds_write_b16_d16_hi v191, v8 offset:49152
	ds_write_b16 v192, v9 offset:49152
	ds_write_b16_d16_hi v193, v9 offset:49152
	v_add_co_u32_e32 v2, vcc, s1, v154
	s_mov_b32 s1, 0xffff0000
	s_nop 0
	v_addc_co_u32_e32 v3, vcc, -1, v155, vcc
	global_load_dwordx4 v[14:17], v[2:3], off
	v_add_co_u32_e32 v2, vcc, s1, v154
	s_movk_i32 s1, 0x8000
	s_nop 0
	v_addc_co_u32_e32 v3, vcc, -1, v155, vcc
	global_load_dwordx4 v[22:25], v[2:3], off
	v_add_co_u32_e32 v2, vcc, s1, v154
	v_lshl_add_u64 v[6:7], v[146:147], 0, s[38:39]
	s_nop 0
	v_addc_co_u32_e32 v3, vcc, -1, v155, vcc
	global_load_dwordx4 v[26:29], v[2:3], off
	global_load_dwordx4 v[30:33], v[154:155], off
	v_lshl_add_u64 v[2:3], v[152:153], 0, s[38:39]
	global_load_dwordx4 v[18:21], v[2:3], off
	v_lshl_add_u64 v[2:3], v[150:151], 0, s[38:39]
	global_load_dwordx4 v[10:13], v[2:3], off
	v_lshl_add_u64 v[2:3], v[148:149], 0, s[38:39]
	s_waitcnt lgkmcnt(0)
	v_mfma_f32_16x16x32_bf16 v[126:129], v[62:65], v[250:253], v[126:129]
	global_load_dwordx4 v[2:5], v[2:3], off
	s_min_u32 s1, s0, 3
	global_load_dwordx4 v[6:9], v[6:7], off
	v_mfma_f32_16x16x32_bf16 v[122:125], v[62:65], v[220:223], v[122:125]
	s_waitcnt lgkmcnt(0)
	s_barrier
; template <int NT, bool BKN, bool MASK = false, bool ROWSS = false, class Epi> ...
;     ...
;   for (int kt = 0; kt < nk - 2; kt += 2) {
;     GEMM_COMPUTE(0);
;     GEMM_STORE(ra1, rb1, 1);
;     GEMM_LOAD(ra1, rb1, kt + 3);
;     __syncthreads();
;     GEMM_COMPUTE(1);
;     GEMM_STORE(ra0, rb0, 0);
;     GEMM_LOAD(ra0, rb0, (kt + 4 < nkm1 ? kt + 4 : nkm1));
;     __syncthreads();
;   }
	v_mfma_f32_16x16x32_bf16 v[50:53], v[62:65], v[224:227], v[114:117]
	s_lshl_b32 s94, s1, 7
	v_lshl_add_u64 v[146:147], v[146:147], 0, s[12:13]
	v_lshl_add_u64 v[148:149], v[148:149], 0, s[12:13]
	v_mfma_f32_16x16x32_bf16 v[62:65], v[62:65], v[216:219], v[110:113]
	v_lshl_add_u64 v[150:151], v[150:151], 0, s[12:13]
	v_lshl_add_u64 v[152:153], v[152:153], 0, s[12:13]
	v_lshl_add_u64 v[154:155], v[154:155], 0, s[6:7]
	v_mfma_f32_16x16x32_bf16 v[66:69], v[82:85], v[250:253], v[106:109]
	v_mfma_f32_16x16x32_bf16 v[74:77], v[82:85], v[220:223], v[102:105]
	v_mfma_f32_16x16x32_bf16 v[78:81], v[82:85], v[224:227], v[98:101]
	v_mfma_f32_16x16x32_bf16 v[82:85], v[82:85], v[216:219], v[94:97]
	v_mfma_f32_16x16x32_bf16 v[86:89], v[242:245], v[250:253], v[90:93]
	v_mfma_f32_16x16x32_bf16 v[90:93], v[242:245], v[220:223], v[198:201]
	v_mfma_f32_16x16x32_bf16 v[94:97], v[242:245], v[224:227], v[202:205]
	v_mfma_f32_16x16x32_bf16 v[98:101], v[242:245], v[216:219], v[206:209]
	v_mfma_f32_16x16x32_bf16 v[102:105], v[246:249], v[250:253], v[230:233]
	v_mfma_f32_16x16x32_bf16 v[106:109], v[246:249], v[220:223], v[234:237]
	v_mfma_f32_16x16x32_bf16 v[110:113], v[246:249], v[224:227], v[238:241]
	v_mfma_f32_16x16x32_bf16 v[114:117], v[246:249], v[216:219], v[210:213]
	ds_read_b128 v[198:201], v197 offset:32768
	ds_read_b128 v[202:205], v197 offset:34816
	ds_read_b128 v[206:209], v197 offset:36864
	ds_read_b128 v[210:213], v197 offset:38912
	ds_read_b128 v[216:219], v196 offset:49152
	ds_read_b128 v[220:223], v196 offset:51200
	ds_read_b128 v[224:227], v196 offset:53248
	ds_read_b128 v[230:233], v196 offset:55296
	s_waitcnt lgkmcnt(0)
	v_mfma_f32_16x16x32_bf16 v[126:129], v[198:201], v[216:219], v[126:129]
	v_mfma_f32_16x16x32_bf16 v[122:125], v[198:201], v[220:223], v[122:125]
	v_mfma_f32_16x16x32_bf16 v[50:53], v[198:201], v[224:227], v[50:53]
	v_mfma_f32_16x16x32_bf16 v[62:65], v[198:201], v[230:233], v[62:65]
	v_mfma_f32_16x16x32_bf16 v[66:69], v[202:205], v[216:219], v[66:69]
	v_mfma_f32_16x16x32_bf16 v[74:77], v[202:205], v[220:223], v[74:77]
	v_mfma_f32_16x16x32_bf16 v[78:81], v[202:205], v[224:227], v[78:81]
	v_mfma_f32_16x16x32_bf16 v[82:85], v[202:205], v[230:233], v[82:85]
	v_mfma_f32_16x16x32_bf16 v[86:89], v[206:209], v[216:219], v[86:89]
	v_mfma_f32_16x16x32_bf16 v[198:201], v[206:209], v[220:223], v[90:93]
	v_mfma_f32_16x16x32_bf16 v[202:205], v[206:209], v[224:227], v[94:97]
	v_mfma_f32_16x16x32_bf16 v[206:209], v[206:209], v[230:233], v[98:101]
	v_mfma_f32_16x16x32_bf16 v[216:219], v[210:213], v[216:219], v[102:105]
	v_mfma_f32_16x16x32_bf16 v[220:223], v[210:213], v[220:223], v[106:109]
	v_mfma_f32_16x16x32_bf16 v[224:227], v[210:213], v[224:227], v[110:113]
	v_mfma_f32_16x16x32_bf16 v[210:213], v[210:213], v[230:233], v[114:117]
	ds_read_b128 v[90:93], v195 offset:32768
	ds_read_b128 v[94:97], v195 offset:34816
	ds_read_b128 v[230:233], v195 offset:36864
	ds_read_b128 v[234:237], v195 offset:38912
	ds_read_b128 v[238:241], v194 offset:49152
	ds_read_b128 v[242:245], v194 offset:51200
	ds_read_b128 v[246:249], v194 offset:53248
	ds_read_b128 v[250:253], v194 offset:55296
	ds_write_b128 v160, v[34:37]
	ds_write_b128 v160, v[38:41] offset:4096
	ds_write_b128 v160, v[42:45] offset:8192
	ds_write_b128 v160, v[46:49] offset:12288
	ds_write_b16 v161, v54 offset:16384
	ds_write_b16_d16_hi v0, v54 offset:16512
	ds_write_b16 v162, v55 offset:16384
	ds_write_b16_d16_hi v163, v55 offset:16384
	ds_write_b16 v164, v56 offset:16384
	ds_write_b16_d16_hi v165, v56 offset:16384
	ds_write_b16 v166, v57 offset:16384
	ds_write_b16_d16_hi v167, v57 offset:16384
	ds_write_b16 v169, v58 offset:16384
	ds_write_b16_d16_hi v168, v58 offset:16512
	ds_write_b16 v170, v59 offset:16384
	ds_write_b16_d16_hi v171, v59 offset:16384
	ds_write_b16 v172, v60 offset:16384
	ds_write_b16_d16_hi v173, v60 offset:16384
	ds_write_b16 v174, v61 offset:16384
	ds_write_b16_d16_hi v175, v61 offset:16384
	ds_write_b16 v176, v70 offset:16384
	ds_write_b16_d16_hi v177, v70 offset:16512
	ds_write_b16 v178, v71 offset:16384
	ds_write_b16_d16_hi v179, v71 offset:16384
	ds_write_b16 v180, v72 offset:16384
	ds_write_b16_d16_hi v181, v72 offset:16384
	ds_write_b16 v182, v73 offset:16384
	ds_write_b16_d16_hi v183, v73 offset:16384
	ds_write_b16 v184, v118 offset:16384
	ds_write_b16_d16_hi v185, v118 offset:16512
	ds_write_b16 v188, v119 offset:16384
	ds_write_b16_d16_hi v189, v119 offset:16384
	ds_write_b16 v190, v120 offset:16384
	ds_write_b16_d16_hi v191, v120 offset:16384
	ds_write_b16 v192, v121 offset:16384
	ds_write_b16_d16_hi v193, v121 offset:16384
	v_lshl_add_u64 v[34:35], v[130:131], 0, s[94:95]
	v_lshl_add_u64 v[38:39], v[136:137], 0, s[94:95]
	v_lshl_add_u64 v[42:43], v[138:139], 0, s[94:95]
	v_lshl_add_u64 v[46:47], v[140:141], 0, s[94:95]
	s_lshl_b32 s94, s1, 15
	v_lshl_add_u64 v[54:55], v[132:133], 0, s[94:95]
	v_add_co_u32_e32 v54, vcc, s16, v54
	v_lshl_add_u64 v[58:59], v[134:135], 0, s[94:95]
	s_nop 0
	v_addc_co_u32_e32 v55, vcc, 0, v55, vcc
	v_add_co_u32_e32 v58, vcc, s16, v58
	v_lshl_add_u64 v[70:71], v[142:143], 0, s[94:95]
	s_nop 0
	v_addc_co_u32_e32 v59, vcc, 0, v59, vcc
	v_add_co_u32_e32 v70, vcc, s16, v70
	v_lshl_add_u64 v[118:119], v[144:145], 0, s[94:95]
	s_nop 0
	v_addc_co_u32_e32 v71, vcc, 0, v71, vcc
	v_add_co_u32_e32 v118, vcc, s16, v118
	global_load_dwordx4 v[34:37], v[34:35], off offset:512
	s_nop 0
	v_addc_co_u32_e32 v119, vcc, 0, v119, vcc
	global_load_dwordx4 v[38:41], v[38:39], off offset:512
	s_waitcnt lgkmcnt(0)
	v_mfma_f32_16x16x32_bf16 v[126:129], v[90:93], v[238:241], v[126:129]
	global_load_dwordx4 v[42:45], v[42:43], off offset:512
	s_cmp_lt_u32 s0, 4
	global_load_dwordx4 v[46:49], v[46:47], off offset:512
	v_mfma_f32_16x16x32_bf16 v[122:125], v[90:93], v[242:245], v[122:125]
	global_load_dwordx4 v[54:57], v[54:55], off
	s_nop 0
	global_load_dwordx4 v[58:61], v[58:59], off
	v_mfma_f32_16x16x32_bf16 v[114:117], v[90:93], v[246:249], v[50:53]
	global_load_dwordx4 v[70:73], v[70:71], off
	s_nop 0
	global_load_dwordx4 v[118:121], v[118:119], off
	v_mfma_f32_16x16x32_bf16 v[110:113], v[90:93], v[250:253], v[62:65]
	s_waitcnt lgkmcnt(0)
	s_barrier
; template <int NT, bool BKN, bool MASK = false, bool ROWSS = false, class Epi> ...
;     ...
;   GEMM_COMPUTE(0);
;   GEMM_STORE(ra1, rb1, 1);
;   __syncthreads();
	v_mfma_f32_16x16x32_bf16 v[106:109], v[94:97], v[238:241], v[66:69]
	v_mfma_f32_16x16x32_bf16 v[102:105], v[94:97], v[242:245], v[74:77]
	v_mfma_f32_16x16x32_bf16 v[98:101], v[94:97], v[246:249], v[78:81]
	v_mfma_f32_16x16x32_bf16 v[94:97], v[94:97], v[250:253], v[82:85]
	v_mfma_f32_16x16x32_bf16 v[90:93], v[230:233], v[238:241], v[86:89]
	v_mfma_f32_16x16x32_bf16 v[86:89], v[230:233], v[242:245], v[198:201]
	v_mfma_f32_16x16x32_bf16 v[82:85], v[230:233], v[246:249], v[202:205]
	v_mfma_f32_16x16x32_bf16 v[78:81], v[230:233], v[250:253], v[206:209]
	v_mfma_f32_16x16x32_bf16 v[74:77], v[234:237], v[238:241], v[216:219]
	v_mfma_f32_16x16x32_bf16 v[66:69], v[234:237], v[242:245], v[220:223]
	v_mfma_f32_16x16x32_bf16 v[62:65], v[234:237], v[246:249], v[224:227]
	v_mfma_f32_16x16x32_bf16 v[50:53], v[234:237], v[250:253], v[210:213]
	s_cbranch_scc1 .LBB0_628
	s_waitcnt vmcnt(0)
	ds_read_b128 v[34:37], v197
	ds_read_b128 v[38:41], v197 offset:2048
	ds_read_b128 v[42:45], v197 offset:4096
	ds_read_b128 v[46:49], v197 offset:6144
	ds_read_b128 v[54:57], v196 offset:16384
	ds_read_b128 v[58:61], v196 offset:18432
	ds_read_b128 v[70:73], v196 offset:20480
	ds_read_b128 v[118:121], v196 offset:22528
	s_lshl_b32 s0, s19, 7
	s_waitcnt lgkmcnt(3)
	v_mfma_f32_16x16x32_bf16 v[126:129], v[34:37], v[54:57], v[126:129]
	s_lshl_b32 s1, s4, 8
	s_or_b32 s0, s1, s0
	s_addk_i32 s0, 0x4000
	s_waitcnt lgkmcnt(2)
	v_mfma_f32_16x16x32_bf16 v[122:125], v[34:37], v[58:61], v[122:125]
	s_lshl_b32 s94, s18, 1
	s_waitcnt lgkmcnt(1)
	v_mfma_f32_16x16x32_bf16 v[114:117], v[34:37], v[70:73], v[114:117]
	s_waitcnt lgkmcnt(0)
	v_mfma_f32_16x16x32_bf16 v[34:37], v[34:37], v[118:121], v[110:113]
	v_mfma_f32_16x16x32_bf16 v[106:109], v[38:41], v[54:57], v[106:109]
	v_mfma_f32_16x16x32_bf16 v[102:105], v[38:41], v[58:61], v[102:105]
	v_mfma_f32_16x16x32_bf16 v[98:101], v[38:41], v[70:73], v[98:101]
	v_mfma_f32_16x16x32_bf16 v[38:41], v[38:41], v[118:121], v[94:97]
	v_mfma_f32_16x16x32_bf16 v[90:93], v[42:45], v[54:57], v[90:93]
	v_mfma_f32_16x16x32_bf16 v[86:89], v[42:45], v[58:61], v[86:89]
	v_mfma_f32_16x16x32_bf16 v[82:85], v[42:45], v[70:73], v[82:85]
	v_mfma_f32_16x16x32_bf16 v[42:45], v[42:45], v[118:121], v[78:81]
	v_mfma_f32_16x16x32_bf16 v[54:57], v[46:49], v[54:57], v[74:77]
	v_mfma_f32_16x16x32_bf16 v[58:61], v[46:49], v[58:61], v[66:69]
	v_mfma_f32_16x16x32_bf16 v[62:65], v[46:49], v[70:73], v[62:65]
	v_mfma_f32_16x16x32_bf16 v[46:49], v[46:49], v[118:121], v[50:53]
	s_nop 2
	ds_read_b128 v[50:53], v195
	ds_read_b128 v[66:69], v195 offset:2048
	ds_read_b128 v[70:73], v195 offset:4096
	ds_read_b128 v[74:77], v195 offset:6144
	ds_read_b128 v[78:81], v194 offset:16384
	ds_read_b128 v[94:97], v194 offset:18432
	ds_read_b128 v[110:113], v194 offset:20480
	ds_read_b128 v[118:121], v194 offset:22528
	ds_write_b128 v160, v[14:17] offset:32768
	ds_write_b128 v160, v[22:25] offset:36864
	ds_write_b128 v160, v[26:29] offset:40960
	ds_write_b128 v160, v[30:33] offset:45056
	ds_write_b16 v161, v18 offset:49152
	ds_write_b16_d16_hi v0, v18 offset:49280
	ds_write_b16 v162, v19 offset:49152
	ds_write_b16_d16_hi v163, v19 offset:49152
	ds_write_b16 v164, v20 offset:49152
	ds_write_b16_d16_hi v165, v20 offset:49152
	ds_write_b16 v166, v21 offset:49152
	ds_write_b16_d16_hi v167, v21 offset:49152
	ds_write_b16 v169, v10 offset:49152
	ds_write_b16_d16_hi v168, v10 offset:49280
	ds_write_b16 v170, v11 offset:49152
	ds_write_b16_d16_hi v171, v11 offset:49152
	ds_write_b16 v172, v12 offset:49152
	ds_write_b16_d16_hi v173, v12 offset:49152
	ds_write_b16 v174, v13 offset:49152
	ds_write_b16_d16_hi v175, v13 offset:49152
	ds_write_b16 v176, v2 offset:49152
	ds_write_b16_d16_hi v177, v2 offset:49280
	ds_write_b16 v178, v3 offset:49152
	ds_write_b16_d16_hi v179, v3 offset:49152
	ds_write_b16 v180, v4 offset:49152
	ds_write_b16_d16_hi v181, v4 offset:49152
	ds_write_b16 v182, v5 offset:49152
	ds_write_b16_d16_hi v183, v5 offset:49152
	ds_write_b16 v184, v6 offset:49152
	ds_write_b16_d16_hi v185, v6 offset:49280
	ds_write_b16 v188, v7 offset:49152
	ds_write_b16_d16_hi v189, v7 offset:49152
	ds_write_b16 v190, v8 offset:49152
	ds_write_b16_d16_hi v191, v8 offset:49152
	ds_write_b16 v192, v9 offset:49152
	ds_write_b16_d16_hi v193, v9 offset:49152
	s_waitcnt lgkmcnt(0)
	v_mfma_f32_16x16x32_bf16 v[126:129], v[50:53], v[78:81], v[126:129]
	s_barrier
; __device__ __forceinline__ u16 f2bf(float f) { return (u16)(pack2(f, 0.f) & 0xffffu); }
; template <int NT, bool BKN, bool MASK = false, bool ROWSS = false, class Epi> ...
;     ...
;   GEMM_COMPUTE(0);
;   GEMM_STORE(ra1, rb1, 1);
;   __syncthreads();
;   GEMM_COMPUTE(1);
; __device__ __forceinline__ void phase_mix_a(const Params& p, int l, bool last, unsigned char* smem) {
;     ...
;       auto epi = [&](f32x4(&acc)[4][4], int r0, int c0) {
; #pragma unroll
;         for (int mi = 0; mi < 4; ++mi)
; #pragma unroll
;           for (int ni = 0; ni < 4; ++ni)
; #pragma unroll
;             for (int j = 0; j < 4; ++j) {
;               const int k = mt * 128 + r0 + mi * 16 + j;
;               p.YM[(size_t)(T_LAT + b * CTX + k) * 1024 + 256 + nh * 128 + c0 + ni * 16] = f2bf(acc[mi][ni][j] * (1.f / 128.f));
;             }
;       };
	ds_read_b128 v[2:5], v197 offset:32768
	ds_read_b128 v[6:9], v197 offset:34816
	ds_read_b128 v[10:13], v197 offset:36864
	ds_read_b128 v[14:17], v197 offset:38912
	ds_read_b128 v[18:21], v196 offset:49152
	ds_read_b128 v[22:25], v196 offset:51200
	ds_read_b128 v[26:29], v196 offset:53248
	ds_read_b128 v[30:33], v196 offset:55296
	v_mfma_f32_16x16x32_bf16 v[122:125], v[50:53], v[94:97], v[122:125]
	v_lshl_add_u32 v0, v158, 6, s0
	v_mfma_f32_16x16x32_bf16 v[114:117], v[50:53], v[110:113], v[114:117]
	v_mfma_f32_16x16x32_bf16 v[34:37], v[50:53], v[118:121], v[34:37]
	v_mfma_f32_16x16x32_bf16 v[50:53], v[66:69], v[78:81], v[106:109]
	v_mfma_f32_16x16x32_bf16 v[102:105], v[66:69], v[94:97], v[102:105]
	v_mfma_f32_16x16x32_bf16 v[98:101], v[66:69], v[110:113], v[98:101]
	v_mfma_f32_16x16x32_bf16 v[38:41], v[66:69], v[118:121], v[38:41]
	v_mfma_f32_16x16x32_bf16 v[66:69], v[70:73], v[78:81], v[90:93]
	v_mfma_f32_16x16x32_bf16 v[54:57], v[74:77], v[78:81], v[54:57]
	v_mfma_f32_16x16x32_bf16 v[58:61], v[74:77], v[94:97], v[58:61]
	v_mfma_f32_16x16x32_bf16 v[62:65], v[74:77], v[110:113], v[62:65]
	v_mfma_f32_16x16x32_bf16 v[46:49], v[74:77], v[118:121], v[46:49]
	v_mfma_f32_16x16x32_bf16 v[86:89], v[70:73], v[94:97], v[86:89]
	v_mfma_f32_16x16x32_bf16 v[82:85], v[70:73], v[110:113], v[82:85]
	v_mfma_f32_16x16x32_bf16 v[42:45], v[70:73], v[118:121], v[42:45]
	s_waitcnt lgkmcnt(3)
	v_mfma_f32_16x16x32_bf16 v[66:69], v[10:13], v[18:21], v[66:69]
	v_mfma_f32_16x16x32_bf16 v[70:73], v[2:5], v[18:21], v[126:129]
	s_waitcnt lgkmcnt(2)
	v_mfma_f32_16x16x32_bf16 v[74:77], v[2:5], v[22:25], v[122:125]
	s_waitcnt lgkmcnt(1)
	v_mfma_f32_16x16x32_bf16 v[78:81], v[2:5], v[26:29], v[114:117]
	s_waitcnt lgkmcnt(0)
	v_mfma_f32_16x16x32_bf16 v[2:5], v[2:5], v[30:33], v[34:37]
	v_mfma_f32_16x16x32_bf16 v[34:37], v[6:9], v[18:21], v[50:53]
	v_mfma_f32_16x16x32_bf16 v[90:93], v[6:9], v[22:25], v[102:105]
	v_mfma_f32_16x16x32_bf16 v[94:97], v[6:9], v[26:29], v[98:101]
	v_mfma_f32_16x16x32_bf16 v[98:101], v[14:17], v[18:21], v[54:57]
	v_mfma_f32_16x16x32_bf16 v[102:105], v[14:17], v[22:25], v[58:61]
	v_mfma_f32_16x16x32_bf16 v[106:109], v[14:17], v[26:29], v[62:65]
	v_mfma_f32_16x16x32_bf16 v[110:113], v[14:17], v[30:33], v[46:49]
	ds_read_b128 v[14:17], v195 offset:32768
	ds_read_b128 v[18:21], v195 offset:34816
	ds_read_b128 v[114:117], v195 offset:36864
	ds_read_b128 v[118:121], v195 offset:38912
	ds_read_b128 v[122:125], v194 offset:49152
	ds_read_b128 v[126:129], v194 offset:51200
	ds_read_b128 v[130:133], v194 offset:53248
	ds_read_b128 v[134:137], v194 offset:55296
	v_mfma_f32_16x16x32_bf16 v[6:9], v[6:9], v[30:33], v[38:41]
	v_mfma_f32_16x16x32_bf16 v[86:89], v[10:13], v[22:25], v[86:89]
	v_mfma_f32_16x16x32_bf16 v[82:85], v[10:13], v[26:29], v[82:85]
	v_mfma_f32_16x16x32_bf16 v[10:13], v[10:13], v[30:33], v[42:45]
	s_waitcnt lgkmcnt(3)
	v_mfma_f32_16x16x32_bf16 v[30:33], v[114:117], v[122:125], v[66:69]
	s_nop 2
	v_mov_b64_e32 v[66:67], s[40:41]
	s_load_dwordx2 s[100:101], s[40:41], 0x128
	v_mfma_f32_16x16x32_bf16 v[62:65], v[14:17], v[122:125], v[70:73]
	v_lshl_or_b32 v68, v159, 2, v0
	v_ashrrev_i32_e32 v69, 31, v68
	v_mul_f32_e32 v30, 0x3c000000, v30
	v_lshlrev_b64 v[70:71], 11, v[68:69]
	v_or_b32_e32 v72, 2, v68
	s_nop 2
	v_mul_f32_e32 v0, 0x3c000000, v62
	v_cvt_pk_bf16_f32 v62, v0, s0
	v_lshlrev_b32_e32 v0, 1, v157
	v_lshl_or_b32 v0, v156, 7, v0
	s_waitcnt lgkmcnt(0)
	v_mfma_f32_16x16x32_bf16 v[50:53], v[14:17], v[134:137], v[2:5]
	v_ashrrev_i32_e32 v73, 31, v72
	v_lshlrev_b64 v[72:73], 11, v[72:73]
	v_mul_f32_e32 v64, 0x3c000000, v64
	v_cvt_pk_bf16_f32 v64, v64, s0
	v_mfma_f32_16x16x32_bf16 v[46:49], v[18:21], v[122:125], v[34:37]
	s_nop 2
	v_mul_f32_e32 v50, 0x3c000000, v50
	v_cvt_pk_bf16_f32 v50, v50, s0
	v_cvt_pk_bf16_f32 v30, v30, s0
	v_mfma_f32_16x16x32_bf16 v[54:57], v[14:17], v[130:133], v[78:81]
	v_mul_f32_e32 v32, 0x3c000000, v32
	v_mul_f32_e32 v46, 0x3c000000, v46
	v_cvt_pk_bf16_f32 v46, v46, s0
	v_mfma_f32_16x16x32_bf16 v[34:37], v[18:21], v[134:137], v[6:9]
	v_mul_f32_e32 v48, 0x3c000000, v48
	s_nop 2
	v_mul_f32_e32 v54, 0x3c000000, v54
	v_cvt_pk_bf16_f32 v54, v54, s0
	v_cvt_pk_bf16_f32 v48, v48, s0
	v_mfma_f32_16x16x32_bf16 v[38:41], v[18:21], v[130:133], v[94:97]
	v_mul_f32_e32 v34, 0x3c000000, v34
	v_cvt_pk_bf16_f32 v34, v34, s0
	v_cvt_pk_bf16_f32 v32, v32, s0
	v_mfma_f32_16x16x32_bf16 v[42:45], v[18:21], v[126:129], v[90:93]
	s_waitcnt lgkmcnt(0)
; __device__ __forceinline__ u16 f2bf(float f) { return (u16)(pack2(f, 0.f) & 0xffffu); }
; __device__ __forceinline__ void phase_mix_a(const Params& p, int l, bool last, unsigned char* smem) {
;     ...
;       auto epi = [&](f32x4(&acc)[4][4], int r0, int c0) {
; #pragma unroll
;         for (int mi = 0; mi < 4; ++mi)
; #pragma unroll
;           for (int ni = 0; ni < 4; ++ni)
; #pragma unroll
;             for (int j = 0; j < 4; ++j) {
;               const int k = mt * 128 + r0 + mi * 16 + j;
;               p.YM[(size_t)(T_LAT + b * CTX + k) * 1024 + 256 + nh * 128 + c0 + ni * 16] = f2bf(acc[mi][ni][j] * (1.f / 128.f));
;             }
;       };
	v_mov_b32_e32 v66, s100
	v_mov_b32_e32 v67, s101
	v_lshl_add_u64 v[70:71], v[66:67], 0, v[70:71]
	v_lshl_add_u64 v[70:71], v[70:71], 0, s[94:95]
	v_lshl_add_u64 v[70:71], v[70:71], 0, v[0:1]
	global_store_short v[70:71], v62, off offset:512
	v_mul_f32_e32 v62, 0x3c000000, v63
	v_cvt_pk_bf16_f32 v69, v62, s0
	v_or_b32_e32 v62, 1, v68
	v_ashrrev_i32_e32 v63, 31, v62
	v_lshlrev_b64 v[62:63], 11, v[62:63]
	v_lshl_add_u64 v[72:73], v[66:67], 0, v[72:73]
	v_lshl_add_u64 v[62:63], v[66:67], 0, v[62:63]
	v_lshl_add_u64 v[72:73], v[72:73], 0, s[94:95]
	v_lshl_add_u64 v[62:63], v[62:63], 0, s[94:95]
	v_lshl_add_u64 v[72:73], v[72:73], 0, v[0:1]
	v_lshl_add_u64 v[62:63], v[62:63], 0, v[0:1]
	global_store_short v[72:73], v64, off offset:512
	v_mul_f32_e32 v64, 0x3c000000, v65
	global_store_short v[62:63], v69, off offset:512
	v_cvt_pk_bf16_f32 v69, v64, s0
	v_or_b32_e32 v64, 3, v68
	global_store_short v[70:71], v50, off offset:608
	v_mul_f32_e32 v50, 0x3c000000, v51
	v_ashrrev_i32_e32 v65, 31, v64
	v_cvt_pk_bf16_f32 v50, v50, s0
	v_lshlrev_b64 v[64:65], 11, v[64:65]
	global_store_short v[62:63], v50, off offset:608
	v_mul_f32_e32 v50, 0x3c000000, v52
	v_lshl_add_u64 v[64:65], v[66:67], 0, v[64:65]
	v_cvt_pk_bf16_f32 v50, v50, s0
	v_lshl_add_u64 v[64:65], v[64:65], 0, s[94:95]
	global_store_short v[72:73], v50, off offset:608
	v_mul_f32_e32 v50, 0x3c000000, v53
	v_lshl_add_u64 v[64:65], v[64:65], 0, v[0:1]
	v_cvt_pk_bf16_f32 v50, v50, s0
	global_store_short v[64:65], v50, off offset:608
	v_or_b32_e32 v50, 16, v68
	v_ashrrev_i32_e32 v51, 31, v50
	v_lshlrev_b64 v[50:51], 11, v[50:51]
	v_lshl_add_u64 v[50:51], v[66:67], 0, v[50:51]
	v_lshl_add_u64 v[50:51], v[50:51], 0, s[94:95]
	v_lshl_add_u64 v[50:51], v[50:51], 0, v[0:1]
	global_store_short v[50:51], v46, off offset:512
	v_mul_f32_e32 v46, 0x3c000000, v47
	v_cvt_pk_bf16_f32 v52, v46, s0
	v_or_b32_e32 v46, 17, v68
	v_ashrrev_i32_e32 v47, 31, v46
	v_lshlrev_b64 v[46:47], 11, v[46:47]
	v_lshl_add_u64 v[46:47], v[66:67], 0, v[46:47]
	v_lshl_add_u64 v[46:47], v[46:47], 0, s[94:95]
	v_lshl_add_u64 v[46:47], v[46:47], 0, v[0:1]
	global_store_short v[46:47], v52, off offset:512
	v_or_b32_e32 v52, 18, v68
	global_store_short v[70:71], v54, off offset:576
	v_mul_f32_e32 v54, 0x3c000000, v55
	v_ashrrev_i32_e32 v53, 31, v52
	v_cvt_pk_bf16_f32 v54, v54, s0
	v_lshlrev_b64 v[52:53], 11, v[52:53]
	global_store_short v[62:63], v54, off offset:576
	v_mul_f32_e32 v54, 0x3c000000, v56
	v_lshl_add_u64 v[52:53], v[66:67], 0, v[52:53]
	v_cvt_pk_bf16_f32 v54, v54, s0
	v_lshl_add_u64 v[52:53], v[52:53], 0, s[94:95]
	global_store_short v[72:73], v54, off offset:576
	v_mul_f32_e32 v54, 0x3c000000, v57
	v_lshl_add_u64 v[52:53], v[52:53], 0, v[0:1]
	v_cvt_pk_bf16_f32 v54, v54, s0
	global_store_short v[52:53], v48, off offset:512
	v_mul_f32_e32 v48, 0x3c000000, v49
	global_store_short v[64:65], v54, off offset:576
	v_cvt_pk_bf16_f32 v54, v48, s0
	v_or_b32_e32 v48, 19, v68
	global_store_short v[50:51], v34, off offset:608
	v_mul_f32_e32 v34, 0x3c000000, v35
	v_ashrrev_i32_e32 v49, 31, v48
	v_cvt_pk_bf16_f32 v34, v34, s0
	v_lshlrev_b64 v[48:49], 11, v[48:49]
	global_store_short v[46:47], v34, off offset:608
	v_mul_f32_e32 v34, 0x3c000000, v36
	v_lshl_add_u64 v[48:49], v[66:67], 0, v[48:49]
	v_cvt_pk_bf16_f32 v34, v34, s0
	v_lshl_add_u64 v[48:49], v[48:49], 0, s[94:95]
	global_store_short v[52:53], v34, off offset:608
	v_mul_f32_e32 v34, 0x3c000000, v37
	v_lshl_add_u64 v[48:49], v[48:49], 0, v[0:1]
	v_cvt_pk_bf16_f32 v34, v34, s0
	global_store_short v[48:49], v34, off offset:608
	v_or_b32_e32 v34, 32, v68
	v_ashrrev_i32_e32 v35, 31, v34
	v_lshlrev_b64 v[34:35], 11, v[34:35]
	v_lshl_add_u64 v[34:35], v[66:67], 0, v[34:35]
	v_lshl_add_u64 v[34:35], v[34:35], 0, s[94:95]
	v_lshl_add_u64 v[34:35], v[34:35], 0, v[0:1]
	global_store_short v[34:35], v30, off offset:512
	v_mul_f32_e32 v30, 0x3c000000, v31
	v_cvt_pk_bf16_f32 v36, v30, s0
	v_or_b32_e32 v30, 33, v68
	v_ashrrev_i32_e32 v31, 31, v30
	v_lshlrev_b64 v[30:31], 11, v[30:31]
	v_lshl_add_u64 v[30:31], v[66:67], 0, v[30:31]
	v_lshl_add_u64 v[30:31], v[30:31], 0, s[94:95]
	v_mul_f32_e32 v38, 0x3c000000, v38
	v_lshl_add_u64 v[30:31], v[30:31], 0, v[0:1]
	v_cvt_pk_bf16_f32 v38, v38, s0
	global_store_short v[30:31], v36, off offset:512
	v_or_b32_e32 v36, 34, v68
	v_mfma_f32_16x16x32_bf16 v[18:21], v[114:117], v[134:137], v[10:13]
	global_store_short v[50:51], v38, off offset:576
	v_mul_f32_e32 v38, 0x3c000000, v39
	v_ashrrev_i32_e32 v37, 31, v36
	v_cvt_pk_bf16_f32 v38, v38, s0
	v_lshlrev_b64 v[36:37], 11, v[36:37]
	global_store_short v[46:47], v38, off offset:576
	v_mul_f32_e32 v38, 0x3c000000, v40
	v_lshl_add_u64 v[36:37], v[66:67], 0, v[36:37]
	v_cvt_pk_bf16_f32 v38, v38, s0
	v_lshl_add_u64 v[36:37], v[36:37], 0, s[94:95]
	global_store_short v[52:53], v38, off offset:576
	v_mul_f32_e32 v38, 0x3c000000, v41
	v_lshl_add_u64 v[36:37], v[36:37], 0, v[0:1]
	v_mul_f32_e32 v18, 0x3c000000, v18
	v_cvt_pk_bf16_f32 v38, v38, s0
	global_store_short v[36:37], v32, off offset:512
	v_mul_f32_e32 v32, 0x3c000000, v33
	v_cvt_pk_bf16_f32 v18, v18, s0
	global_store_short v[48:49], v38, off offset:576
	v_cvt_pk_bf16_f32 v38, v32, s0
	v_or_b32_e32 v32, 35, v68
	global_store_short v[34:35], v18, off offset:608
	v_mul_f32_e32 v18, 0x3c000000, v19
	v_ashrrev_i32_e32 v33, 31, v32
	v_cvt_pk_bf16_f32 v18, v18, s0
	v_lshlrev_b64 v[32:33], 11, v[32:33]
	global_store_short v[30:31], v18, off offset:608
	v_mul_f32_e32 v18, 0x3c000000, v20
	v_lshl_add_u64 v[32:33], v[66:67], 0, v[32:33]
	v_cvt_pk_bf16_f32 v18, v18, s0
	v_lshl_add_u64 v[32:33], v[32:33], 0, s[94:95]
	global_store_short v[36:37], v18, off offset:608
; __device__ __forceinline__ u16 f2bf(float f) { return (u16)(pack2(f, 0.f) & 0xffffu); }
; __device__ __forceinline__ int bid_() { int b = blockIdx.x; asm volatile("" : "+s"(b)); return b; }
; __device__ __forceinline__ void phase_mix_a(const Params& p, int l, bool last, unsigned char* smem) {
;     ...
;     for (int t = bid_(); t < 8; t += gridDim.x) {
;       const int nh = t & 1, mt = (t >> 1) & 1, b = t >> 2;
;       auto epi = [&](f32x4(&acc)[4][4], int r0, int c0) {
; #pragma unroll
;         for (int mi = 0; mi < 4; ++mi)
; #pragma unroll
;           for (int ni = 0; ni < 4; ++ni)
; #pragma unroll
;             for (int j = 0; j < 4; ++j) {
;               const int k = mt * 128 + r0 + mi * 16 + j;
;               p.YM[(size_t)(T_LAT + b * CTX + k) * 1024 + 256 + nh * 128 + c0 + ni * 16] = f2bf(acc[mi][ni][j] * (1.f / 128.f));
;             }
;       };
;       gemm_tile<4, true>(p.Mc + (size_t)mt * 128 * 512, 512, nullptr, 128, p.GDc + (size_t)b * 2 * CTX * 256 + nh * 128, 256, 512, smem, epi);
;     }
;   }
	v_mul_f32_e32 v18, 0x3c000000, v21
	v_lshl_add_u64 v[32:33], v[32:33], 0, v[0:1]
	v_cvt_pk_bf16_f32 v18, v18, s0
	v_mfma_f32_16x16x32_bf16 v[58:61], v[14:17], v[126:129], v[74:77]
	global_store_short v[32:33], v18, off offset:608
	v_or_b32_e32 v18, 48, v68
	v_ashrrev_i32_e32 v19, 31, v18
	v_mfma_f32_16x16x32_bf16 v[14:17], v[118:121], v[122:125], v[98:101]
	v_lshlrev_b64 v[18:19], 11, v[18:19]
	v_lshl_add_u64 v[18:19], v[66:67], 0, v[18:19]
	v_lshl_add_u64 v[18:19], v[18:19], 0, s[94:95]
	v_lshl_add_u64 v[18:19], v[18:19], 0, v[0:1]
	v_mfma_f32_16x16x32_bf16 v[22:25], v[114:117], v[130:133], v[82:85]
	s_nop 2
	v_mul_f32_e32 v14, 0x3c000000, v14
	v_cvt_pk_bf16_f32 v14, v14, s0
	global_store_short v[18:19], v14, off offset:512
	v_mul_f32_e32 v14, 0x3c000000, v15
	v_cvt_pk_bf16_f32 v20, v14, s0
	v_or_b32_e32 v14, 49, v68
	v_ashrrev_i32_e32 v15, 31, v14
	v_lshlrev_b64 v[14:15], 11, v[14:15]
	v_lshl_add_u64 v[14:15], v[66:67], 0, v[14:15]
	v_lshl_add_u64 v[14:15], v[14:15], 0, s[94:95]
	v_mul_f32_e32 v22, 0x3c000000, v22
	v_lshl_add_u64 v[14:15], v[14:15], 0, v[0:1]
	v_cvt_pk_bf16_f32 v22, v22, s0
	global_store_short v[14:15], v20, off offset:512
	v_or_b32_e32 v20, 50, v68
	global_store_short v[34:35], v22, off offset:576
	v_mul_f32_e32 v22, 0x3c000000, v23
	v_ashrrev_i32_e32 v21, 31, v20
	v_cvt_pk_bf16_f32 v22, v22, s0
	v_lshlrev_b64 v[20:21], 11, v[20:21]
	global_store_short v[30:31], v22, off offset:576
	v_mul_f32_e32 v22, 0x3c000000, v24
	v_lshl_add_u64 v[20:21], v[66:67], 0, v[20:21]
	v_cvt_pk_bf16_f32 v22, v22, s0
	v_mul_f32_e32 v16, 0x3c000000, v16
	v_lshl_add_u64 v[20:21], v[20:21], 0, s[94:95]
	global_store_short v[36:37], v22, off offset:576
	v_mul_f32_e32 v22, 0x3c000000, v25
	v_cvt_pk_bf16_f32 v16, v16, s0
	v_lshl_add_u64 v[20:21], v[20:21], 0, v[0:1]
	v_cvt_pk_bf16_f32 v22, v22, s0
	global_store_short v[20:21], v16, off offset:512
	v_mul_f32_e32 v16, 0x3c000000, v17
	global_store_short v[32:33], v22, off offset:576
	v_cvt_pk_bf16_f32 v22, v16, s0
	v_or_b32_e32 v16, 51, v68
	v_mfma_f32_16x16x32_bf16 v[10:13], v[118:121], v[126:129], v[102:105]
	v_ashrrev_i32_e32 v17, 31, v16
	v_lshlrev_b64 v[16:17], 11, v[16:17]
	v_lshl_add_u64 v[16:17], v[66:67], 0, v[16:17]
	v_lshl_add_u64 v[16:17], v[16:17], 0, s[94:95]
	v_lshl_add_u64 v[16:17], v[16:17], 0, v[0:1]
	s_nop 2
	v_mul_f32_e32 v0, 0x3c000000, v10
	v_cvt_pk_bf16_f32 v0, v0, s0
	global_store_short v[18:19], v0, off offset:544
	v_mul_f32_e32 v0, 0x3c000000, v11
	v_cvt_pk_bf16_f32 v0, v0, s0
	v_mfma_f32_16x16x32_bf16 v[6:9], v[118:121], v[130:133], v[106:109]
	global_store_short v[14:15], v0, off offset:544
	v_mul_f32_e32 v0, 0x3c000000, v12
	v_cvt_pk_bf16_f32 v0, v0, s0
	global_store_short v[20:21], v0, off offset:544
	v_mul_f32_e32 v0, 0x3c000000, v13
	v_cvt_pk_bf16_f32 v0, v0, s0
	global_store_short v[16:17], v0, off offset:544
	s_nop 0
	v_mul_f32_e32 v0, 0x3c000000, v6
	v_cvt_pk_bf16_f32 v0, v0, s0
	global_store_short v[18:19], v0, off offset:576
	v_mul_f32_e32 v0, 0x3c000000, v7
	v_cvt_pk_bf16_f32 v0, v0, s0
	v_mfma_f32_16x16x32_bf16 v[26:29], v[114:117], v[126:129], v[86:89]
	global_store_short v[14:15], v0, off offset:576
	v_mul_f32_e32 v0, 0x3c000000, v8
	v_cvt_pk_bf16_f32 v0, v0, s0
	v_mfma_f32_16x16x32_bf16 v[2:5], v[118:121], v[134:137], v[110:113]
	global_store_short v[20:21], v0, off offset:576
	v_mul_f32_e32 v0, 0x3c000000, v9
	v_cvt_pk_bf16_f32 v0, v0, s0
	v_mul_f32_e32 v58, 0x3c000000, v58
	v_mul_f32_e32 v42, 0x3c000000, v42
	v_mul_f32_e32 v26, 0x3c000000, v26
	global_store_short v[16:17], v0, off offset:576
	s_nop 0
	v_mul_f32_e32 v0, 0x3c000000, v2
	v_cvt_pk_bf16_f32 v58, v58, s0
	v_cvt_pk_bf16_f32 v42, v42, s0
	v_cvt_pk_bf16_f32 v26, v26, s0
	v_cvt_pk_bf16_f32 v0, v0, s0
	global_store_short v[70:71], v58, off offset:544
	v_mul_f32_e32 v58, 0x3c000000, v59
	global_store_short v[50:51], v42, off offset:544
	v_mul_f32_e32 v42, 0x3c000000, v43
	global_store_short v[34:35], v26, off offset:544
	v_mul_f32_e32 v26, 0x3c000000, v27
	global_store_short v[18:19], v0, off offset:608
	v_mul_f32_e32 v0, 0x3c000000, v3
	v_cvt_pk_bf16_f32 v58, v58, s0
	v_cvt_pk_bf16_f32 v42, v42, s0
	v_cvt_pk_bf16_f32 v26, v26, s0
	v_cvt_pk_bf16_f32 v0, v0, s0
	global_store_short v[62:63], v58, off offset:544
	v_mul_f32_e32 v58, 0x3c000000, v60
	global_store_short v[46:47], v42, off offset:544
	v_mul_f32_e32 v42, 0x3c000000, v44
	global_store_short v[30:31], v26, off offset:544
	v_mul_f32_e32 v26, 0x3c000000, v28
	global_store_short v[14:15], v0, off offset:608
	v_mul_f32_e32 v0, 0x3c000000, v4
	v_cvt_pk_bf16_f32 v58, v58, s0
	v_cvt_pk_bf16_f32 v42, v42, s0
	v_cvt_pk_bf16_f32 v26, v26, s0
	v_cvt_pk_bf16_f32 v0, v0, s0
	global_store_short v[72:73], v58, off offset:544
	v_mul_f32_e32 v58, 0x3c000000, v61
	global_store_short v[52:53], v42, off offset:544
	v_mul_f32_e32 v42, 0x3c000000, v45
	global_store_short v[36:37], v26, off offset:544
	v_mul_f32_e32 v26, 0x3c000000, v29
	global_store_short v[20:21], v0, off offset:608
	v_mul_f32_e32 v0, 0x3c000000, v5
	v_cvt_pk_bf16_f32 v58, v58, s0
	v_cvt_pk_bf16_f32 v42, v42, s0
	v_cvt_pk_bf16_f32 v26, v26, s0
	v_cvt_pk_bf16_f32 v0, v0, s0
	v_readlane_b32 s0, v254, 0
	s_add_i32 s8, s8, s0
	v_readlane_b32 s0, v254, 46
	s_add_i32 s9, s9, s0
	s_cmp_lt_i32 s8, 8
	global_store_short v[64:65], v69, off offset:512
	global_store_short v[64:65], v58, off offset:544
	global_store_short v[48:49], v54, off offset:512
	global_store_short v[48:49], v42, off offset:544
	global_store_short v[32:33], v38, off offset:512
	global_store_short v[32:33], v26, off offset:544
	global_store_short v[16:17], v22, off offset:512
	global_store_short v[16:17], v0, off offset:608
	v_readlane_b32 s1, v254, 1
	s_cbranch_scc1 .LBB0_627
	v_mov_b32_e32 v224, 0x358637bd
	v_mov_b32_e32 v225, 0x11800
	v_mov_b32_e32 v226, 0x11804
	v_mov_b32_e32 v227, v229
	v_xor_b32_e32 v249, 32, v186
	v_xor_b32_e32 v250, 16, v186
	v_xor_b32_e32 v251, 8, v186
	v_xor_b32_e32 v252, 4, v186
	v_xor_b32_e32 v253, 2, v186
	v_xor_b32_e32 v212, 1, v186

; __device__ __forceinline__ int tid_() { int t = threadIdx.x; asm volatile("" : "+v"(t)); return t; }
; #define XCD_FOR(u, T)                                                                                         \
;   for (int _x = bid_() & 7, _gb = gridDim.x >> 3, _hi = (int)(((long)(_x + 1) * (T)) >> 3),                    \
;            u = (int)(((long)_x * (T)) >> 3) + (bid_() >> 3);                                                  \
;        u < _hi; u += _gb)
; template <int NT, bool BKN, bool MASK = false, bool ROWSS = false, class Epi> ...
;     ...
;   const int t = tid_(), lane = t & 63, wid = t >> 6, wr = wid >> 1, wc = wid & 1, l16 = lane & 15, quad = lane >> 4;
;   const u16* ap[4];
;   const u16* bp[NT];
;   unsigned amask = 0u;
; #pragma unroll
;   for (int i = 0; i < 4; ++i) {
;     const int row = (t >> 3) + 32 * i;
;     const bool v = MASK ? (row < mvalid) : true;
;     amask |= v ? (1u << i) : 0u;
;     int r = v ? row : 0;
;     if (arows) r = arows[r];
;     ap[i] = A + (size_t)r * lda + (t & 7) * 8;
;   }
; #pragma unroll
;   for (int i = 0; i < NT; ++i) {
;     if (!BKN) bp[i] = B + (size_t)((t >> 3) + 32 * i) * ldb + (t & 7) * 8;
;     else { const int c = t + 256 * i; bp[i] = B + (size_t)(c / CPR) * ldb + (c % CPR) * 8; }
;   }
;   const size_t bstep = BKN ? (size_t)64 * ldb : (size_t)64;
; __device__ __forceinline__ void phase_mix_b(const Params& p, int l, bool last, unsigned char* smem) {
;   XCD_FOR(t, 512) {
;     const int nq = t & 3, k2 = (t >> 2) & 63, b = t >> 8;
;     auto epi = [&](f32x4(&acc)[4][2], int r0, int c0) {
;       auto vf = [&](int, int, float v) { return v * 0.001381067932004976f; };
;       auto rp = [&](int k1) -> u16* { return p.YM + (size_t)(b * SEQ + 64 * k1 + k2) * 1024 + 256 + nq * 64; };
;       epi_staged_bf16<2>(acc, r0, c0, smem, vf, rp);
;     };
;     gemm_tile<2, true>(p.M2, 256, nullptr, 128, p.PF + (size_t)(b * 64 + k2) * 2 * 128 * 256 + nq * 64, 256, 256, smem, epi);
;   }
.LBB0_685:
	v_mov_b64_e32 v[18:19], s[4:5]
	s_load_dwordx2 s[100:101], s[4:5], 0x100
	s_waitcnt lgkmcnt(0)
	v_mov_b32_e32 v10, s100
	v_mov_b32_e32 v11, s101
	s_load_dwordx2 s[100:101], s[4:5], 0x140
	s_waitcnt lgkmcnt(0)
	v_mov_b32_e32 v12, s100
	v_mov_b32_e32 v13, s101
	v_mov_b32_e32 v4, v187
	s_ashr_i32 s38, s9, 8
	s_nop 0
	v_ashrrev_i32_e32 v2, 3, v4
	v_ashrrev_i32_e32 v7, 31, v4
	v_add_u32_e32 v8, 0x100, v4
	v_lshrrev_b32_e32 v5, 4, v4
	v_and_b32_e32 v29, 15, v4
	v_bfe_u32 v30, v4, 4, 2
	v_bfe_u32 v9, v4, 1, 3
	v_ashrrev_i32_e32 v3, 31, v2
	v_lshrrev_b32_e32 v7, 29, v7
	v_ashrrev_i32_e32 v16, 31, v8
	v_bfe_u32 v28, v4, 6, 1
	v_lshlrev_b32_e32 v6, 4, v4
	v_ashrrev_i32_e32 v31, 7, v4
	v_xor_b32_e32 v17, v5, v4
	v_bitop3_b32 v5, v5, v9, 3 bitop3:0x6c
	v_lshlrev_b32_e32 v20, 7, v29
	v_bitop3_b32 v9, v30, v9, 4 bitop3:0x36
	v_lshlrev_b64 v[14:15], 9, v[2:3]
	v_add_u32_e32 v3, v4, v7
	v_lshrrev_b32_e32 v7, 29, v16
	v_and_b32_e32 v0, 0x70, v6
	v_and_b32_e32 v6, 0xffffff80, v6
	v_lshlrev_b32_e32 v16, 4, v17
	v_lshl_or_b32 v17, v31, 13, v20
	v_lshl_or_b32 v20, v28, 12, v20
	v_lshlrev_b32_e32 v9, 4, v9
	v_ashrrev_i32_e32 v2, 3, v3
	v_and_b32_e32 v21, -8, v3
	v_add_u32_e32 v7, v8, v7
	v_lshlrev_b32_e32 v5, 4, v5
	v_and_or_b32 v36, v16, s14, v6
	v_or_b32_e32 v32, v9, v17
	v_or_b32_e32 v33, v9, v20
	v_ashrrev_i32_e32 v3, 31, v2
	v_sub_u32_e32 v9, v4, v21
	v_ashrrev_i32_e32 v4, 3, v7
	v_and_b32_e32 v16, -8, v7
	v_or_b32_e32 v34, v5, v17
	v_or_b32_e32 v35, v5, v20
	v_and_b32_e32 v17, -8, v2
	v_and_b32_e32 v20, 7, v2
	v_lshlrev_b64 v[6:7], 9, v[2:3]
	v_lshlrev_b32_e32 v2, 3, v9
	v_ashrrev_i32_e32 v5, 31, v4
	v_sub_u32_e32 v16, v8, v16
	v_lshlrev_b32_e32 v21, 9, v9
	v_lshlrev_b32_e32 v22, 5, v9
	v_and_b32_e32 v23, -8, v4
	v_and_b32_e32 v24, 7, v4
	v_lshlrev_b64 v[8:9], 9, v[4:5]
	v_lshlrev_b32_e32 v4, 3, v16
	v_bitop3_b32 v22, v22, v17, 32 bitop3:0x6c
	v_or_b32_e32 v25, v20, v21
	v_or_b32_e32 v26, 2, v2
	v_or_b32_e32 v27, 3, v2
	v_or_b32_e32 v38, 4, v2
	v_or_b32_e32 v39, 5, v2
	v_or_b32_e32 v40, 6, v2
	v_or_b32_e32 v41, 7, v2
	v_lshlrev_b32_e32 v42, 9, v16
	v_lshlrev_b32_e32 v16, 5, v16
	v_add_u32_e32 v21, v22, v21
	v_add_lshl_u32 v37, v25, v22, 1
	v_lshlrev_b32_e32 v22, 6, v26
	v_lshlrev_b32_e32 v25, 2, v26
	v_lshlrev_b32_e32 v26, 6, v27
	v_lshlrev_b32_e32 v27, 2, v27
	v_lshlrev_b32_e32 v43, 6, v38
	v_lshlrev_b32_e32 v38, 2, v38
	v_lshlrev_b32_e32 v44, 6, v39
	v_lshlrev_b32_e32 v39, 2, v39
	v_lshlrev_b32_e32 v45, 6, v40
	v_lshlrev_b32_e32 v40, 2, v40
	v_lshlrev_b32_e32 v46, 6, v41
	v_lshlrev_b32_e32 v41, 2, v41
	v_bitop3_b32 v16, v16, v23, 32 bitop3:0x6c
	v_or_b32_e32 v47, v24, v42
	v_or_b32_e32 v48, 2, v4
	v_or_b32_e32 v49, 3, v4
	s_bfe_u32 s19, s9, 0x60002
	s_and_b32 s0, s18, 0xc0
	s_lshl_b32 s1, s38, 6
	v_or_b32_e32 v50, 4, v4
	v_or_b32_e32 v51, 5, v4
	v_or_b32_e32 v52, 6, v4
	v_or_b32_e32 v53, 7, v4
	v_or_b32_e32 v21, v21, v20
	v_and_b32_e32 v25, 40, v25
	v_and_b32_e32 v27, 40, v27
	v_and_b32_e32 v54, 48, v38
	v_and_b32_e32 v55, 48, v39
	v_and_b32_e32 v40, 56, v40
	v_and_b32_e32 v41, 56, v41
	v_add_u32_e32 v42, v16, v42
	v_add_lshl_u32 v38, v47, v16, 1
	v_lshlrev_b32_e32 v16, 6, v48
	v_lshlrev_b32_e32 v47, 2, v48
	v_lshlrev_b32_e32 v48, 6, v49
	v_lshlrev_b32_e32 v49, 2, v49
	s_lshl_b32 s94, s0, 1
	s_or_b32 s0, s1, s19
	v_lshlrev_b32_e32 v56, 6, v50
	v_lshlrev_b32_e32 v50, 2, v50
	v_lshlrev_b32_e32 v57, 6, v51
	v_lshlrev_b32_e32 v51, 2, v51
	v_lshlrev_b32_e32 v58, 6, v52
	v_lshlrev_b32_e32 v52, 2, v52
	v_lshlrev_b32_e32 v59, 6, v53
	v_lshlrev_b32_e32 v53, 2, v53
	v_lshlrev_b32_e32 v39, 1, v21
	v_xad_u32 v21, v25, v17, v22
	v_xad_u32 v22, v27, v17, v26
	v_xad_u32 v25, v54, v17, v43
	v_xad_u32 v26, v55, v17, v44
	v_xad_u32 v27, v40, v17, v45
	v_xad_u32 v17, v41, v17, v46
	v_or_b32_e32 v40, v42, v24
	v_and_b32_e32 v41, 40, v47
	v_and_b32_e32 v42, 40, v49
	s_ashr_i32 s1, s0, 31
	v_and_b32_e32 v43, 48, v50
	v_and_b32_e32 v44, 48, v51
	v_and_b32_e32 v45, 56, v52
	v_and_b32_e32 v46, 56, v53
	v_or_b32_e32 v21, v21, v20
	v_or_b32_e32 v22, v22, v20
	v_or_b32_e32 v25, v25, v20
	v_or_b32_e32 v26, v26, v20
	v_or_b32_e32 v27, v27, v20
	v_or_b32_e32 v17, v17, v20
	v_xad_u32 v16, v41, v23, v16
	v_xad_u32 v20, v42, v23, v48
	s_lshl_b64 s[0:1], s[0:1], 17
	v_xad_u32 v47, v43, v23, v56
	v_xad_u32 v48, v44, v23, v57
	v_xad_u32 v49, v45, v23, v58
	v_xad_u32 v23, v46, v23, v59
	v_lshlrev_b32_e32 v46, 1, v17
	v_or_b32_e32 v16, v16, v24
	v_or_b32_e32 v17, v20, v24
	v_lshlrev_b32_e32 v41, 1, v21
	v_or_b32_e32 v20, v47, v24
	v_or_b32_e32 v21, v48, v24
	v_lshlrev_b32_e32 v47, 1, v16
	v_lshlrev_b32_e32 v48, 1, v17
	s_waitcnt lgkmcnt(0)
	v_lshl_add_u64 v[12:13], v[12:13], 0, s[0:1]
	v_lshl_add_u64 v[16:17], v[10:11], 0, v[0:1]
	v_lshlrev_b32_e32 v42, 1, v22
	v_lshlrev_b32_e32 v43, 1, v25
	v_or_b32_e32 v22, v49, v24
	v_or_b32_e32 v23, v23, v24
	v_lshl_add_u64 v[10:11], v[12:13], 0, s[94:95]
	v_lshl_add_u64 v[24:25], v[16:17], 0, v[14:15]
	v_lshl_add_u64 v[6:7], v[10:11], 0, v[6:7]
	v_lshl_add_u64 v[8:9], v[10:11], 0, v[8:9]
	v_add_co_u32_e32 v10, vcc, s69, v24
	s_mov_b64 s[0:1], 0xc000
	s_nop 0
	v_addc_co_u32_e32 v11, vcc, 0, v25, vcc
	v_add_co_u32_e32 v12, vcc, s34, v24
	v_lshlrev_b32_e32 v44, 1, v26
	v_lshlrev_b32_e32 v45, 1, v27
	v_lshl_add_u64 v[26:27], v[24:25], 0, s[0:1]
	v_addc_co_u32_e32 v13, vcc, 0, v25, vcc
	s_mov_b32 s0, 0xc000
	v_add_co_u32_e32 v14, vcc, s0, v24
	v_ashrrev_i32_e32 v3, 31, v2
	v_ashrrev_i32_e32 v5, 31, v4
	v_addc_co_u32_e32 v15, vcc, 0, v25, vcc
	s_barrier
; template <int NT, bool BKN, bool MASK = false, bool ROWSS = false, class Epi> ...
;     ...
;   __syncthreads();
;   GEMM_LOAD(ra0, rb0, 0);
;   GEMM_LOAD(ra1, rb1, 1);
;   GEMM_STORE(ra0, rb0, 0);
;   GEMM_LOAD(ra0, rb0, (2 < nkm1 ? 2 : nkm1));
;   __syncthreads();
	v_lshlrev_b32_e32 v49, 1, v20
	v_lshlrev_b32_e32 v50, 1, v21
	v_lshlrev_b32_e32 v51, 1, v22
	v_lshlrev_b32_e32 v52, 1, v23
	v_lshl_add_u64 v[20:21], v[24:25], 0, s[62:63]
	v_lshl_add_u64 v[22:23], v[24:25], 0, s[10:11]
	global_load_dwordx4 v[54:57], v[24:25], off
	global_load_dwordx4 v[58:61], v[24:25], off offset:128
	v_lshl_add_u64 v[110:111], v[2:3], 1, v[6:7]
	v_lshl_add_u64 v[112:113], v[4:5], 1, v[8:9]
	global_load_dwordx4 v[62:65], v[10:11], off
	global_load_dwordx4 v[66:69], v[12:13], off
	global_load_dwordx4 v[70:73], v[14:15], off
	global_load_dwordx4 v[74:77], v[20:21], off offset:128
	global_load_dwordx4 v[2:5], v[24:25], off offset:256
	global_load_dwordx4 v[78:81], v[22:23], off offset:128
	global_load_dwordx4 v[6:9], v[20:21], off offset:256
	global_load_dwordx4 v[82:85], v[26:27], off offset:128
	global_load_dwordx4 v[10:13], v[22:23], off offset:256
	global_load_dwordx4 v[14:17], v[26:27], off offset:256
	global_load_dwordx4 v[86:89], v[110:111], off
	global_load_dwordx4 v[90:93], v[112:113], off
	v_add_co_u32_e32 v94, vcc, s34, v110
	v_lshlrev_b32_e32 v40, 1, v40
	s_nop 0
	v_addc_co_u32_e32 v95, vcc, 0, v111, vcc
	v_add_co_u32_e32 v98, vcc, s34, v112
	v_lshlrev_b32_e32 v0, 6, v31
	s_nop 0
	v_addc_co_u32_e32 v99, vcc, 0, v113, vcc
	v_add_co_u32_e32 v102, vcc, s15, v110
	v_lshlrev_b32_e32 v29, 1, v29
	s_nop 0
	v_addc_co_u32_e32 v103, vcc, 0, v111, vcc
	v_add_co_u32_e32 v106, vcc, s15, v112
	s_add_i32 s9, s9, s3
	s_nop 0
	v_addc_co_u32_e32 v107, vcc, 0, v113, vcc
	global_load_dwordx4 v[94:97], v[94:95], off
	s_nop 0
	global_load_dwordx4 v[98:101], v[98:99], off
	s_nop 0
	global_load_dwordx4 v[102:105], v[102:103], off
	s_nop 0
	global_load_dwordx4 v[106:109], v[106:107], off
	s_waitcnt vmcnt(0) lgkmcnt(0)
	ds_write_b128 v36, v[54:57]
	ds_write_b128 v36, v[62:65] offset:4096
	ds_write_b128 v36, v[66:69] offset:8192
	ds_write_b128 v36, v[70:73] offset:12288
	ds_write_b16 v39, v86 offset:16384
	ds_write_b16_d16_hi v37, v86 offset:16512
	ds_write_b16 v41, v87 offset:16384
	ds_write_b16_d16_hi v42, v87 offset:16384
	ds_write_b16 v43, v88 offset:16384
	ds_write_b16_d16_hi v44, v88 offset:16384
	ds_write_b16 v45, v89 offset:16384
	ds_write_b16_d16_hi v46, v89 offset:16384
	ds_write_b16 v40, v90 offset:16384
	ds_write_b16_d16_hi v38, v90 offset:16512
	ds_write_b16 v47, v91 offset:16384
	ds_write_b16_d16_hi v48, v91 offset:16384
	ds_write_b16 v49, v92 offset:16384
	ds_write_b16_d16_hi v50, v92 offset:16384
	ds_write_b16 v51, v93 offset:16384
	ds_write_b16_d16_hi v52, v93 offset:16384
	s_waitcnt lgkmcnt(0)
	s_barrier
	ds_read_b128 v[54:57], v34
	ds_read_b128 v[62:65], v35 offset:16384
	ds_read_b128 v[66:69], v34 offset:2048
	ds_read_b128 v[70:73], v35 offset:18432
	ds_read_b128 v[90:93], v34 offset:4096
	v_add_co_u32_e32 v146, vcc, s55, v110
	ds_read_b128 v[114:117], v34 offset:6144
	ds_read_b128 v[118:121], v32
	ds_read_b128 v[122:125], v32 offset:2048
	v_addc_co_u32_e32 v147, vcc, 0, v111, vcc
	v_add_co_u32_e32 v148, vcc, s55, v112
	ds_read_b128 v[126:129], v32 offset:4096
	ds_read_b128 v[130:133], v32 offset:6144
	ds_read_b128 v[134:137], v33 offset:16384
	ds_read_b128 v[142:145], v33 offset:18432
	ds_write_b128 v36, v[58:61] offset:32768
	ds_write_b128 v36, v[74:77] offset:36864
	ds_write_b128 v36, v[78:81] offset:40960
	ds_write_b128 v36, v[82:85] offset:45056
	v_addc_co_u32_e32 v149, vcc, 0, v113, vcc
	s_waitcnt lgkmcnt(11)
	v_mfma_f32_16x16x32_bf16 v[138:141], v[90:93], v[62:65], 0
	global_load_dwordx4 v[74:77], v[24:25], off offset:384
	global_load_dwordx4 v[78:81], v[20:21], off offset:384
	s_nop 0
	global_load_dwordx4 v[20:23], v[22:23], off offset:384
	s_nop 0
	global_load_dwordx4 v[24:27], v[26:27], off offset:384
	s_add_i32 s18, s18, s54
	v_mfma_f32_16x16x32_bf16 v[58:61], v[90:93], v[70:73], 0
	global_load_dwordx4 v[82:85], v[146:147], off
	global_load_dwordx4 v[90:93], v[148:149], off
	ds_write_b16 v39, v94 offset:49152
	ds_write_b16_d16_hi v37, v94 offset:49280
	ds_write_b16 v41, v95 offset:49152
	ds_write_b16_d16_hi v42, v95 offset:49152
	v_mfma_f32_16x16x32_bf16 v[86:89], v[54:57], v[62:65], 0
	ds_write_b16 v43, v96 offset:49152
	ds_write_b16_d16_hi v44, v96 offset:49152
	ds_write_b16 v45, v97 offset:49152
	ds_write_b16_d16_hi v46, v97 offset:49152
	ds_write_b16 v40, v98 offset:49152
	ds_write_b16_d16_hi v38, v98 offset:49280
	ds_write_b16 v47, v99 offset:49152
	ds_write_b16_d16_hi v48, v99 offset:49152
	ds_write_b16 v49, v100 offset:49152
	v_mfma_f32_16x16x32_bf16 v[54:57], v[54:57], v[70:73], 0
	ds_write_b16_d16_hi v50, v100 offset:49152
	ds_write_b16 v51, v101 offset:49152
	ds_write_b16_d16_hi v52, v101 offset:49152
	s_waitcnt lgkmcnt(0)
	s_barrier
; template <int NT, bool BKN, bool MASK = false, bool ROWSS = false, class Epi> ...
;     ...
;   for (int kt = 0; kt < nk - 2; kt += 2) {
;     GEMM_COMPUTE(0);
;     GEMM_STORE(ra1, rb1, 1);
;     GEMM_LOAD(ra1, rb1, kt + 3);
;     __syncthreads();
;     GEMM_COMPUTE(1);
;     GEMM_STORE(ra0, rb0, 0);
;     GEMM_LOAD(ra0, rb0, (kt + 4 < nkm1 ? kt + 4 : nkm1));
;     __syncthreads();
;   }
	v_mfma_f32_16x16x32_bf16 v[110:113], v[66:69], v[62:65], 0
	ds_read_b128 v[98:101], v34 offset:32768
	v_mfma_f32_16x16x32_bf16 v[66:69], v[66:69], v[70:73], 0
	v_mfma_f32_16x16x32_bf16 v[62:65], v[114:117], v[62:65], 0
	v_mfma_f32_16x16x32_bf16 v[70:73], v[114:117], v[70:73], 0
	v_mfma_f32_16x16x32_bf16 v[86:89], v[118:121], v[134:137], v[86:89]
	v_mfma_f32_16x16x32_bf16 v[54:57], v[118:121], v[142:145], v[54:57]
	v_mfma_f32_16x16x32_bf16 v[110:113], v[122:125], v[134:137], v[110:113]
	v_mfma_f32_16x16x32_bf16 v[66:69], v[122:125], v[142:145], v[66:69]
	ds_read_b128 v[114:117], v35 offset:49152
	ds_read_b128 v[118:121], v34 offset:34816
	ds_read_b128 v[122:125], v35 offset:51200
	s_waitcnt lgkmcnt(0)
	v_mfma_f32_16x16x32_bf16 v[86:89], v[98:101], v[114:117], v[86:89]
	v_mfma_f32_16x16x32_bf16 v[54:57], v[98:101], v[122:125], v[54:57]
	v_mfma_f32_16x16x32_bf16 v[98:101], v[118:121], v[114:117], v[110:113]
	v_mfma_f32_16x16x32_bf16 v[66:69], v[118:121], v[122:125], v[66:69]
	s_nop 1
	ds_read_b128 v[110:113], v34 offset:36864
	ds_read_b128 v[118:121], v34 offset:38912
	v_mfma_f32_16x16x32_bf16 v[94:97], v[126:129], v[134:137], v[138:141]
	v_mfma_f32_16x16x32_bf16 v[58:61], v[126:129], v[142:145], v[58:61]
	v_mfma_f32_16x16x32_bf16 v[62:65], v[130:133], v[134:137], v[62:65]
	v_mfma_f32_16x16x32_bf16 v[70:73], v[130:133], v[142:145], v[70:73]
	ds_read_b128 v[126:129], v32 offset:32768
	ds_read_b128 v[130:133], v32 offset:34816
	s_waitcnt lgkmcnt(0)
	v_mfma_f32_16x16x32_bf16 v[94:97], v[110:113], v[114:117], v[94:97]
	v_mfma_f32_16x16x32_bf16 v[58:61], v[110:113], v[122:125], v[58:61]
	ds_read_b128 v[110:113], v32 offset:36864
	ds_read_b128 v[134:137], v32 offset:38912
	ds_read_b128 v[138:141], v33 offset:49152
	v_mfma_f32_16x16x32_bf16 v[62:65], v[118:121], v[114:117], v[62:65]
	ds_read_b128 v[114:117], v33 offset:51200
	ds_write_b128 v36, v[2:5]
	ds_write_b128 v36, v[6:9] offset:4096
	ds_write_b128 v36, v[10:13] offset:8192
	ds_write_b128 v36, v[14:17] offset:12288
	ds_write_b16 v39, v102 offset:16384
	v_mfma_f32_16x16x32_bf16 v[2:5], v[118:121], v[122:125], v[70:73]
	ds_write_b16_d16_hi v37, v102 offset:16512
	ds_write_b16 v41, v103 offset:16384
	ds_write_b16_d16_hi v42, v103 offset:16384
	ds_write_b16 v43, v104 offset:16384
	ds_write_b16_d16_hi v44, v104 offset:16384
	ds_write_b16 v45, v105 offset:16384
	ds_write_b16_d16_hi v46, v105 offset:16384
	ds_write_b16 v40, v106 offset:16384
	ds_write_b16_d16_hi v38, v106 offset:16512
	ds_write_b16 v47, v107 offset:16384
	ds_write_b16_d16_hi v48, v107 offset:16384
	ds_write_b16 v49, v108 offset:16384
	ds_write_b16_d16_hi v50, v108 offset:16384
	ds_write_b16 v51, v109 offset:16384
	ds_write_b16_d16_hi v52, v109 offset:16384
	s_waitcnt lgkmcnt(0)
	s_barrier
	ds_read_b128 v[70:73], v34
	v_mfma_f32_16x16x32_bf16 v[6:9], v[126:129], v[138:141], v[86:89]
	v_mfma_f32_16x16x32_bf16 v[10:13], v[126:129], v[114:117], v[54:57]
	v_mfma_f32_16x16x32_bf16 v[14:17], v[130:133], v[138:141], v[98:101]
	v_mfma_f32_16x16x32_bf16 v[54:57], v[130:133], v[114:117], v[66:69]
	v_mfma_f32_16x16x32_bf16 v[66:69], v[110:113], v[138:141], v[94:97]
	ds_read_b128 v[86:89], v35 offset:16384
	s_nop 1
	ds_read_b128 v[94:97], v34 offset:2048
	ds_read_b128 v[98:101], v35 offset:18432
	v_mfma_f32_16x16x32_bf16 v[58:61], v[110:113], v[114:117], v[58:61]
	s_waitcnt lgkmcnt(0)
	v_mfma_f32_16x16x32_bf16 v[6:9], v[70:73], v[86:89], v[6:9]
	v_mfma_f32_16x16x32_bf16 v[10:13], v[70:73], v[98:101], v[10:13]
	v_mfma_f32_16x16x32_bf16 v[14:17], v[94:97], v[86:89], v[14:17]
	v_mfma_f32_16x16x32_bf16 v[54:57], v[94:97], v[98:101], v[54:57]
	ds_read_b128 v[70:73], v34 offset:4096
	ds_read_b128 v[94:97], v34 offset:6144
	v_mfma_f32_16x16x32_bf16 v[62:65], v[134:137], v[138:141], v[62:65]
	v_mfma_f32_16x16x32_bf16 v[2:5], v[134:137], v[114:117], v[2:5]
	s_waitcnt lgkmcnt(0)
	v_mfma_f32_16x16x32_bf16 v[66:69], v[70:73], v[86:89], v[66:69]
	v_mfma_f32_16x16x32_bf16 v[58:61], v[70:73], v[98:101], v[58:61]
	ds_read_b128 v[70:73], v32
	v_mfma_f32_16x16x32_bf16 v[62:65], v[94:97], v[86:89], v[62:65]
	v_mfma_f32_16x16x32_bf16 v[2:5], v[94:97], v[98:101], v[2:5]
	ds_read_b128 v[86:89], v33 offset:16384
	ds_read_b128 v[94:97], v32 offset:2048
	ds_read_b128 v[98:101], v33 offset:18432
	s_waitcnt lgkmcnt(0)
	v_mfma_f32_16x16x32_bf16 v[6:9], v[70:73], v[86:89], v[6:9]
	v_mfma_f32_16x16x32_bf16 v[10:13], v[70:73], v[98:101], v[10:13]
	v_mfma_f32_16x16x32_bf16 v[14:17], v[94:97], v[86:89], v[14:17]
	v_mfma_f32_16x16x32_bf16 v[54:57], v[94:97], v[98:101], v[54:57]
	ds_read_b128 v[70:73], v32 offset:4096
	ds_read_b128 v[94:97], v32 offset:6144
	s_waitcnt vmcnt(0)
	ds_write_b128 v36, v[74:77] offset:32768
	ds_write_b128 v36, v[78:81] offset:36864
	ds_write_b128 v36, v[20:23] offset:40960
	ds_write_b128 v36, v[24:27] offset:45056
	ds_write_b16 v39, v82 offset:49152
	ds_write_b16_d16_hi v37, v82 offset:49280
	ds_write_b16 v41, v83 offset:49152
	ds_write_b16_d16_hi v42, v83 offset:49152
	ds_write_b16 v43, v84 offset:49152
	ds_write_b16_d16_hi v44, v84 offset:49152
	ds_write_b16 v45, v85 offset:49152
	ds_write_b16_d16_hi v46, v85 offset:49152
	ds_write_b16 v40, v90 offset:49152
	ds_write_b16_d16_hi v38, v90 offset:49280
	ds_write_b16 v47, v91 offset:49152
	ds_write_b16_d16_hi v48, v91 offset:49152
	ds_write_b16 v49, v92 offset:49152
	ds_write_b16_d16_hi v50, v92 offset:49152
	ds_write_b16 v51, v93 offset:49152
	ds_write_b16_d16_hi v52, v93 offset:49152
	s_waitcnt lgkmcnt(0)
	s_barrier
; __device__ __forceinline__ u16 f2bf(float f) { return (u16)(pack2(f, 0.f) & 0xffffu); }
; __device__ __forceinline__ int tid_() { int t = threadIdx.x; asm volatile("" : "+v"(t)); return t; }
; template <int NT, bool BKN, bool MASK = false, bool ROWSS = false, class Epi> ...
;     ...
;   GEMM_COMPUTE(0);
;   GEMM_STORE(ra1, rb1, 1);
;   __syncthreads();
;   GEMM_COMPUTE(1);
; template <int NT, class VF, class RP>
; __device__ __forceinline__ void epi_staged_bf16(f32x4 (&acc)[4][NT], int r0, int c0, unsigned char* smem, VF vf, RP rowptr) {
;   constexpr int BN = NT * 32, PITCH = BN + 8, CPR = BN / 8;
;   u16* Ts = (u16*)smem;
;   const int t = tid_();
;   __syncthreads();
; #pragma unroll
;   for (int mi = 0; mi < 4; ++mi)
; #pragma unroll
;     for (int ni = 0; ni < NT; ++ni)
; #pragma unroll
;       for (int j = 0; j < 4; ++j) {
;         const int r = r0 + mi * 16 + j, c = c0 + ni * 16;
;         Ts[r * PITCH + c] = f2bf(vf(r, c, acc[mi][ni][j]));
	ds_read_b128 v[20:23], v34 offset:32768
	ds_read_b128 v[24:27], v35 offset:49152
	ds_read_b128 v[36:39], v34 offset:34816
	ds_read_b128 v[40:43], v35 offset:51200
	s_waitcnt lgkmcnt(2)
	v_mfma_f32_16x16x32_bf16 v[6:9], v[20:23], v[24:27], v[6:9]
	s_waitcnt lgkmcnt(0)
	v_mfma_f32_16x16x32_bf16 v[10:13], v[20:23], v[40:43], v[10:13]
	v_mfma_f32_16x16x32_bf16 v[14:17], v[36:39], v[24:27], v[14:17]
	v_mfma_f32_16x16x32_bf16 v[20:23], v[36:39], v[40:43], v[54:57]
	ds_read_b128 v[36:39], v34 offset:36864
	ds_read_b128 v[44:47], v34 offset:38912
	s_nop 0
	ds_read_b128 v[52:55], v32 offset:32768
	v_mfma_f32_16x16x32_bf16 v[66:69], v[70:73], v[86:89], v[66:69]
	v_mfma_f32_16x16x32_bf16 v[58:61], v[70:73], v[98:101], v[58:61]
	v_mfma_f32_16x16x32_bf16 v[62:65], v[94:97], v[86:89], v[62:65]
	v_mfma_f32_16x16x32_bf16 v[2:5], v[94:97], v[98:101], v[2:5]
	s_waitcnt lgkmcnt(2)
	v_mfma_f32_16x16x32_bf16 v[48:51], v[36:39], v[24:27], v[66:69]
	v_mfma_f32_16x16x32_bf16 v[34:37], v[36:39], v[40:43], v[58:61]
	s_waitcnt lgkmcnt(1)
	v_mfma_f32_16x16x32_bf16 v[24:27], v[44:47], v[24:27], v[62:65]
	s_nop 0
	v_mov_b32_e32 v60, v187
	v_mfma_f32_16x16x32_bf16 v[2:5], v[44:47], v[40:43], v[2:5]
	ds_read_b128 v[38:41], v33 offset:49152
	ds_read_b128 v[42:45], v32 offset:34816
	ds_read_b128 v[56:59], v33 offset:51200
	s_waitcnt lgkmcnt(2)
	v_mfma_f32_16x16x32_bf16 v[6:9], v[52:55], v[38:41], v[6:9]
	s_waitcnt lgkmcnt(0)
	v_mfma_f32_16x16x32_bf16 v[10:13], v[52:55], v[56:59], v[10:13]
	v_mfma_f32_16x16x32_bf16 v[14:17], v[42:45], v[38:41], v[14:17]
	v_mfma_f32_16x16x32_bf16 v[20:23], v[42:45], v[56:59], v[20:23]
	ds_read_b128 v[42:45], v32 offset:36864
	ds_read_b128 v[52:55], v32 offset:38912
	v_lshl_or_b32 v32, v30, 2, v0
	v_lshl_or_b32 v0, v28, 6, v29
	s_waitcnt lgkmcnt(1)
	v_mfma_f32_16x16x32_bf16 v[46:49], v[42:45], v[38:41], v[48:51]
	v_mad_u64_u32 v[32:33], s[0:1], v32, s96, v[0:1]
	v_mul_f32_e32 v0, 0x3ab504f3, v6
	v_mfma_f32_16x16x32_bf16 v[28:31], v[42:45], v[56:59], v[34:37]
	v_mul_f32_e32 v6, 0x3ab504f3, v7
	v_mul_f32_e32 v7, 0x3ab504f3, v8
	v_mul_f32_e32 v8, 0x3ab504f3, v9
	s_waitcnt lgkmcnt(0)
	v_mfma_f32_16x16x32_bf16 v[24:27], v[52:55], v[38:41], v[24:27]
	v_mul_f32_e32 v9, 0x3ab504f3, v10
	v_mul_f32_e32 v10, 0x3ab504f3, v11
	v_mul_f32_e32 v11, 0x3ab504f3, v12
	v_mfma_f32_16x16x32_bf16 v[2:5], v[52:55], v[56:59], v[2:5]
	v_mul_f32_e32 v12, 0x3ab504f3, v13
	v_mul_f32_e32 v13, 0x3ab504f3, v14
	v_mul_f32_e32 v14, 0x3ab504f3, v15
	v_mul_f32_e32 v15, 0x3ab504f3, v16
	v_mul_f32_e32 v16, 0x3ab504f3, v17
	v_mul_f32_e32 v17, 0x3ab504f3, v20
	v_mul_f32_e32 v20, 0x3ab504f3, v21
	v_mul_f32_e32 v21, 0x3ab504f3, v22
	v_mul_f32_e32 v22, 0x3ab504f3, v23
	v_mul_f32_e32 v23, 0x3ab504f3, v46
	v_mul_f32_e32 v33, 0x3ab504f3, v47
	v_mul_f32_e32 v34, 0x3ab504f3, v48
	v_mul_f32_e32 v35, 0x3ab504f3, v49
	v_mul_f32_e32 v28, 0x3ab504f3, v28
	v_mul_f32_e32 v29, 0x3ab504f3, v29
	v_mul_f32_e32 v30, 0x3ab504f3, v30
	v_mul_f32_e32 v31, 0x3ab504f3, v31
	v_mul_f32_e32 v24, 0x3ab504f3, v24
	v_mul_f32_e32 v25, 0x3ab504f3, v25
	v_mul_f32_e32 v26, 0x3ab504f3, v26
	v_mul_f32_e32 v27, 0x3ab504f3, v27
	v_mul_f32_e32 v2, 0x3ab504f3, v2
	v_mul_f32_e32 v3, 0x3ab504f3, v3
	v_mul_f32_e32 v4, 0x3ab504f3, v4
	v_mul_f32_e32 v5, 0x3ab504f3, v5
	v_cvt_pk_bf16_f32 v0, v0, s0
	v_cvt_pk_bf16_f32 v6, v6, s0
	v_cvt_pk_bf16_f32 v7, v7, s0
	s_barrier
; __device__ __forceinline__ u16 f2bf(float f) { return (u16)(pack2(f, 0.f) & 0xffffu); }
; template <int NT, class VF, class RP>
; __device__ __forceinline__ void epi_staged_bf16(f32x4 (&acc)[4][NT], int r0, int c0, unsigned char* smem, VF vf, RP rowptr) {
;     ...
;   __syncthreads();
; #pragma unroll
;   for (int mi = 0; mi < 4; ++mi)
; #pragma unroll
;     for (int ni = 0; ni < NT; ++ni)
; #pragma unroll
;       for (int j = 0; j < 4; ++j) {
;         const int r = r0 + mi * 16 + j, c = c0 + ni * 16;
;         Ts[r * PITCH + c] = f2bf(vf(r, c, acc[mi][ni][j]));
;       }
;   __syncthreads();
; #pragma unroll
;   for (int i = 0; i < CPR / 2; ++i) {
;     const int c = t + 256 * i, row = c / CPR, ch = c % CPR;
;     u16* d = rowptr(row);
;     if (d) *(u32x4*)(d + ch * 8) = *(const u32x4*)(Ts + row * PITCH + ch * 8);
;   }
; __device__ __forceinline__ void phase_mix_b(const Params& p, int l, bool last, unsigned char* smem) {
;     ...
;       auto rp = [&](int k1) -> u16* { return p.YM + (size_t)(b * SEQ + 64 * k1 + k2) * 1024 + 256 + nq * 64; };
	v_cvt_pk_bf16_f32 v8, v8, s0
	v_cvt_pk_bf16_f32 v9, v9, s0
	v_cvt_pk_bf16_f32 v10, v10, s0
	v_cvt_pk_bf16_f32 v11, v11, s0
	v_cvt_pk_bf16_f32 v12, v12, s0
	v_cvt_pk_bf16_f32 v13, v13, s0
	v_cvt_pk_bf16_f32 v14, v14, s0
	v_cvt_pk_bf16_f32 v15, v15, s0
	v_cvt_pk_bf16_f32 v16, v16, s0
	v_cvt_pk_bf16_f32 v17, v17, s0
	v_cvt_pk_bf16_f32 v20, v20, s0
	v_cvt_pk_bf16_f32 v21, v21, s0
	v_cvt_pk_bf16_f32 v22, v22, s0
	v_cvt_pk_bf16_f32 v23, v23, s0
	v_cvt_pk_bf16_f32 v33, v33, s0
	v_cvt_pk_bf16_f32 v34, v34, s0
	v_cvt_pk_bf16_f32 v35, v35, s0
	v_cvt_pk_bf16_f32 v28, v28, s0
	v_cvt_pk_bf16_f32 v29, v29, s0
	v_cvt_pk_bf16_f32 v30, v30, s0
	v_cvt_pk_bf16_f32 v31, v31, s0
	v_cvt_pk_bf16_f32 v24, v24, s0
	v_cvt_pk_bf16_f32 v25, v25, s0
	v_cvt_pk_bf16_f32 v26, v26, s0
	v_cvt_pk_bf16_f32 v27, v27, s0
	v_cvt_pk_bf16_f32 v2, v2, s0
	v_cvt_pk_bf16_f32 v3, v3, s0
	v_cvt_pk_bf16_f32 v4, v4, s0
	v_cvt_pk_bf16_f32 v5, v5, s0
	ds_write_b16 v32, v0
	ds_write_b16 v32, v6 offset:144
	ds_write_b16 v32, v7 offset:288
	ds_write_b16 v32, v8 offset:432
	ds_write_b16 v32, v9 offset:32
	ds_write_b16 v32, v10 offset:176
	ds_write_b16 v32, v11 offset:320
	ds_write_b16 v32, v12 offset:464
	ds_write_b16 v32, v13 offset:2304
	ds_write_b16 v32, v14 offset:2448
	ds_write_b16 v32, v15 offset:2592
	ds_write_b16 v32, v16 offset:2736
	ds_write_b16 v32, v17 offset:2336
	ds_write_b16 v32, v20 offset:2480
	ds_write_b16 v32, v21 offset:2624
	ds_write_b16 v32, v22 offset:2768
	ds_write_b16 v32, v23 offset:4608
	ds_write_b16 v32, v33 offset:4752
	ds_write_b16 v32, v34 offset:4896
	ds_write_b16 v32, v35 offset:5040
	ds_write_b16 v32, v28 offset:4640
	ds_write_b16 v32, v29 offset:4784
	ds_write_b16 v32, v30 offset:4928
	ds_write_b16 v32, v31 offset:5072
	ds_write_b16 v32, v24 offset:6912
	ds_write_b16 v32, v25 offset:7056
	ds_write_b16 v32, v26 offset:7200
	ds_write_b16 v32, v27 offset:7344
	ds_write_b16 v32, v2 offset:6944
	ds_write_b16 v32, v3 offset:7088
	ds_write_b16 v32, v4 offset:7232
	ds_write_b16 v32, v5 offset:7376
	s_waitcnt lgkmcnt(0)
	s_barrier
	global_load_dwordx2 v[6:7], v[18:19], off offset:296
	v_ashrrev_i32_e32 v0, 31, v60
	v_lshrrev_b32_e32 v0, 29, v0
	v_add_u32_e32 v0, v60, v0
	s_lshl_b32 s0, s38, 13
	v_ashrrev_i32_e32 v2, 3, v0
	v_and_b32_e32 v0, -8, v0
	v_lshl_add_u32 v3, v2, 6, s0
	v_sub_u32_e32 v0, v60, v0
	v_mul_lo_u32 v2, v2, s96
	v_or_b32_e32 v8, s19, v3
	v_lshlrev_b32_e32 v10, 3, v0
	v_lshl_add_u32 v0, v0, 4, v2
	v_ashrrev_i32_e32 v9, 31, v8
	ds_read_b128 v[2:5], v0
	v_lshlrev_b64 v[8:9], 11, v[8:9]
	v_ashrrev_i32_e32 v11, 31, v10
	v_add_u32_e32 v0, 0x100, v60
	s_cmp_ge_i32 s9, s8
	s_waitcnt vmcnt(0) lgkmcnt(0)
	v_lshl_add_u64 v[6:7], v[6:7], 0, v[8:9]
	v_lshl_add_u64 v[6:7], v[6:7], 0, s[94:95]
	v_lshl_add_u64 v[6:7], v[10:11], 1, v[6:7]
	global_store_dwordx4 v[6:7], v[2:5], off offset:512
	global_load_dwordx2 v[6:7], v[18:19], off offset:296
	s_nop 0
	v_ashrrev_i32_e32 v2, 31, v0
	v_lshrrev_b32_e32 v2, 29, v2
	v_add_u32_e32 v2, v0, v2
	v_ashrrev_i32_e32 v3, 3, v2
	v_and_b32_e32 v2, -8, v2
	v_lshl_add_u32 v4, v3, 6, s0
	v_sub_u32_e32 v0, v0, v2
	v_mul_lo_u32 v2, v3, s96
	v_or_b32_e32 v8, s19, v4
	v_lshlrev_b32_e32 v10, 3, v0
	v_lshl_add_u32 v0, v0, 4, v2
	v_ashrrev_i32_e32 v9, 31, v8
	ds_read_b128 v[2:5], v0
	v_lshlrev_b64 v[8:9], 11, v[8:9]
	v_ashrrev_i32_e32 v11, 31, v10
	v_add_u32_e32 v0, 0x200, v60
	s_waitcnt vmcnt(0) lgkmcnt(0)
	v_lshl_add_u64 v[6:7], v[6:7], 0, v[8:9]
	v_lshl_add_u64 v[6:7], v[6:7], 0, s[94:95]
	v_lshl_add_u64 v[6:7], v[10:11], 1, v[6:7]
	global_store_dwordx4 v[6:7], v[2:5], off offset:512
	global_load_dwordx2 v[6:7], v[18:19], off offset:296
	s_nop 0
	v_ashrrev_i32_e32 v2, 31, v0
	v_lshrrev_b32_e32 v2, 29, v2
	v_add_u32_e32 v2, v0, v2
	v_ashrrev_i32_e32 v3, 3, v2
	v_and_b32_e32 v2, -8, v2
	v_lshl_add_u32 v4, v3, 6, s0
	v_sub_u32_e32 v0, v0, v2
	v_mul_lo_u32 v2, v3, s96
	v_or_b32_e32 v8, s19, v4
	v_lshlrev_b32_e32 v10, 3, v0
	v_lshl_add_u32 v0, v0, 4, v2
	v_ashrrev_i32_e32 v9, 31, v8
	ds_read_b128 v[2:5], v0
	v_lshlrev_b64 v[8:9], 11, v[8:9]
	v_ashrrev_i32_e32 v11, 31, v10
	v_add_u32_e32 v0, 0x300, v60
	s_waitcnt vmcnt(0) lgkmcnt(0)
	v_lshl_add_u64 v[6:7], v[6:7], 0, v[8:9]
	v_lshl_add_u64 v[6:7], v[6:7], 0, s[94:95]
	v_lshl_add_u64 v[6:7], v[10:11], 1, v[6:7]
	global_store_dwordx4 v[6:7], v[2:5], off offset:512
	global_load_dwordx2 v[6:7], v[18:19], off offset:296
	s_nop 0
	v_ashrrev_i32_e32 v2, 31, v0
	v_lshrrev_b32_e32 v2, 29, v2
	v_add_u32_e32 v2, v0, v2
	v_ashrrev_i32_e32 v3, 3, v2
	v_and_b32_e32 v2, -8, v2
	v_lshl_add_u32 v4, v3, 6, s0
	v_sub_u32_e32 v0, v0, v2
	v_mul_lo_u32 v2, v3, s96
	v_or_b32_e32 v8, s19, v4
	v_lshlrev_b32_e32 v10, 3, v0
	v_lshl_add_u32 v0, v0, 4, v2
	v_ashrrev_i32_e32 v9, 31, v8
	ds_read_b128 v[2:5], v0
	v_lshlrev_b64 v[8:9], 11, v[8:9]
	v_ashrrev_i32_e32 v11, 31, v10
	s_waitcnt vmcnt(0) lgkmcnt(0)
	v_lshl_add_u64 v[6:7], v[6:7], 0, v[8:9]
	v_lshl_add_u64 v[6:7], v[6:7], 0, s[94:95]
	v_lshl_add_u64 v[6:7], v[10:11], 1, v[6:7]
	global_store_dwordx4 v[6:7], v[2:5], off offset:512
	s_cbranch_scc0 .LBB0_685

; __device__ __forceinline__ void attn_item(const Params& p, int b, int h, int qt, float shift, unsigned char* smem) {
;     ...
;   {
;     bf16x8 vfr[4];
;     ATT_VLOAD((ntile - 1) % 3, 0);
;     ATT_SHIFT(sB);
;     ATT_FINISH(sB, (ntile - 1) % 3);
;   }
.LBB0_765:
	s_or_b64 exec, exec, s[0:1]
	v_exp_f32_e32 v185, v46
	v_exp_f32_e32 v193, v47
	v_exp_f32_e32 v195, v48
	v_exp_f32_e32 v199, v49
	v_exp_f32_e32 v201, v50
	v_exp_f32_e32 v203, v51
	v_exp_f32_e32 v205, v52
	v_exp_f32_e32 v47, v53
	v_exp_f32_e32 v173, v14
	v_add_f32_e32 v110, 0, v171
	v_add_f32_e32 v0, 0, v0
	v_exp_f32_e32 v171, v15
	v_pk_add_f32 v[48:49], v[184:185], v[0:1]
	v_exp_f32_e32 v177, v16
	v_pk_add_f32 v[48:49], v[192:193], v[48:49]
	v_cvt_pk_bf16_f32 v102, v185, v193
	v_cvt_pk_bf16_f32 v103, v195, v199
	v_cvt_pk_bf16_f32 v104, v201, v203
	v_cvt_pk_bf16_f32 v105, v205, v47
	v_exp_f32_e32 v175, v17
	v_mov_b32_e32 v111, v1
	v_pk_add_f32 v[48:49], v[194:195], v[48:49]
	v_exp_f32_e32 v181, v6
	s_waitcnt lgkmcnt(2)
	v_mfma_f32_16x16x32_bf16 v[50:53], v[90:93], v[102:105], v[34:37]
	v_add_f32_e64 v48, v198, v48
	v_add_f32_e64 v49, v199, v49
	v_exp_f32_e32 v179, v7
	v_exp_f32_e32 v183, v8
	v_pk_add_f32 v[34:35], v[172:173], v[110:111]
	v_exp_f32_e32 v113, v9
	v_pk_add_f32 v[34:35], v[170:171], v[34:35]
	v_pk_add_f32 v[48:49], v[200:201], v[48:49]
	v_pk_add_f32 v[34:35], v[176:177], v[34:35]
	v_pk_add_f32 v[48:49], v[202:203], v[48:49]
	v_pk_add_f32 v[34:35], v[174:175], v[34:35]
	v_pk_add_f32 v[48:49], v[204:205], v[48:49]
	v_mov_b32_e32 v46, v196
	v_pk_add_f32 v[34:35], v[180:181], v[34:35]
	v_pk_add_f32 v[48:49], v[46:47], v[48:49]
	v_cvt_pk_bf16_f32 v106, v173, v171
	v_cvt_pk_bf16_f32 v107, v177, v175
	v_cvt_pk_bf16_f32 v108, v181, v179
	v_cvt_pk_bf16_f32 v109, v183, v113
	v_pk_add_f32 v[34:35], v[178:179], v[34:35]
	v_add_f32_e32 v0, v48, v49
	v_mfma_f32_16x16x32_bf16 v[46:49], v[86:89], v[102:105], v[10:13]
	v_add_f32_e64 v34, v182, v34
	v_add_f32_e64 v35, v183, v35
	v_mov_b32_e32 v112, v197
	s_add_i32 s50, s50, s3
	s_waitcnt lgkmcnt(1)
	v_mfma_f32_16x16x32_bf16 v[10:13], v[94:97], v[106:109], v[62:65]
	s_cmp_gt_i32 s50, 63
	s_nop 1
	v_add3_u32 v62, s34, v208, v188
	v_mfma_f32_16x16x32_bf16 v[42:45], v[94:97], v[102:105], v[42:45]
	v_add_f32_e64 v94, v112, v34
	v_add_f32_e64 v95, v113, v35
	v_add_u32_e32 v34, 0x4800, v62
	v_add3_u32 v63, s34, v206, v188
	ds_read2_b64 v[34:37], v34 offset1:4
	v_add_u32_e32 v63, 0x4800, v63
	s_waitcnt lgkmcnt(1)
	v_mfma_f32_16x16x32_bf16 v[6:9], v[98:101], v[106:109], v[82:85]
	v_add_u32_e32 v62, 0x5000, v62
	s_movk_i32 s34, 0x100
	s_nop 0
	ds_read2_b64 v[82:85], v63 offset1:4
	v_mfma_f32_16x16x32_bf16 v[18:21], v[86:89], v[106:109], v[18:21]
	v_mfma_f32_16x16x32_bf16 v[14:17], v[90:93], v[106:109], v[38:41]
	ds_read2_b64 v[86:89], v62 offset0:64 offset1:68
	ds_read2_b64 v[90:93], v62 offset0:224 offset1:228
	s_waitcnt lgkmcnt(0)
	s_barrier
; __device__ __forceinline__ void attn_item(const Params& p, int b, int h, int qt, float shift, unsigned char* smem) {
;     ...
; #pragma unroll
;   for (int qi = 0; qi < 2; ++qi) {
;     float ls = qi ? lrun1 : lrun0;
;     ls += __shfl_xor(ls, 16);
;     ls += __shfl_xor(ls, 32);
;     const float inv = 1.f / ls;
;     const int pos = qt * 128 + wid * 32 + qi * 16 + l16;
;     const int row = (pos < CTX) ? (T_LAT + b * CTX + pos) : (b * SEQ + pos - CTX);
;     u16* orow = p.YM + (size_t)row * 1024 + 512 + h * 128 + quad * 4;
; #pragma unroll
;     for (int vt = 0; vt < 8; ++vt) {
;       u32x2 pk;
;       pk.x = pack2(o[vt][qi][0] * inv, o[vt][qi][1] * inv);
;       pk.y = pack2(o[vt][qi][2] * inv, o[vt][qi][3] * inv);
;       *(u32x2*)(orow + vt * 16) = pk;
;     }
;   }
	v_mfma_f32_16x16x32_bf16 v[38:41], v[98:101], v[102:105], v[66:69]
	v_mfma_f32_16x16x32_bf16 v[66:69], v[34:37], v[102:105], v[22:25]
	v_mfma_f32_16x16x32_bf16 v[34:37], v[34:37], v[106:109], v[26:29]
	v_mfma_f32_16x16x32_bf16 v[26:29], v[86:89], v[106:109], v[70:73]
	s_nop 2
	v_add_u32_e32 v70, s47, v190
	v_mfma_f32_16x16x32_bf16 v[62:65], v[82:85], v[102:105], v[30:33]
	s_mov_b32 s47, s95
	v_mfma_f32_16x16x32_bf16 v[30:33], v[82:85], v[106:109], v[54:57]
	v_mfma_f32_16x16x32_bf16 v[54:57], v[90:93], v[102:105], v[74:77]
	s_nop 2
	v_or_b32_e32 v77, v70, v189
	ds_bpermute_b32 v70, v230, v0
	v_mfma_f32_16x16x32_bf16 v[22:25], v[90:93], v[106:109], v[78:81]
	v_mov_b32_e32 v189, v1
	v_add_f32_e32 v76, v94, v95
	s_waitcnt lgkmcnt(0)
	v_add_f32_e32 v0, v0, v70
	ds_bpermute_b32 v70, v229, v0
	v_mov_b32_e32 v78, s48
	v_mov_b32_e32 v79, s49
	v_mfma_f32_16x16x32_bf16 v[58:61], v[86:89], v[102:105], v[58:61]
	s_waitcnt lgkmcnt(0)
	v_add_f32_e32 v0, v0, v70
	v_div_scale_f32 v70, s[0:1], v0, v0, 1.0
	v_rcp_f32_e32 v71, v70
	s_nop 0
	v_fma_f32 v72, -v70, v71, 1.0
	v_fmac_f32_e32 v71, v72, v71
	v_div_scale_f32 v72, vcc, 1.0, v0, 1.0
	v_mul_f32_e32 v73, v72, v71
	v_fma_f32 v74, -v70, v73, v72
	v_fmac_f32_e32 v73, v74, v71
	v_fma_f32 v70, -v70, v73, v72
	v_div_fmas_f32 v70, v70, v71, v73
	v_cmp_gt_i32_e32 vcc, s34, v77
	v_div_fixup_f32 v0, v70, v0, 1.0
	v_pk_mul_f32 v[38:39], v[38:39], v[0:1] op_sel_hi:[1,0]
	v_cndmask_b32_e32 v70, v78, v79, vcc
	v_add_u32_e32 v72, v70, v77
	v_mov_b64_e32 v[70:71], s[4:5]
	s_load_dwordx2 s[100:101], s[4:5], 0x128
	v_ashrrev_i32_e32 v73, 31, v72
	v_lshlrev_b64 v[72:73], 11, v[72:73]
	v_pk_mul_f32 v[40:41], v[40:41], v[0:1] op_sel_hi:[1,0]
	v_cvt_pk_bf16_f32 v38, v38, v39
	v_cvt_pk_bf16_f32 v39, v40, v41
	v_pk_mul_f32 v[40:41], v[68:69], v[0:1] op_sel_hi:[1,0]
	v_pk_mul_f32 v[46:47], v[46:47], v[0:1] op_sel_hi:[1,0]
	v_pk_mul_f32 v[48:49], v[48:49], v[0:1] op_sel_hi:[1,0]
	v_cvt_pk_bf16_f32 v46, v46, v47
	v_cvt_pk_bf16_f32 v47, v48, v49
	v_pk_mul_f32 v[48:49], v[52:53], v[0:1] op_sel_hi:[1,0]
	v_pk_mul_f32 v[42:43], v[42:43], v[0:1] op_sel_hi:[1,0]
	v_pk_mul_f32 v[44:45], v[44:45], v[0:1] op_sel_hi:[1,0]
	v_cvt_pk_bf16_f32 v42, v42, v43
	v_cvt_pk_bf16_f32 v43, v44, v45
	s_waitcnt lgkmcnt(0)
	v_mov_b32_e32 v74, s100
	v_mov_b32_e32 v75, s101
	v_lshl_add_u64 v[72:73], v[74:75], 0, v[72:73]
	v_lshl_add_u64 v[72:73], v[72:73], 0, s[46:47]
	v_lshl_add_u64 v[72:73], v[72:73], 0, v[188:189]
	global_store_dwordx2 v[72:73], v[38:39], off offset:1120
	v_pk_mul_f32 v[38:39], v[66:67], v[0:1] op_sel_hi:[1,0]
	global_store_dwordx2 v[72:73], v[46:47], off offset:1024
	v_cvt_pk_bf16_f32 v38, v38, v39
	v_cvt_pk_bf16_f32 v39, v40, v41
	global_store_dwordx2 v[72:73], v[38:39], off offset:1152
	v_pk_mul_f32 v[38:39], v[62:63], v[0:1] op_sel_hi:[1,0]
	v_pk_mul_f32 v[40:41], v[64:65], v[0:1] op_sel_hi:[1,0]
	v_cvt_pk_bf16_f32 v38, v38, v39
	v_cvt_pk_bf16_f32 v39, v40, v41
	global_store_dwordx2 v[72:73], v[38:39], off offset:1184
	v_pk_mul_f32 v[38:39], v[58:59], v[0:1] op_sel_hi:[1,0]
	v_pk_mul_f32 v[40:41], v[60:61], v[0:1] op_sel_hi:[1,0]
	v_cvt_pk_bf16_f32 v38, v38, v39
	v_cvt_pk_bf16_f32 v39, v40, v41
	v_pk_mul_f32 v[46:47], v[50:51], v[0:1] op_sel_hi:[1,0]
	global_store_dwordx2 v[72:73], v[38:39], off offset:1216
	v_pk_mul_f32 v[38:39], v[54:55], v[0:1] op_sel_hi:[1,0]
	v_pk_mul_f32 v[40:41], v[56:57], v[0:1] op_sel_hi:[1,0]
	ds_bpermute_b32 v0, v230, v76
	v_cvt_pk_bf16_f32 v38, v38, v39
	v_cvt_pk_bf16_f32 v39, v40, v41
	global_store_dwordx2 v[72:73], v[38:39], off offset:1248
	global_store_dwordx2 v[72:73], v[42:43], off offset:1088
	s_waitcnt lgkmcnt(0)
	v_add_f32_e32 v0, v76, v0
	ds_bpermute_b32 v38, v229, v0
	v_cvt_pk_bf16_f32 v46, v46, v47
	v_cvt_pk_bf16_f32 v47, v48, v49
	global_store_dwordx2 v[72:73], v[46:47], off offset:1056
	s_waitcnt lgkmcnt(0)
	v_add_f32_e32 v0, v0, v38
	v_div_scale_f32 v38, s[0:1], v0, v0, 1.0
	v_rcp_f32_e32 v39, v38
	s_nop 0
	v_fma_f32 v40, -v38, v39, 1.0
	v_fmac_f32_e32 v39, v40, v39
	v_div_scale_f32 v40, vcc, 1.0, v0, 1.0
	v_mul_f32_e32 v41, v40, v39
	v_fma_f32 v42, -v38, v41, v40
	v_fmac_f32_e32 v41, v42, v39
	v_fma_f32 v38, -v38, v41, v40
	v_div_fmas_f32 v38, v38, v39, v41
	global_load_dwordx2 v[40:41], v[70:71], off offset:296
	v_div_fixup_f32 v0, v38, v0, 1.0
	v_or_b32_e32 v38, 16, v77
	v_cmp_gt_i32_e32 vcc, s34, v38
	v_pk_mul_f32 v[6:7], v[6:7], v[0:1] op_sel_hi:[1,0]
	v_pk_mul_f32 v[8:9], v[8:9], v[0:1] op_sel_hi:[1,0]
	v_cndmask_b32_e32 v39, v78, v79, vcc
	v_add_u32_e32 v38, v39, v38
	v_ashrrev_i32_e32 v39, 31, v38
	v_lshlrev_b64 v[38:39], 11, v[38:39]
	v_cvt_pk_bf16_f32 v6, v6, v7
	v_cvt_pk_bf16_f32 v7, v8, v9
	v_pk_mul_f32 v[8:9], v[36:37], v[0:1] op_sel_hi:[1,0]
	v_pk_mul_f32 v[18:19], v[18:19], v[0:1] op_sel_hi:[1,0]
	v_pk_mul_f32 v[20:21], v[20:21], v[0:1] op_sel_hi:[1,0]
	v_pk_mul_f32 v[14:15], v[14:15], v[0:1] op_sel_hi:[1,0]
	v_pk_mul_f32 v[16:17], v[16:17], v[0:1] op_sel_hi:[1,0]
	v_pk_mul_f32 v[10:11], v[10:11], v[0:1] op_sel_hi:[1,0]
	v_pk_mul_f32 v[12:13], v[12:13], v[0:1] op_sel_hi:[1,0]
	v_cvt_pk_bf16_f32 v18, v18, v19
	v_cvt_pk_bf16_f32 v19, v20, v21
	v_cvt_pk_bf16_f32 v14, v14, v15
	v_cvt_pk_bf16_f32 v15, v16, v17
	v_cvt_pk_bf16_f32 v10, v10, v11
	v_cvt_pk_bf16_f32 v11, v12, v13
	s_waitcnt vmcnt(0) lgkmcnt(0)
	v_lshl_add_u64 v[38:39], v[40:41], 0, v[38:39]
	v_lshl_add_u64 v[38:39], v[38:39], 0, s[46:47]
	v_lshl_add_u64 v[38:39], v[38:39], 0, v[188:189]
	global_store_dwordx2 v[38:39], v[6:7], off offset:1120
	v_pk_mul_f32 v[6:7], v[34:35], v[0:1] op_sel_hi:[1,0]
	global_store_dwordx2 v[38:39], v[18:19], off offset:1024
	v_cvt_pk_bf16_f32 v6, v6, v7
	v_cvt_pk_bf16_f32 v7, v8, v9
	global_store_dwordx2 v[38:39], v[6:7], off offset:1152
	v_pk_mul_f32 v[6:7], v[30:31], v[0:1] op_sel_hi:[1,0]
	v_pk_mul_f32 v[8:9], v[32:33], v[0:1] op_sel_hi:[1,0]
	v_cvt_pk_bf16_f32 v6, v6, v7
	v_cvt_pk_bf16_f32 v7, v8, v9
	global_store_dwordx2 v[38:39], v[6:7], off offset:1184
	v_pk_mul_f32 v[6:7], v[26:27], v[0:1] op_sel_hi:[1,0]
	v_pk_mul_f32 v[8:9], v[28:29], v[0:1] op_sel_hi:[1,0]
	v_cvt_pk_bf16_f32 v6, v6, v7
	v_cvt_pk_bf16_f32 v7, v8, v9
	global_store_dwordx2 v[38:39], v[6:7], off offset:1216
	v_pk_mul_f32 v[6:7], v[22:23], v[0:1] op_sel_hi:[1,0]
	v_pk_mul_f32 v[8:9], v[24:25], v[0:1] op_sel_hi:[1,0]
	v_cvt_pk_bf16_f32 v6, v6, v7
	v_cvt_pk_bf16_f32 v7, v8, v9
	global_store_dwordx2 v[38:39], v[14:15], off offset:1056
	global_store_dwordx2 v[38:39], v[10:11], off offset:1088
	global_store_dwordx2 v[38:39], v[6:7], off offset:1248
	s_cbranch_scc1 .LBB0_776

; __device__ __forceinline__ void phase_attn(const Params& p, int l, bool last, unsigned char* smem) {
;     ...
;   if (!last)
;     for (int q = j; q < 2; q += gb) attn_item(p, x >> 2, x & 3, q, shift, smem);
.LBB0_778:
	s_or_b64 exec, exec, s[0:1]
	v_exp_f32_e32 v185, v46
	v_exp_f32_e32 v193, v47
	v_exp_f32_e32 v195, v48
	v_exp_f32_e32 v197, v49
	v_exp_f32_e32 v199, v50
	v_exp_f32_e32 v201, v51
	v_exp_f32_e32 v205, v52
	v_exp_f32_e32 v47, v53
	v_exp_f32_e32 v173, v14
	v_add_f32_e32 v110, 0, v171
	v_exp_f32_e32 v171, v15
	v_add_f32_e32 v0, 0, v0
	v_exp_f32_e32 v177, v16
	v_pk_add_f32 v[48:49], v[184:185], v[0:1]
	v_cvt_pk_bf16_f32 v102, v185, v193
	v_cvt_pk_bf16_f32 v103, v195, v197
	v_cvt_pk_bf16_f32 v104, v199, v201
	v_cvt_pk_bf16_f32 v105, v205, v47
	v_exp_f32_e32 v175, v17
	v_mov_b32_e32 v111, v1
	v_pk_add_f32 v[48:49], v[192:193], v[48:49]
	v_exp_f32_e32 v181, v6
	s_waitcnt lgkmcnt(2)
	v_mfma_f32_16x16x32_bf16 v[50:53], v[90:93], v[102:105], v[34:37]
	v_add_f32_e64 v48, v194, v48
	v_add_f32_e64 v49, v195, v49
	v_exp_f32_e32 v179, v7
	v_pk_add_f32 v[48:49], v[196:197], v[48:49]
	v_pk_add_f32 v[34:35], v[172:173], v[110:111]
	v_exp_f32_e32 v183, v8
	v_pk_add_f32 v[34:35], v[170:171], v[34:35]
	v_exp_f32_e32 v113, v9
	v_pk_add_f32 v[34:35], v[176:177], v[34:35]
	v_pk_add_f32 v[48:49], v[198:199], v[48:49]
	v_pk_add_f32 v[34:35], v[174:175], v[34:35]
	v_pk_add_f32 v[48:49], v[200:201], v[48:49]
	v_pk_add_f32 v[34:35], v[180:181], v[34:35]
	v_pk_add_f32 v[48:49], v[204:205], v[48:49]
	v_mov_b32_e32 v46, v202
	v_pk_add_f32 v[34:35], v[178:179], v[34:35]
	v_pk_add_f32 v[48:49], v[46:47], v[48:49]
	v_cvt_pk_bf16_f32 v106, v173, v171
	v_cvt_pk_bf16_f32 v107, v177, v175
	v_cvt_pk_bf16_f32 v108, v181, v179
	v_cvt_pk_bf16_f32 v109, v183, v113
	v_pk_add_f32 v[34:35], v[182:183], v[34:35]
	v_mov_b32_e32 v112, v203
	v_add_f32_e32 v0, v48, v49
	v_mfma_f32_16x16x32_bf16 v[46:49], v[86:89], v[102:105], v[10:13]
	s_movk_i32 s34, 0x100
	s_add_i32 s8, s8, s3
	s_cmp_lt_i32 s8, 2
	s_waitcnt lgkmcnt(1)
	v_mfma_f32_16x16x32_bf16 v[42:45], v[94:97], v[102:105], v[42:45]
	v_mfma_f32_16x16x32_bf16 v[10:13], v[94:97], v[106:109], v[62:65]
	v_add_f32_e64 v94, v112, v34
	v_add_f32_e64 v95, v113, v35
	v_add_u32_e32 v34, 0xa000, v191
	ds_read2_b64 v[34:37], v34 offset0:128 offset1:132
	v_add_u32_e32 v62, 0xa800, v191
	v_mfma_f32_16x16x32_bf16 v[18:21], v[86:89], v[106:109], v[18:21]
	s_waitcnt lgkmcnt(1)
	v_mfma_f32_16x16x32_bf16 v[6:9], v[98:101], v[106:109], v[82:85]
	s_nop 2
	ds_read2_b64 v[82:85], v62 offset0:32 offset1:36
	ds_read2_b64 v[86:89], v62 offset0:192 offset1:196
	v_add_u32_e32 v62, 0xb000, v191
	v_mfma_f32_16x16x32_bf16 v[14:17], v[90:93], v[106:109], v[38:41]
	ds_read2_b64 v[90:93], v62 offset0:96 offset1:100
	s_waitcnt lgkmcnt(0)
	s_barrier
; __device__ __forceinline__ void attn_item(const Params& p, int b, int h, int qt, float shift, unsigned char* smem) {
;     ...
; #pragma unroll
;   for (int qi = 0; qi < 2; ++qi) {
;     float ls = qi ? lrun1 : lrun0;
;     ls += __shfl_xor(ls, 16);
;     ls += __shfl_xor(ls, 32);
;     const float inv = 1.f / ls;
;     const int pos = qt * 128 + wid * 32 + qi * 16 + l16;
;     const int row = (pos < CTX) ? (T_LAT + b * CTX + pos) : (b * SEQ + pos - CTX);
;     u16* orow = p.YM + (size_t)row * 1024 + 512 + h * 128 + quad * 4;
; #pragma unroll
;     for (int vt = 0; vt < 8; ++vt) {
;       u32x2 pk;
;       pk.x = pack2(o[vt][qi][0] * inv, o[vt][qi][1] * inv);
;       pk.y = pack2(o[vt][qi][2] * inv, o[vt][qi][3] * inv);
;       *(u32x2*)(orow + vt * 16) = pk;
;     }
;   }
	v_mfma_f32_16x16x32_bf16 v[38:41], v[98:101], v[102:105], v[66:69]
	v_mfma_f32_16x16x32_bf16 v[66:69], v[34:37], v[102:105], v[22:25]
	v_mfma_f32_16x16x32_bf16 v[34:37], v[34:37], v[106:109], v[26:29]
	v_mfma_f32_16x16x32_bf16 v[26:29], v[86:89], v[106:109], v[70:73]
	s_nop 2
	v_add_u32_e32 v70, s46, v190
	v_mfma_f32_16x16x32_bf16 v[62:65], v[82:85], v[102:105], v[30:33]
	v_mfma_f32_16x16x32_bf16 v[30:33], v[82:85], v[106:109], v[54:57]
	v_mfma_f32_16x16x32_bf16 v[54:57], v[90:93], v[102:105], v[74:77]
	s_nop 2
	v_or_b32_e32 v77, v70, v189
	ds_bpermute_b32 v70, v230, v0
	v_mfma_f32_16x16x32_bf16 v[22:25], v[90:93], v[106:109], v[78:81]
	v_mov_b32_e32 v189, v1
	v_add_f32_e32 v76, v94, v95
	s_waitcnt lgkmcnt(0)
	v_add_f32_e32 v0, v0, v70
	ds_bpermute_b32 v70, v229, v0
	v_mov_b32_e32 v78, s18
	v_mov_b32_e32 v79, s19
	v_mfma_f32_16x16x32_bf16 v[58:61], v[86:89], v[102:105], v[58:61]
	s_waitcnt lgkmcnt(0)
	v_add_f32_e32 v0, v0, v70
	v_div_scale_f32 v70, s[0:1], v0, v0, 1.0
	v_rcp_f32_e32 v71, v70
	s_nop 0
	v_fma_f32 v72, -v70, v71, 1.0
	v_fmac_f32_e32 v71, v72, v71
	v_div_scale_f32 v72, vcc, 1.0, v0, 1.0
	v_mul_f32_e32 v73, v72, v71
	v_fma_f32 v74, -v70, v73, v72
	v_fmac_f32_e32 v73, v74, v71
	v_fma_f32 v70, -v70, v73, v72
	v_div_fmas_f32 v70, v70, v71, v73
	v_cmp_gt_i32_e32 vcc, s34, v77
	v_div_fixup_f32 v0, v70, v0, 1.0
	v_pk_mul_f32 v[38:39], v[38:39], v[0:1] op_sel_hi:[1,0]
	v_cndmask_b32_e32 v70, v78, v79, vcc
	v_add_u32_e32 v72, v70, v77
	v_mov_b64_e32 v[70:71], s[4:5]
	s_load_dwordx2 s[100:101], s[4:5], 0x128
	v_ashrrev_i32_e32 v73, 31, v72
	v_lshlrev_b64 v[72:73], 11, v[72:73]
	v_pk_mul_f32 v[40:41], v[40:41], v[0:1] op_sel_hi:[1,0]
	v_cvt_pk_bf16_f32 v38, v38, v39
	v_cvt_pk_bf16_f32 v39, v40, v41
	v_pk_mul_f32 v[40:41], v[68:69], v[0:1] op_sel_hi:[1,0]
	v_pk_mul_f32 v[46:47], v[46:47], v[0:1] op_sel_hi:[1,0]
	v_pk_mul_f32 v[48:49], v[48:49], v[0:1] op_sel_hi:[1,0]
	v_cvt_pk_bf16_f32 v46, v46, v47
	v_cvt_pk_bf16_f32 v47, v48, v49
	v_pk_mul_f32 v[48:49], v[52:53], v[0:1] op_sel_hi:[1,0]
	v_pk_mul_f32 v[42:43], v[42:43], v[0:1] op_sel_hi:[1,0]
	v_pk_mul_f32 v[44:45], v[44:45], v[0:1] op_sel_hi:[1,0]
	v_cvt_pk_bf16_f32 v42, v42, v43
	v_cvt_pk_bf16_f32 v43, v44, v45
	s_waitcnt lgkmcnt(0)
	v_mov_b32_e32 v74, s100
	v_mov_b32_e32 v75, s101
	v_lshl_add_u64 v[72:73], v[74:75], 0, v[72:73]
	v_lshl_add_u64 v[72:73], v[72:73], 0, s[94:95]
	v_lshl_add_u64 v[72:73], v[72:73], 0, v[188:189]
	global_store_dwordx2 v[72:73], v[38:39], off offset:1120
	v_pk_mul_f32 v[38:39], v[66:67], v[0:1] op_sel_hi:[1,0]
	global_store_dwordx2 v[72:73], v[46:47], off offset:1024
	v_cvt_pk_bf16_f32 v38, v38, v39
	v_cvt_pk_bf16_f32 v39, v40, v41
	global_store_dwordx2 v[72:73], v[38:39], off offset:1152
	v_pk_mul_f32 v[38:39], v[62:63], v[0:1] op_sel_hi:[1,0]
	v_pk_mul_f32 v[40:41], v[64:65], v[0:1] op_sel_hi:[1,0]
	v_cvt_pk_bf16_f32 v38, v38, v39
	v_cvt_pk_bf16_f32 v39, v40, v41
	global_store_dwordx2 v[72:73], v[38:39], off offset:1184
	v_pk_mul_f32 v[38:39], v[58:59], v[0:1] op_sel_hi:[1,0]
	v_pk_mul_f32 v[40:41], v[60:61], v[0:1] op_sel_hi:[1,0]
	v_cvt_pk_bf16_f32 v38, v38, v39
	v_cvt_pk_bf16_f32 v39, v40, v41
	v_pk_mul_f32 v[46:47], v[50:51], v[0:1] op_sel_hi:[1,0]
	global_store_dwordx2 v[72:73], v[38:39], off offset:1216
	v_pk_mul_f32 v[38:39], v[54:55], v[0:1] op_sel_hi:[1,0]
	v_pk_mul_f32 v[40:41], v[56:57], v[0:1] op_sel_hi:[1,0]
	ds_bpermute_b32 v0, v230, v76
	v_cvt_pk_bf16_f32 v38, v38, v39
	v_cvt_pk_bf16_f32 v39, v40, v41
	global_store_dwordx2 v[72:73], v[38:39], off offset:1248
	global_store_dwordx2 v[72:73], v[42:43], off offset:1088
	s_waitcnt lgkmcnt(0)
	v_add_f32_e32 v0, v76, v0
	ds_bpermute_b32 v38, v229, v0
	v_cvt_pk_bf16_f32 v46, v46, v47
	v_cvt_pk_bf16_f32 v47, v48, v49
	global_store_dwordx2 v[72:73], v[46:47], off offset:1056
	s_waitcnt lgkmcnt(0)
	v_add_f32_e32 v0, v0, v38
	v_div_scale_f32 v38, s[0:1], v0, v0, 1.0
	v_rcp_f32_e32 v39, v38
	s_nop 0
	v_fma_f32 v40, -v38, v39, 1.0
	v_fmac_f32_e32 v39, v40, v39
	v_div_scale_f32 v40, vcc, 1.0, v0, 1.0
	v_mul_f32_e32 v41, v40, v39
	v_fma_f32 v42, -v38, v41, v40
	v_fmac_f32_e32 v41, v42, v39
	v_fma_f32 v38, -v38, v41, v40
	v_div_fmas_f32 v38, v38, v39, v41
	global_load_dwordx2 v[40:41], v[70:71], off offset:296
	v_div_fixup_f32 v0, v38, v0, 1.0
	v_or_b32_e32 v38, 16, v77
	v_cmp_gt_i32_e32 vcc, s34, v38
	v_pk_mul_f32 v[6:7], v[6:7], v[0:1] op_sel_hi:[1,0]
	v_pk_mul_f32 v[8:9], v[8:9], v[0:1] op_sel_hi:[1,0]
	v_cndmask_b32_e32 v39, v78, v79, vcc
	v_add_u32_e32 v38, v39, v38
	v_ashrrev_i32_e32 v39, 31, v38
	v_lshlrev_b64 v[38:39], 11, v[38:39]
	v_cvt_pk_bf16_f32 v6, v6, v7
	v_cvt_pk_bf16_f32 v7, v8, v9
	v_pk_mul_f32 v[8:9], v[36:37], v[0:1] op_sel_hi:[1,0]
	v_pk_mul_f32 v[18:19], v[18:19], v[0:1] op_sel_hi:[1,0]
	v_pk_mul_f32 v[20:21], v[20:21], v[0:1] op_sel_hi:[1,0]
	v_pk_mul_f32 v[14:15], v[14:15], v[0:1] op_sel_hi:[1,0]
	v_pk_mul_f32 v[16:17], v[16:17], v[0:1] op_sel_hi:[1,0]
	v_pk_mul_f32 v[10:11], v[10:11], v[0:1] op_sel_hi:[1,0]
	v_pk_mul_f32 v[12:13], v[12:13], v[0:1] op_sel_hi:[1,0]
	v_cvt_pk_bf16_f32 v18, v18, v19
	v_cvt_pk_bf16_f32 v19, v20, v21
	v_cvt_pk_bf16_f32 v14, v14, v15
	v_cvt_pk_bf16_f32 v15, v16, v17
	v_cvt_pk_bf16_f32 v10, v10, v11
	v_cvt_pk_bf16_f32 v11, v12, v13
	s_waitcnt vmcnt(0) lgkmcnt(0)
	v_lshl_add_u64 v[38:39], v[40:41], 0, v[38:39]
	v_lshl_add_u64 v[38:39], v[38:39], 0, s[94:95]
	v_lshl_add_u64 v[38:39], v[38:39], 0, v[188:189]
	global_store_dwordx2 v[38:39], v[6:7], off offset:1120
	v_pk_mul_f32 v[6:7], v[34:35], v[0:1] op_sel_hi:[1,0]
	global_store_dwordx2 v[38:39], v[18:19], off offset:1024
	v_cvt_pk_bf16_f32 v6, v6, v7
	v_cvt_pk_bf16_f32 v7, v8, v9
	global_store_dwordx2 v[38:39], v[6:7], off offset:1152
	v_pk_mul_f32 v[6:7], v[30:31], v[0:1] op_sel_hi:[1,0]
	v_pk_mul_f32 v[8:9], v[32:33], v[0:1] op_sel_hi:[1,0]
	v_cvt_pk_bf16_f32 v6, v6, v7
	v_cvt_pk_bf16_f32 v7, v8, v9
	global_store_dwordx2 v[38:39], v[6:7], off offset:1184
	v_pk_mul_f32 v[6:7], v[26:27], v[0:1] op_sel_hi:[1,0]
	v_pk_mul_f32 v[8:9], v[28:29], v[0:1] op_sel_hi:[1,0]
	v_cvt_pk_bf16_f32 v6, v6, v7
	v_cvt_pk_bf16_f32 v7, v8, v9
	global_store_dwordx2 v[38:39], v[6:7], off offset:1216
	v_pk_mul_f32 v[6:7], v[22:23], v[0:1] op_sel_hi:[1,0]
	v_pk_mul_f32 v[8:9], v[24:25], v[0:1] op_sel_hi:[1,0]
	v_cvt_pk_bf16_f32 v6, v6, v7
	v_cvt_pk_bf16_f32 v7, v8, v9
	global_store_dwordx2 v[38:39], v[14:15], off offset:1056
	global_store_dwordx2 v[38:39], v[10:11], off offset:1088
	global_store_dwordx2 v[38:39], v[6:7], off offset:1248
	s_cbranch_scc0 .LBB0_790

; __device__ __forceinline__ void epi_staged_residual(f32x4 (&acc)[4][4], int r0, int c0, unsigned char* smem, const float* __restrict__ g,
;                                                     const float* __restrict__ xs, float* __restrict__ xd) {
;     ...
; #pragma unroll
;     for (int i = 0; i < 8; ++i) {
;       const int c = t + 256 * i, row = c >> 5, ch = c & 31;
;       const float4 a = *(const float4*)(Ts + row * PITCH + ch * 4);
;       const float4 gg = *(const float4*)(g + ch * 4);
;       const size_t o = (size_t)(pass * 64 + row) * DM + ch * 4;
;       float4 x = *(const float4*)(xs + o);
;       x.x += gg.x * a.x; x.y += gg.y * a.y; x.z += gg.z * a.z; x.w += gg.w * a.w;
;       *(float4*)(xd + o) = x;
;     }
.LBB0_844:
	s_or_b64 exec, exec, s[8:9]
	s_add_u32 s98, s0, s28
	s_addc_u32 s99, s1, s29
	s_add_u32 s100, s46, s28
	s_addc_u32 s101, s47, s29
	s_waitcnt lgkmcnt(0)
	s_barrier
	global_load_dwordx4 v[72:75], v89, s[98:99]
	global_load_dwordx4 v[76:79], v90, s[98:99]
	global_load_dwordx4 v[80:83], v91, s[98:99]
	global_load_dwordx4 v[96:99], v92, s[98:99]
	global_load_dwordx4 v[100:103], v93, s[98:99]
	global_load_dwordx4 v[236:239], v94, s[98:99]
	global_load_dwordx4 v[240:243], v95, s[98:99]
	global_load_dwordx4 v[244:247], v104, s[98:99]
	ds_read_b128 v[206:209], v88 offset:0
	ds_read_b128 v[210:213], v88 offset:4224
	ds_read_b128 v[216:219], v88 offset:8448
	ds_read_b128 v[220:223], v88 offset:12672
	s_waitcnt vmcnt(4) lgkmcnt(0)
	v_pk_fma_f32 v[206:207], v[2:3], v[206:207], v[72:73]
	v_pk_fma_f32 v[208:209], v[4:5], v[208:209], v[74:75]
	v_pk_fma_f32 v[210:211], v[2:3], v[210:211], v[76:77]
	v_pk_fma_f32 v[212:213], v[4:5], v[212:213], v[78:79]
	v_pk_fma_f32 v[216:217], v[2:3], v[216:217], v[80:81]
	v_pk_fma_f32 v[218:219], v[4:5], v[218:219], v[82:83]
	v_pk_fma_f32 v[220:221], v[2:3], v[220:221], v[96:97]
	v_pk_fma_f32 v[222:223], v[4:5], v[222:223], v[98:99]
	global_store_dwordx4 v89, v[206:209], s[100:101]
	global_store_dwordx4 v90, v[210:213], s[100:101]
	global_store_dwordx4 v91, v[216:219], s[100:101]
	global_store_dwordx4 v92, v[220:223], s[100:101]
	ds_read_b128 v[206:209], v88 offset:16896
	ds_read_b128 v[210:213], v88 offset:21120
	ds_read_b128 v[216:219], v88 offset:25344
	ds_read_b128 v[220:223], v88 offset:29568
	s_waitcnt vmcnt(4) lgkmcnt(0)
	v_pk_fma_f32 v[206:207], v[2:3], v[206:207], v[100:101]
	v_pk_fma_f32 v[208:209], v[4:5], v[208:209], v[102:103]
	v_pk_fma_f32 v[210:211], v[2:3], v[210:211], v[236:237]
	v_pk_fma_f32 v[212:213], v[4:5], v[212:213], v[238:239]
	v_pk_fma_f32 v[216:217], v[2:3], v[216:217], v[240:241]
	v_pk_fma_f32 v[218:219], v[4:5], v[218:219], v[242:243]
	v_pk_fma_f32 v[220:221], v[2:3], v[220:221], v[244:245]
	v_pk_fma_f32 v[222:223], v[4:5], v[222:223], v[246:247]
	global_store_dwordx4 v93, v[206:209], s[100:101]
	global_store_dwordx4 v94, v[210:213], s[100:101]
	global_store_dwordx4 v95, v[216:219], s[100:101]
	global_store_dwordx4 v104, v[220:223], s[100:101]
	s_add_i32 s19, s19, s3
	s_add_i32 s50, s50, s3
	s_add_i32 s51, s51, s21
	s_cmp_ge_i32 s19, s18
	s_cbranch_scc1 .LBB0_851

; __device__ __forceinline__ void epi_staged_residual(f32x4 (&acc)[4][4], int r0, int c0, unsigned char* smem, const float* __restrict__ g,
;                                                     const float* __restrict__ xs, float* __restrict__ xd) {
;     ...
;   const int wr = r0 >> 6;
; #pragma unroll
;   for (int pass = 0; pass < 2; ++pass) {
;     __syncthreads();
;     if (wr == pass) {
; #pragma unroll
;       for (int mi = 0; mi < 4; ++mi)
; #pragma unroll
;         for (int ni = 0; ni < 4; ++ni)
; #pragma unroll
;           for (int j = 0; j < 4; ++j) Ts[((r0 & 63) + mi * 16 + j) * PITCH + c0 + ni * 16] = acc[mi][ni][j];
;     }
;     __syncthreads();
; #pragma unroll
;     for (int i = 0; i < 8; ++i) {
;       const int c = t + 256 * i, row = c >> 5, ch = c & 31;
;       const float4 a = *(const float4*)(Ts + row * PITCH + ch * 4);
;       const float4 gg = *(const float4*)(g + ch * 4);
;       const size_t o = (size_t)(pass * 64 + row) * DM + ch * 4;
;       float4 x = *(const float4*)(xs + o);
;       x.x += gg.x * a.x; x.y += gg.y * a.y; x.z += gg.z * a.z; x.w += gg.w * a.w;
;       *(float4*)(xd + o) = x;
;     }
.LBB0_849:
	s_or_b64 exec, exec, s[8:9]
	s_lshl_b32 s8, s52, 7
	s_lshl_b64 s[0:1], s[0:1], 2
	s_add_u32 s9, s42, s0
	s_addc_u32 s34, s43, s1
	v_ashrrev_i32_e32 v70, 5, v84
	s_add_u32 s35, s4, s0
	v_mul_lo_u32 v71, v70, s97
	s_addc_u32 s47, s5, s1
	s_lshl_b32 s8, s8, 2
	v_add_u32_e32 v88, v0, v71
	v_ashrrev_i32_e32 v71, 31, v70
	s_add_u32 s0, s9, s8
	v_lshlrev_b64 v[70:71], 12, v[70:71]
	s_addc_u32 s1, s34, 0
	v_or_b32_e32 v70, v70, v0
	v_lshl_add_u64 v[76:77], s[0:1], 0, v[70:71]
	s_waitcnt lgkmcnt(0)
	s_barrier
	s_add_u32 s46, s35, s8
	s_addc_u32 s47, s47, 0
	v_cmp_eq_u32_e32 vcc, 1, v158
	v_mov_b32_e32 v89, v70
	v_add_u32_e32 v90, 0x8000, v70
	v_add_u32_e32 v91, 0x10000, v70
	v_add_u32_e32 v92, 0x18000, v70
	v_add_u32_e32 v93, 0x20000, v70
	v_add_u32_e32 v94, 0x28000, v70
	v_add_u32_e32 v95, 0x30000, v70
	v_add_u32_e32 v104, 0x38000, v70
	global_load_dwordx4 v[72:75], v89, s[0:1]
	global_load_dwordx4 v[76:79], v90, s[0:1]
	global_load_dwordx4 v[80:83], v91, s[0:1]
	global_load_dwordx4 v[96:99], v92, s[0:1]
	global_load_dwordx4 v[100:103], v93, s[0:1]
	global_load_dwordx4 v[236:239], v94, s[0:1]
	global_load_dwordx4 v[240:243], v95, s[0:1]
	global_load_dwordx4 v[244:247], v104, s[0:1]
	ds_read_b128 v[206:209], v88 offset:0
	ds_read_b128 v[210:213], v88 offset:4224
	ds_read_b128 v[216:219], v88 offset:8448
	ds_read_b128 v[220:223], v88 offset:12672
	s_waitcnt vmcnt(4) lgkmcnt(0)
	v_pk_fma_f32 v[206:207], v[2:3], v[206:207], v[72:73]
	v_pk_fma_f32 v[208:209], v[4:5], v[208:209], v[74:75]
	v_pk_fma_f32 v[210:211], v[2:3], v[210:211], v[76:77]
	v_pk_fma_f32 v[212:213], v[4:5], v[212:213], v[78:79]
	v_pk_fma_f32 v[216:217], v[2:3], v[216:217], v[80:81]
	v_pk_fma_f32 v[218:219], v[4:5], v[218:219], v[82:83]
	v_pk_fma_f32 v[220:221], v[2:3], v[220:221], v[96:97]
	v_pk_fma_f32 v[222:223], v[4:5], v[222:223], v[98:99]
	global_store_dwordx4 v89, v[206:209], s[46:47]
	global_store_dwordx4 v90, v[210:213], s[46:47]
	global_store_dwordx4 v91, v[216:219], s[46:47]
	global_store_dwordx4 v92, v[220:223], s[46:47]
	ds_read_b128 v[206:209], v88 offset:16896
	ds_read_b128 v[210:213], v88 offset:21120
	ds_read_b128 v[216:219], v88 offset:25344
	ds_read_b128 v[220:223], v88 offset:29568
	s_waitcnt vmcnt(4) lgkmcnt(0)
	v_pk_fma_f32 v[206:207], v[2:3], v[206:207], v[100:101]
	v_pk_fma_f32 v[208:209], v[4:5], v[208:209], v[102:103]
	v_pk_fma_f32 v[210:211], v[2:3], v[210:211], v[236:237]
	v_pk_fma_f32 v[212:213], v[4:5], v[212:213], v[238:239]
	v_pk_fma_f32 v[216:217], v[2:3], v[216:217], v[240:241]
	v_pk_fma_f32 v[218:219], v[4:5], v[218:219], v[242:243]
	v_pk_fma_f32 v[220:221], v[2:3], v[220:221], v[244:245]
	v_pk_fma_f32 v[222:223], v[4:5], v[222:223], v[246:247]
	global_store_dwordx4 v93, v[206:209], s[46:47]
	global_store_dwordx4 v94, v[210:213], s[46:47]
	global_store_dwordx4 v95, v[216:219], s[46:47]
	global_store_dwordx4 v104, v[220:223], s[46:47]
	s_barrier
	s_and_saveexec_b64 s[8:9], vcc
	s_cbranch_execz .LBB0_844
	v_lshl_add_u32 v0, v86, 2, v87
	ds_write2_b32 v0, v6, v14 offset1:16
	ds_write2_b32 v0, v7, v15 offset0:132 offset1:148
	v_add_u32_e32 v6, 0x400, v0
	ds_write2_b32 v6, v8, v16 offset0:8 offset1:24
	ds_write2_b32 v6, v9, v17 offset0:140 offset1:156
	ds_write2_b32 v0, v10, v18 offset0:32 offset1:48
	ds_write2_b32 v0, v11, v19 offset0:164 offset1:180
	ds_write2_b32 v6, v12, v20 offset0:40 offset1:56
	ds_write2_b32 v6, v13, v21 offset0:172 offset1:188
	v_add_u32_e32 v6, 0x2000, v0
	v_add_u32_e32 v7, 0x2400, v0
	ds_write2_b32 v6, v26, v38 offset0:64 offset1:80
	ds_write2_b32 v6, v27, v39 offset0:196 offset1:212
	ds_write2_b32 v7, v28, v40 offset0:72 offset1:88
	ds_write2_b32 v7, v29, v41 offset0:204 offset1:220
	ds_write2_b32 v6, v22, v30 offset0:96 offset1:112
	ds_write2_b32 v6, v23, v31 offset0:228 offset1:244
	ds_write2_b32 v7, v24, v32 offset0:104 offset1:120
	ds_write2_b32 v7, v25, v33 offset0:236 offset1:252
	v_add_u32_e32 v6, 0x4000, v0
	v_add_u32_e32 v7, 0x4400, v0
	v_add_u32_e32 v8, 0x4800, v0
	ds_write2_b32 v6, v34, v42 offset0:128 offset1:144
	ds_write2_b32 v7, v35, v43 offset0:4 offset1:20
	ds_write2_b32 v7, v36, v44 offset0:136 offset1:152
	ds_write2_b32 v8, v37, v45 offset0:12 offset1:28
	ds_write2_b32 v6, v46, v50 offset0:160 offset1:176
	ds_write2_b32 v7, v47, v51 offset0:36 offset1:52
	ds_write2_b32 v7, v48, v52 offset0:168 offset1:184
	ds_write2_b32 v8, v49, v53 offset0:44 offset1:60
	v_add_u32_e32 v6, 0x6000, v0
	v_add_u32_e32 v7, 0x6400, v0
	v_add_u32_e32 v0, 0x6800, v0
	ds_write2_b32 v6, v54, v58 offset0:192 offset1:208
	ds_write2_b32 v7, v55, v59 offset0:68 offset1:84
	ds_write2_b32 v7, v56, v60 offset0:200 offset1:216
	ds_write2_b32 v0, v57, v61 offset0:76 offset1:92
	ds_write2_b32 v6, v62, v66 offset0:224 offset1:240
	ds_write2_b32 v7, v63, v67 offset0:100 offset1:116
	ds_write2_b32 v7, v64, v68 offset0:232 offset1:248
	ds_write2_b32 v0, v65, v69 offset0:108 offset1:124
	s_branch .LBB0_844

; __device__ __forceinline__ u16 f2bf(float f) { return (u16)(pack2(f, 0.f) & 0xffffu); }
; __device__ __forceinline__ int tid_() { int t = threadIdx.x; asm volatile("" : "+v"(t)); return t; }
; __device__ __forceinline__ float silu_f(float x) { return x / (1.f + __expf(-x)); }
; template <int NT, bool BKN, bool MASK = false, bool ROWSS = false, class Epi> ...
;     ...
; #pragma unroll
;   for (int i = 0; i < 4; ++i) {
;     const int row = (t >> 3) + 32 * i;
;     const bool v = MASK ? (row < mvalid) : true;
;     amask |= v ? (1u << i) : 0u;
;     int r = v ? row : 0;
;     if (arows) r = arows[r];
;     ap[i] = A + (size_t)r * lda + (t & 7) * 8;
;   }
; __device__ __forceinline__ void phase_moe_up(const Params& p, int l, bool last, unsigned char* smem) {
;     ...
;     if (pass == npass - 1) { const int e_ = t >> 7, b_ = (t >> 6) & 1; inst = b_ * 16 + e_; mt = (t >> 3) & 7; nt = t & 7; mvalid = 128; hid_row = inst * 1024 + mt * 128; }
;     else { const int e_ = t >> 4, b_ = (t >> 3) & 1; inst = 32 + b_ * 16 + e_; mt = 0; nt = t & 7; mvalid = 32; hid_row = 32768 + (inst - 32) * 128; }
;     const int e = inst & 15;
;     const u16* W = p.WguT + (size_t)(l * 16 + e) * 1024 * 1024 + (size_t)nt * 128 * 1024;
;     auto epi = [&](f32x4(&acc)[4][4], int r0, int c0) {
;       u16* Ts = (u16*)smem;
;       const int t2 = tid_();
;       __syncthreads();
; #pragma unroll
;       for (int mi = 0; mi < 4; ++mi)
; #pragma unroll
;         for (int n2 = 0; n2 < 2; ++n2)
; #pragma unroll
;           for (int j = 0; j < 4; ++j) {
;             const int m = r0 + mi * 16 + j;
;             const int fl = (c0 >> 6) * 32 + n2 * 16 + (c0 & 15);
;             Ts[m * 72 + fl] = f2bf(silu_f(acc[mi][2 * n2][j]) * acc[mi][2 * n2 + 1][j]);
;           }
;       __syncthreads();
; #pragma unroll
;       for (int i = 0; i < 4; ++i) {
;         const int c = t2 + 256 * i, row = c >> 3, ch = c & 7;
;         if (row < mvalid) *(u32x4*)(p.HID + (size_t)(hid_row + row) * 512 + nt * 64 + ch * 8) = *(const u32x4*)(Ts + row * 72 + ch * 8);
;       }
;     };
;     if (mvalid == 128) gemm_tile<4, false, false>(p.H, 1024, p.IDXG + (size_t)inst * 1024 + mt * 128, 128, W, 1024, 1024, smem, epi);
;     else gemm_tile<4, false, true>(p.H, 1024, p.IDXG + (size_t)inst * 1024 + mt * 128, mvalid, W, 1024, 1024, smem, epi);
.LBB0_1107:
	v_mov_b64_e32 v[2:3], s[4:5]
	s_load_dwordx2 s[100:101], s[4:5], 0xe0
	s_waitcnt lgkmcnt(0)
	v_mov_b32_e32 v158, s100
	v_mov_b32_e32 v159, s101
	s_load_dwordx2 s[100:101], s[4:5], 0x118
	s_waitcnt lgkmcnt(0)
	v_mov_b32_e32 v160, s100
	v_mov_b32_e32 v161, s101
	s_nop 0
	s_load_dwordx2 s[100:101], s[4:5], 0x198
	s_waitcnt lgkmcnt(0)
	v_mov_b32_e32 v2, s100
	v_mov_b32_e32 v3, s101
	s_lshl_b32 s9, s38, 20
	s_and_b32 s9, s9, 0xf00000
	s_and_b32 s83, s64, 7
	s_or_b32 s94, s9, s18
	s_ashr_i32 s39, s38, 31
	s_lshl_b64 s[38:39], s[38:39], 12
	s_and_b32 s8, s65, 7
	s_lshl_b32 s8, s8, 18
	s_and_b64 vcc, exec, s[34:35]
	s_waitcnt lgkmcnt(0)
	v_lshl_add_u64 v[4:5], s[94:95], 1, v[158:159]
	s_lshl_b32 s94, s83, 18
	v_lshl_add_u64 v[162:163], v[4:5], 0, s[94:95]
	v_lshl_add_u64 v[4:5], v[2:3], 0, s[38:39]
	s_lshl_b32 s94, s40, 2
	v_lshl_add_u64 v[164:165], v[4:5], 0, s[94:95]
	v_cmp_ne_u64_e64 s[38:39], 0, v[2:3]
	s_mov_b64 s[40:41], -1
	s_cbranch_vccz .LBB0_1150
	v_mov_b32_e32 v18, v187
	s_nop 0
	v_ashrrev_i32_e32 v10, 3, v18
	v_cmp_gt_i32_e64 s[40:41], s86, v10
	s_nop 1
	v_cndmask_b32_e64 v2, 0, v10, s[40:41]
	s_and_saveexec_b64 s[0:1], s[38:39]
	s_cbranch_execz .LBB0_1110
	v_ashrrev_i32_e32 v3, 31, v2
	v_lshl_add_u64 v[2:3], v[2:3], 2, v[164:165]
	global_load_dword v2, v[2:3], off

; template <int NT, bool BKN, bool MASK = false, bool ROWSS = false, class Epi> ...
;     ...
; #pragma unroll
;   for (int i = 0; i < 4; ++i) {
;     const int row = (t >> 3) + 32 * i;
;     const bool v = MASK ? (row < mvalid) : true;
;     amask |= v ? (1u << i) : 0u;
;     int r = v ? row : 0;
;     if (arows) r = arows[r];
;     ap[i] = A + (size_t)r * lda + (t & 7) * 8;
;   }
; #pragma unroll
;   for (int i = 0; i < NT; ++i) {
;     if (!BKN) bp[i] = B + (size_t)((t >> 3) + 32 * i) * ldb + (t & 7) * 8;
;     else { const int c = t + 256 * i; bp[i] = B + (size_t)(c / CPR) * ldb + (c % CPR) * 8; }
;   }
;   const size_t bstep = BKN ? (size_t)64 * ldb : (size_t)64;
;   int nmi = 4;
;   if (MASK) { nmi = (mvalid - wr * 64 + 15) >> 4; nmi = nmi < 0 ? 0 : (nmi > 4 ? 4 : nmi); nmi = __builtin_amdgcn_readfirstlane(nmi); }
;   u32x4 ra0[4], rb0[NT], ra1[4], rb1[NT];
; __device__ __forceinline__ void phase_moe_down(const Params& p, int l, bool last, unsigned char* smem) {
;     ...
;     if (pass == npass - 1) { const int e_ = t >> 7, b_ = (t >> 6) & 1; inst = b_ * 16 + e_; mt = (t >> 3) & 7; nt = t & 7; mvalid = 128; hid_row = inst * 1024 + mt * 128; }
;     else { const int e_ = t >> 4, b_ = (t >> 3) & 1; inst = 32 + b_ * 16 + e_; mt = 0; nt = t & 7; mvalid = 32; hid_row = 32768 + (inst - 32) * 128; }
;     const int e = inst & 15;
;     const float* gate = p.GATE + (size_t)inst * 1024 + mt * 128;
;     const u16* W = p.WdT + (size_t)(l * 16 + e) * 1024 * 512 + (size_t)nt * 128 * 512;
;     u16* yb = p.YB + (size_t)hid_row * 1024 + nt * 128;
;     auto epi = [&](f32x4(&acc)[4][4], int r0, int c0) {
;       auto vf = [&](int r, int, float v) { return (r < mvalid ? gate[r] : 0.f) * v; };
;       auto rp = [&](int r) -> u16* { return r < mvalid ? yb + (size_t)r * 1024 : nullptr; };
;       epi_staged_bf16<4>(acc, r0, c0, smem, vf, rp);
;     };
;     if (mvalid == 128) gemm_tile<4, false, false>(p.HID + (size_t)hid_row * 512, 512, nullptr, 128, W, 512, 512, smem, epi);
;     else gemm_tile<4, false, true>(p.HID + (size_t)hid_row * 512, 512, nullptr, mvalid, W, 512, 512, smem, epi);
.LBB0_1272:
	v_mov_b64_e32 v[2:3], s[4:5]
	s_load_dwordx2 s[100:101], s[4:5], 0x180
	s_waitcnt lgkmcnt(0)
	v_mov_b32_e32 v4, s100
	v_mov_b32_e32 v5, s101
	s_ashr_i32 s39, s38, 31
	s_lshl_b64 s[40:41], s[38:39], 12
	s_lshl_b32 s94, s8, 2
	s_lshl_b32 s8, s38, 19
	s_and_b32 s8, s8, 0x780000
	s_or_b32 s8, s8, s18
	s_and_b32 s42, s57, 7
	s_ashr_i32 s37, s36, 31
	s_and_b64 vcc, exec, s[34:35]
	s_load_dwordx2 s[100:101], s[4:5], 0x1a8
	s_waitcnt lgkmcnt(0)
	v_mov_b32_e32 v164, s100
	v_mov_b32_e32 v165, s101
	s_waitcnt lgkmcnt(0)
	v_lshl_add_u64 v[4:5], v[4:5], 0, s[40:41]
	v_lshl_add_u64 v[162:163], v[4:5], 0, s[94:95]
	global_load_dwordx2 v[4:5], v[2:3], off offset:232
	s_lshl_b32 s94, s8, 1
	global_load_dwordx2 v[2:3], v[2:3], off offset:368
	s_lshl_b64 s[8:9], s[36:37], 11
	s_waitcnt vmcnt(0) lgkmcnt(0)
	v_lshl_add_u64 v[4:5], v[4:5], 0, s[94:95]
	s_lshl_b32 s94, s42, 17
	v_lshl_add_u64 v[166:167], v[4:5], 0, s[94:95]
	v_lshl_add_u64 v[4:5], v[164:165], 0, s[8:9]
	s_lshl_b32 s94, s42, 8
	s_lshl_b64 s[8:9], s[36:37], 10
	v_lshl_add_u64 v[160:161], v[4:5], 0, s[94:95]
	v_lshl_add_u64 v[168:169], v[2:3], 0, s[8:9]
	s_mov_b64 s[36:37], -1
	s_cbranch_vccz .LBB0_1278
	v_mov_b32_e32 v140, v187
	s_nop 0
	v_ashrrev_i32_e32 v4, 3, v140
	v_cmp_gt_i32_e64 s[40:41], s60, v4
	v_lshlrev_b32_e32 v3, 4, v140
	v_and_b32_e32 v0, 0x70, v3
	v_cndmask_b32_e64 v8, 0, v4, s[40:41]
	v_ashrrev_i32_e32 v9, 31, v8
	v_lshl_add_u64 v[6:7], v[168:169], 0, v[0:1]
	v_lshlrev_b64 v[8:9], 10, v[8:9]
	v_lshl_add_u64 v[170:171], v[6:7], 0, v[8:9]
	v_add_u32_e32 v8, 32, v4
	v_cmp_gt_i32_e64 s[42:43], s60, v8
	v_ashrrev_i32_e32 v5, 31, v4
	v_ashrrev_i32_e32 v9, 31, v8
	v_cndmask_b32_e64 v10, 0, v8, s[42:43]
	v_ashrrev_i32_e32 v11, 31, v10
	v_lshlrev_b64 v[10:11], 10, v[10:11]
	v_lshl_add_u64 v[172:173], v[6:7], 0, v[10:11]
	v_add_u32_e32 v10, 64, v4
	v_cmp_gt_i32_e64 s[44:45], s60, v10
	v_ashrrev_i32_e32 v11, 31, v10
	s_barrier
	v_cndmask_b32_e64 v12, 0, v10, s[44:45]
	v_ashrrev_i32_e32 v13, 31, v12
	v_lshlrev_b64 v[12:13], 10, v[12:13]
	v_lshl_add_u64 v[174:175], v[6:7], 0, v[12:13]
	v_add_u32_e32 v12, 0x60, v4
	v_cmp_gt_i32_e64 s[38:39], s60, v12
	v_lshlrev_b64 v[4:5], 10, v[4:5]
	v_ashrrev_i32_e32 v13, 31, v12
	v_cndmask_b32_e64 v14, 0, v12, s[38:39]
	v_ashrrev_i32_e32 v15, 31, v14
	v_lshlrev_b64 v[14:15], 10, v[14:15]
	v_lshl_add_u64 v[176:177], v[6:7], 0, v[14:15]
	v_lshl_add_u64 v[6:7], v[166:167], 0, v[0:1]
	v_lshl_add_u64 v[178:179], v[6:7], 0, v[4:5]
	v_lshlrev_b64 v[4:5], 10, v[8:9]
	v_lshl_add_u64 v[180:181], v[6:7], 0, v[4:5]
	v_lshlrev_b64 v[4:5], 10, v[10:11]
	v_lshl_add_u64 v[182:183], v[6:7], 0, v[4:5]
	v_lshlrev_b64 v[4:5], 10, v[12:13]
	v_lshl_add_u64 v[184:185], v[6:7], 0, v[4:5]
	global_load_dwordx4 v[4:7], v[170:171], off
	global_load_dwordx4 v[8:11], v[172:173], off
	global_load_dwordx4 v[12:15], v[174:175], off
	global_load_dwordx4 v[16:19], v[176:177], off
	global_load_dwordx4 v[20:23], v[178:179], off
	global_load_dwordx4 v[24:27], v[180:181], off
	global_load_dwordx4 v[28:31], v[182:183], off
	global_load_dwordx4 v[32:35], v[184:185], off
	global_load_dwordx4 v[128:131], v[170:171], off offset:128
	global_load_dwordx4 v[120:123], v[172:173], off offset:128
	global_load_dwordx4 v[124:127], v[174:175], off offset:128
	global_load_dwordx4 v[108:111], v[176:177], off offset:128
	global_load_dwordx4 v[100:103], v[178:179], off offset:128
	global_load_dwordx4 v[104:107], v[180:181], off offset:128
	global_load_dwordx4 v[112:115], v[182:183], off offset:128
	global_load_dwordx4 v[116:119], v[184:185], off offset:128
	v_ashrrev_i32_e32 v0, 1, v140
	v_and_b32_e32 v190, 0xffffffc0, v0
	v_sub_u32_e32 v0, s60, v190
	v_ashrrev_i32_e32 v0, 4, v0
	v_lshrrev_b32_e32 v2, 4, v140
	v_med3_i32 v0, v0, 0, 4
	v_and_b32_e32 v3, 0xffffff80, v3
	v_readfirstlane_b32 s8, v0
	v_xor_b32_e32 v0, v2, v140
	v_lshlrev_b32_e32 v0, 4, v0
	v_and_or_b32 v191, v0, s14, v3
	v_and_b32_e32 v189, 15, v140
	v_bfe_u32 v141, v140, 1, 3
	v_bfe_u32 v188, v140, 6, 1
	v_bitop3_b32 v0, v2, v141, 3 bitop3:0x6c
	v_lshlrev_b32_e32 v2, 6, v189
	v_or_b32_e32 v142, v190, v189
	v_lshlrev_b32_e32 v0, 4, v0
	v_lshl_or_b32 v143, v188, 12, v2
	v_lshl_or_b32 v192, v142, 7, v0
	v_lshl_or_b32 v193, v143, 1, v0
	s_cmp_gt_i32 s8, 0
	s_cselect_b64 s[36:37], -1, 0
	s_cmp_lt_i32 s8, 1
	s_waitcnt vmcnt(0) lgkmcnt(0)
	v_cndmask_b32_e64 v7, 0, v7, s[40:41]
	v_cndmask_b32_e64 v6, 0, v6, s[40:41]
	v_cndmask_b32_e64 v5, 0, v5, s[40:41]
	v_cndmask_b32_e64 v4, 0, v4, s[40:41]
	v_cndmask_b32_e64 v11, 0, v11, s[42:43]
	v_cndmask_b32_e64 v10, 0, v10, s[42:43]
	v_cndmask_b32_e64 v9, 0, v9, s[42:43]
	v_cndmask_b32_e64 v8, 0, v8, s[42:43]
	v_cndmask_b32_e64 v15, 0, v15, s[44:45]
	v_cndmask_b32_e64 v14, 0, v14, s[44:45]
	v_cndmask_b32_e64 v13, 0, v13, s[44:45]
	v_cndmask_b32_e64 v12, 0, v12, s[44:45]
	v_cndmask_b32_e64 v19, 0, v19, s[38:39]
	v_cndmask_b32_e64 v18, 0, v18, s[38:39]
	v_cndmask_b32_e64 v17, 0, v17, s[38:39]
	v_cndmask_b32_e64 v16, 0, v16, s[38:39]
	ds_write_b128 v191, v[4:7]
	ds_write_b128 v191, v[8:11] offset:4096
	ds_write_b128 v191, v[12:15] offset:8192
	ds_write_b128 v191, v[16:19] offset:12288
	ds_write_b128 v191, v[20:23] offset:16384
	ds_write_b128 v191, v[24:27] offset:20480
	ds_write_b128 v191, v[28:31] offset:24576
	ds_write_b128 v191, v[32:35] offset:28672
	global_load_dwordx4 v[88:91], v[170:171], off offset:256
	global_load_dwordx4 v[92:95], v[172:173], off offset:256
	global_load_dwordx4 v[76:79], v[174:175], off offset:256
	global_load_dwordx4 v[68:71], v[176:177], off offset:256
	global_load_dwordx4 v[72:75], v[178:179], off offset:256
	global_load_dwordx4 v[80:83], v[180:181], off offset:256
	global_load_dwordx4 v[84:87], v[182:183], off offset:256
	global_load_dwordx4 v[96:99], v[184:185], off offset:256
	s_waitcnt lgkmcnt(0)
	s_barrier
	ds_read_b128 v[20:23], v192 offset:2048
	ds_read_b128 v[16:19], v192 offset:4096
	ds_read_b128 v[4:7], v192 offset:6144
	ds_read_b128 v[8:11], v193 offset:16384
	ds_read_b128 v[12:15], v193 offset:18432
	ds_read_b128 v[132:135], v193 offset:20480
	ds_read_b128 v[136:139], v193 offset:22528
	s_cbranch_scc1 .LBB0_1422
	ds_read_b128 v[24:27], v192
	s_waitcnt lgkmcnt(0)
	v_mfma_f32_16x16x32_bf16 v[64:67], v[24:27], v[8:11], 0
	v_mfma_f32_16x16x32_bf16 v[60:63], v[24:27], v[12:15], 0
	v_mfma_f32_16x16x32_bf16 v[56:59], v[24:27], v[132:135], 0
	v_mfma_f32_16x16x32_bf16 v[52:55], v[24:27], v[136:139], 0
	s_cmp_gt_i32 s8, 1
	s_cselect_b64 s[0:1], -1, 0
	s_cmp_lt_i32 s8, 2
	s_cbranch_scc1 .LBB0_1423
